# PEER V phase in the two latent-only layers: 32-token groups (two groups per wave exactly, half the group start-ups)
# speedup vs baseline: 1.0084x; 1.0018x over previous
.LBB0_3098:
	s_or_b64 exec, exec, s[0:1]
	s_mov_b64 s[0:1], 0
	s_mov_b64 s[8:9], 0
	s_waitcnt lgkmcnt(0)
	s_barrier
	v_readlane_b32 s12, v250, 0
	s_mov_b64 s[8:9], 0
	v_readlane_b32 s13, v250, 1
	v_readlane_b32 s14, v250, 2
	s_mov_b64 s[18:19], 0
	s_mov_b64 s[12:13], 0
	s_mov_b64 s[8:9], 0
	v_readlane_b32 s15, v250, 3
	s_add_u32 s0, s14, s0
	s_mov_b64 s[10:11], 0
	s_addc_u32 s1, s15, s1
	s_mov_b64 s[16:17], 0
	s_mov_b64 s[8:9], 0
	s_mov_b64 s[14:15], 0
	v_mov_b32_e32 v2, v0
	s_add_u32 s0, s0, 0x6800
	s_getreg_b32 s2, hwreg(HW_REG_XCC_ID, 0, 4)
	v_and_b32_e32 v3, 63, v2
	s_addc_u32 s1, s1, 0
	s_and_b32 s26, s2, 7
	v_mov_b32_e32 v202, 0
	v_cmp_eq_u32_e64 s[8:9], 0, v3
	s_and_saveexec_b64 s[20:21], s[8:9]
	s_cbranch_execz .LBB0_3102
	s_mov_b64 s[24:25], exec
	v_mbcnt_lo_u32_b32 v4, s24, 0
	v_mbcnt_hi_u32_b32 v4, s25, v4
	v_cmp_eq_u32_e32 vcc, 0, v4
	s_and_saveexec_b64 s[22:23], vcc
	s_cbranch_execz .LBB0_3101
	s_bcnt1_i32_b64 s24, s[24:25]
	s_lshl_b32 s27, s26, 8
	s_lshl_b32 s24, s24, 5
	v_mov_b32_e32 v5, s27
	v_mov_b32_e32 v6, s24
	global_atomic_add v5, v5, v6, s[0:1] sc0
.LBB0_3101:
	s_or_b64 exec, exec, s[22:23]
	s_waitcnt vmcnt(0)
	v_readfirstlane_b32 s22, v5
	s_nop 1
	v_lshl_add_u32 v202, v4, 5, s22
.LBB0_3102:
	s_or_b64 exec, exec, s[20:21]
	v_readlane_b32 s20, v250, 0
	v_readlane_b32 s22, v250, 2
	v_readlane_b32 s23, v250, 3
	s_add_u32 s18, s22, s18
	s_addc_u32 s19, s23, s19
	v_readlane_b32 s21, v250, 1
	s_add_u32 s20, s22, s12
	s_addc_u32 s21, s23, s13
	s_add_u32 s12, s22, s16
	s_addc_u32 s13, s23, s17
	s_add_u32 s12, s12, 0x3ed06000
	s_addc_u32 s13, s13, 0
	s_add_u32 s14, s22, s14
	s_addc_u32 s15, s23, s15
	s_add_u32 s14, s14, 0x4c618000
	s_addc_u32 s15, s15, 0
	s_add_u32 s10, s22, s10
	s_addc_u32 s11, s23, s11
	v_lshlrev_b32_e32 v203, 2, v3
	v_lshlrev_b32_e32 v4, 4, v3
	v_lshlrev_b32_e32 v3, 3, v3
	s_add_u32 s16, s10, 0x50e18000
	v_and_b32_e32 v182, 0x1c0, v3
	v_mov_b32_e32 v183, 0
	v_and_b32_e32 v3, 56, v2
	s_addc_u32 s17, s11, 0
	v_and_b32_e32 v204, 0x70, v4
	v_lshl_add_u64 v[4:5], s[18:19], 0, v[182:183]
	s_mov_b64 s[10:11], 0x2ade6000
	v_lshlrev_b32_e32 v182, 2, v3
	v_lshl_add_u64 v[184:185], v[4:5], 0, s[10:11]
	v_lshl_add_u64 v[4:5], s[20:21], 0, v[182:183]
	s_mov_b64 s[10:11], 0x4c198000
	v_and_b32_e32 v2, 8, v2
	v_lshl_add_u64 v[186:187], v[4:5], 0, s[10:11]
	s_mov_b32 s29, 0
	v_cmp_eq_u32_e64 s[10:11], 0, v2
	v_mov_b32_e32 v206, s26
	v_mov_b32_e32 v205, 32
	s_mov_b32 s28, 0xa000
	s_branch .LBB0_3105

.LBB0_3109:
	s_add_i32 s24, s18, s30
	s_add_i32 s19, s24, 2
	s_add_i32 s26, s24, 1
	s_add_i32 s21, s24, 3
	s_cmp_lt_u32 s30, 30
	s_cselect_b32 s20, s19, s24
	s_cselect_b32 s22, s21, s26
	s_ashr_i32 s21, s20, 31
	s_ashr_i32 s27, s26, 31
	s_ashr_i32 s25, s24, 31
	s_lshl_b64 s[34:35], s[20:21], 9
	s_lshl_b64 s[36:37], s[26:27], 8
	s_lshl_b64 s[20:21], s[24:25], 12
	s_add_i32 s19, s30, 1
	s_cmp_lt_u32 s19, 31
	s_cselect_b64 s[38:39], -1, 0
	s_ashr_i32 s23, s22, 31
	s_lshl_b64 s[22:23], s[22:23], 9
	s_cmp_lg_u64 s[38:39], 0
	s_addc_u32 s24, s24, 1
	s_lshl_b64 s[26:27], s[26:27], 12
	v_lshl_add_u64 v[18:19], v[184:185], 0, s[34:35]
	v_lshl_add_u64 v[30:31], v[186:187], 0, s[36:37]
	global_load_dwordx4 v[166:169], v[18:19], off offset:48
	global_load_dwordx4 v[170:173], v[18:19], off offset:32
	global_load_dwordx4 v[174:177], v[18:19], off offset:16
	global_load_dwordx4 v[178:181], v[18:19], off
	s_nop 0
	global_load_dwordx4 v[18:21], v[30:31], off offset:16
	global_load_dwordx4 v[90:93], v[30:31], off
	v_lshl_add_u64 v[196:197], v[190:191], 0, s[26:27]
	v_lshl_add_u64 v[30:31], v[192:193], 0, s[26:27]
	global_load_dwordx2 v[198:199], v[196:197], off
	global_load_dwordx2 v[200:201], v[30:31], off
	s_waitcnt vmcnt(29)
	v_lshl_add_u32 v30, v138, 7, v207
	v_lshl_add_u32 v31, v139, 7, v207
	global_load_dwordx4 v[162:165], v30, s[12:13]
	global_load_dwordx4 v[158:161], v31, s[12:13]
	v_lshl_add_u32 v30, v140, 7, v207
	v_lshl_add_u32 v31, v141, 7, v207
	global_load_dwordx4 v[154:157], v30, s[12:13]
	global_load_dwordx4 v[150:153], v31, s[12:13]
	v_lshl_add_u32 v30, v130, 7, v207
	v_lshl_add_u32 v31, v131, 7, v207
	global_load_dwordx4 v[142:145], v30, s[12:13]
	global_load_dwordx4 v[126:129], v31, s[12:13]
	v_lshl_add_u32 v30, v132, 7, v207
	v_lshl_add_u32 v31, v133, 7, v207
	global_load_dwordx4 v[110:113], v30, s[12:13]
	global_load_dwordx4 v[102:105], v31, s[12:13]
	v_lshl_add_u32 v30, v122, 7, v207
	v_lshl_add_u32 v31, v123, 7, v207
	global_load_dwordx4 v[94:97], v30, s[12:13]
	global_load_dwordx4 v[86:89], v31, s[12:13]
	v_lshl_add_u32 v30, v124, 7, v207
	v_lshl_add_u32 v31, v125, 7, v207
	global_load_dwordx4 v[78:81], v30, s[12:13]
	global_load_dwordx4 v[70:73], v31, s[12:13]
	s_waitcnt vmcnt(40)
	v_lshl_add_u32 v30, v118, 7, v207
	v_lshl_add_u32 v31, v119, 7, v207
	global_load_dwordx4 v[58:61], v30, s[12:13]
	global_load_dwordx4 v[50:53], v31, s[12:13]
	v_lshl_add_u32 v30, v120, 7, v207
	v_lshl_add_u32 v31, v121, 7, v207
	global_load_dwordx4 v[38:41], v30, s[12:13]
	s_nop 0
	global_load_dwordx4 v[30:33], v31, s[12:13]
	s_ashr_i32 s25, s24, 31
	s_lshl_b64 s[26:27], s[24:25], 8
	s_lshl_b64 s[24:25], s[24:25], 12
	s_add_i32 s19, s30, 2
	s_cmp_gt_u32 s30, 29
	s_waitcnt vmcnt(36)
	v_cvt_scalef32_pk_f16_fp4 v118, v146, 1.0
	v_pk_fma_f16 v118, v42, v118, 0 op_sel_hi:[0,1,1]
	v_cvt_scalef32_pk_f16_fp4 v119, v146, 1.0 op_sel:[1,0,0]
	v_cvt_scalef32_pk_f16_fp4 v120, v146, 1.0 op_sel:[0,1,0]
	v_cvt_scalef32_pk_f16_fp4 v121, v146, 1.0 op_sel:[1,1,0]
	s_waitcnt vmcnt(35)
	v_cvt_scalef32_pk_f16_fp4 v146, v134, 1.0
	v_pk_fma_f16 v119, v42, v119, 0 op_sel_hi:[0,1,1]
	v_pk_fma_f16 v118, v42, v146, v118 op_sel:[1,0,0]
	v_cvt_scalef32_pk_f16_fp4 v146, v134, 1.0 op_sel:[1,0,0]
	v_pk_fma_f16 v121, v42, v121, 0 op_sel_hi:[0,1,1]
	v_cvt_scalef32_pk_f16_fp4 v122, v147, 1.0
	v_pk_fma_f16 v119, v42, v146, v119 op_sel:[1,0,0]
	v_cvt_scalef32_pk_f16_fp4 v146, v134, 1.0 op_sel:[0,1,0]
	v_cvt_scalef32_pk_f16_fp4 v134, v134, 1.0 op_sel:[1,1,0]
	v_pk_fma_f16 v122, v42, v122, 0 op_sel_hi:[0,1,1]
	v_cvt_scalef32_pk_f16_fp4 v123, v147, 1.0 op_sel:[1,0,0]
	v_pk_fma_f16 v121, v42, v134, v121 op_sel:[1,0,0]
	v_cvt_scalef32_pk_f16_fp4 v134, v135, 1.0
	v_pk_fma_f16 v123, v42, v123, 0 op_sel_hi:[0,1,1]
	v_cvt_scalef32_pk_f16_fp4 v124, v147, 1.0 op_sel:[0,1,0]
	v_pk_fma_f16 v122, v42, v134, v122 op_sel:[1,0,0]
	v_cvt_scalef32_pk_f16_fp4 v134, v135, 1.0 op_sel:[1,0,0]
	v_pk_fma_f16 v124, v42, v124, 0 op_sel_hi:[0,1,1]
	v_cvt_scalef32_pk_f16_fp4 v125, v147, 1.0 op_sel:[1,1,0]
	v_pk_fma_f16 v123, v42, v134, v123 op_sel:[1,0,0]
	v_cvt_scalef32_pk_f16_fp4 v134, v135, 1.0 op_sel:[0,1,0]
	v_pk_fma_f16 v125, v42, v125, 0 op_sel_hi:[0,1,1]
	v_cvt_scalef32_pk_f16_fp4 v130, v148, 1.0
	v_pk_fma_f16 v124, v42, v134, v124 op_sel:[1,0,0]
	v_cvt_scalef32_pk_f16_fp4 v134, v135, 1.0 op_sel:[1,1,0]
	v_pk_fma_f16 v130, v42, v130, 0 op_sel_hi:[0,1,1]
	v_cvt_scalef32_pk_f16_fp4 v131, v148, 1.0 op_sel:[1,0,0]
	v_pk_fma_f16 v125, v42, v134, v125 op_sel:[1,0,0]
	v_cvt_scalef32_pk_f16_fp4 v134, v136, 1.0
	v_pk_fma_f16 v131, v42, v131, 0 op_sel_hi:[0,1,1]
	v_cvt_scalef32_pk_f16_fp4 v132, v148, 1.0 op_sel:[0,1,0]
	v_pk_fma_f16 v130, v42, v134, v130 op_sel:[1,0,0]
	v_cvt_scalef32_pk_f16_fp4 v134, v136, 1.0 op_sel:[1,0,0]
	v_pk_fma_f16 v132, v42, v132, 0 op_sel_hi:[0,1,1]
	v_cvt_scalef32_pk_f16_fp4 v133, v148, 1.0 op_sel:[1,1,0]
	v_pk_fma_f16 v131, v42, v134, v131 op_sel:[1,0,0]
	v_cvt_scalef32_pk_f16_fp4 v134, v136, 1.0 op_sel:[0,1,0]
	v_pk_fma_f16 v133, v42, v133, 0 op_sel_hi:[0,1,1]
	v_cvt_scalef32_pk_f16_fp4 v138, v149, 1.0
	v_cvt_scalef32_pk_f16_fp4 v139, v149, 1.0 op_sel:[1,0,0]
	v_cvt_scalef32_pk_f16_fp4 v140, v149, 1.0 op_sel:[0,1,0]
	v_cvt_scalef32_pk_f16_fp4 v141, v149, 1.0 op_sel:[1,1,0]
	v_pk_fma_f16 v132, v42, v134, v132 op_sel:[1,0,0]
	v_cvt_scalef32_pk_f16_fp4 v134, v136, 1.0 op_sel:[1,1,0]
	v_pk_fma_f16 v120, v42, v120, 0 op_sel_hi:[0,1,1]
	v_pk_fma_f16 v138, v42, v138, 0 op_sel_hi:[0,1,1]
	v_pk_fma_f16 v139, v42, v139, 0 op_sel_hi:[0,1,1]
	v_pk_fma_f16 v140, v42, v140, 0 op_sel_hi:[0,1,1]
	v_pk_fma_f16 v141, v42, v141, 0 op_sel_hi:[0,1,1]
	v_pk_fma_f16 v133, v42, v134, v133 op_sel:[1,0,0]
	v_cvt_scalef32_pk_f16_fp4 v134, v137, 1.0
	v_cvt_scalef32_pk_f16_fp4 v135, v137, 1.0 op_sel:[1,0,0]
	v_cvt_scalef32_pk_f16_fp4 v136, v137, 1.0 op_sel:[0,1,0]
	v_cvt_scalef32_pk_f16_fp4 v137, v137, 1.0 op_sel:[1,1,0]
	v_pk_fma_f16 v120, v42, v146, v120 op_sel:[1,0,0]
	v_pk_fma_f16 v134, v42, v134, v138 op_sel:[1,0,0]
	v_pk_fma_f16 v135, v42, v135, v139 op_sel:[1,0,0]
	v_pk_fma_f16 v136, v42, v136, v140 op_sel:[1,0,0]
	v_pk_fma_f16 v42, v42, v137, v141 op_sel:[1,0,0]
	s_waitcnt vmcnt(34)
	v_cvt_scalef32_pk_f16_fp4 v137, v114, 1.0
	v_pk_fma_f16 v118, v43, v137, v118 op_sel_hi:[0,1,1]
	v_cvt_scalef32_pk_f16_fp4 v137, v114, 1.0 op_sel:[1,0,0]
	v_pk_fma_f16 v119, v43, v137, v119 op_sel_hi:[0,1,1]
	v_cvt_scalef32_pk_f16_fp4 v137, v114, 1.0 op_sel:[0,1,0]
	v_cvt_scalef32_pk_f16_fp4 v114, v114, 1.0 op_sel:[1,1,0]
	v_pk_fma_f16 v114, v43, v114, v121 op_sel_hi:[0,1,1]
	v_cvt_scalef32_pk_f16_fp4 v121, v115, 1.0
	v_pk_fma_f16 v121, v43, v121, v122 op_sel_hi:[0,1,1]
	v_cvt_scalef32_pk_f16_fp4 v122, v115, 1.0 op_sel:[1,0,0]
	v_pk_fma_f16 v122, v43, v122, v123 op_sel_hi:[0,1,1]
	v_cvt_scalef32_pk_f16_fp4 v123, v115, 1.0 op_sel:[0,1,0]
	v_pk_fma_f16 v123, v43, v123, v124 op_sel_hi:[0,1,1]
	v_cvt_scalef32_pk_f16_fp4 v115, v115, 1.0 op_sel:[1,1,0]
	v_cvt_scalef32_pk_f16_fp4 v124, v116, 1.0
	v_pk_fma_f16 v115, v43, v115, v125 op_sel_hi:[0,1,1]
	v_pk_fma_f16 v124, v43, v124, v130 op_sel_hi:[0,1,1]
	v_cvt_scalef32_pk_f16_fp4 v125, v116, 1.0 op_sel:[1,0,0]
	v_cvt_scalef32_pk_f16_fp4 v130, v116, 1.0 op_sel:[0,1,0]
	v_cvt_scalef32_pk_f16_fp4 v116, v116, 1.0 op_sel:[1,1,0]
	v_pk_fma_f16 v125, v43, v125, v131 op_sel_hi:[0,1,1]
	v_pk_fma_f16 v130, v43, v130, v132 op_sel_hi:[0,1,1]
	v_pk_fma_f16 v116, v43, v116, v133 op_sel_hi:[0,1,1]
	v_cvt_scalef32_pk_f16_fp4 v131, v117, 1.0
	v_cvt_scalef32_pk_f16_fp4 v132, v117, 1.0 op_sel:[1,0,0]
	v_cvt_scalef32_pk_f16_fp4 v133, v117, 1.0 op_sel:[0,1,0]
	v_cvt_scalef32_pk_f16_fp4 v117, v117, 1.0 op_sel:[1,1,0]
	v_pk_fma_f16 v42, v43, v117, v42 op_sel_hi:[0,1,1]
	s_waitcnt vmcnt(33)
	v_cvt_scalef32_pk_f16_fp4 v117, v106, 1.0
	v_pk_fma_f16 v117, v43, v117, v118 op_sel:[1,0,0]
	v_cvt_scalef32_pk_f16_fp4 v118, v106, 1.0 op_sel:[1,0,0]
	v_pk_fma_f16 v118, v43, v118, v119 op_sel:[1,0,0]
	v_cvt_scalef32_pk_f16_fp4 v119, v106, 1.0 op_sel:[0,1,0]
	v_cvt_scalef32_pk_f16_fp4 v106, v106, 1.0 op_sel:[1,1,0]
	v_pk_fma_f16 v120, v43, v137, v120 op_sel_hi:[0,1,1]
	v_pk_fma_f16 v106, v43, v106, v114 op_sel:[1,0,0]
	v_cvt_scalef32_pk_f16_fp4 v114, v107, 1.0
	v_pk_fma_f16 v119, v43, v119, v120 op_sel:[1,0,0]
	v_pk_fma_f16 v114, v43, v114, v121 op_sel:[1,0,0]
	v_cvt_scalef32_pk_f16_fp4 v120, v107, 1.0 op_sel:[1,0,0]
	v_cvt_scalef32_pk_f16_fp4 v121, v107, 1.0 op_sel:[0,1,0]
	v_cvt_scalef32_pk_f16_fp4 v107, v107, 1.0 op_sel:[1,1,0]
	v_pk_fma_f16 v120, v43, v120, v122 op_sel:[1,0,0]
	v_pk_fma_f16 v121, v43, v121, v123 op_sel:[1,0,0]
	v_pk_fma_f16 v107, v43, v107, v115 op_sel:[1,0,0]
	v_cvt_scalef32_pk_f16_fp4 v115, v108, 1.0
	v_cvt_scalef32_pk_f16_fp4 v122, v108, 1.0 op_sel:[1,0,0]
	v_cvt_scalef32_pk_f16_fp4 v123, v108, 1.0 op_sel:[0,1,0]
	v_cvt_scalef32_pk_f16_fp4 v108, v108, 1.0 op_sel:[1,1,0]
	v_pk_fma_f16 v131, v43, v131, v134 op_sel_hi:[0,1,1]
	v_pk_fma_f16 v132, v43, v132, v135 op_sel_hi:[0,1,1]
	v_pk_fma_f16 v133, v43, v133, v136 op_sel_hi:[0,1,1]
	v_pk_fma_f16 v115, v43, v115, v124 op_sel:[1,0,0]
	v_pk_fma_f16 v122, v43, v122, v125 op_sel:[1,0,0]
	v_pk_fma_f16 v108, v43, v108, v116 op_sel:[1,0,0]
	v_cvt_scalef32_pk_f16_fp4 v116, v109, 1.0
	v_cvt_scalef32_pk_f16_fp4 v124, v109, 1.0 op_sel:[1,0,0]
	v_cvt_scalef32_pk_f16_fp4 v125, v109, 1.0 op_sel:[0,1,0]
	v_cvt_scalef32_pk_f16_fp4 v109, v109, 1.0 op_sel:[1,1,0]
	v_pk_fma_f16 v123, v43, v123, v130 op_sel:[1,0,0]
	v_pk_fma_f16 v116, v43, v116, v131 op_sel:[1,0,0]
	v_pk_fma_f16 v124, v43, v124, v132 op_sel:[1,0,0]
	v_pk_fma_f16 v125, v43, v125, v133 op_sel:[1,0,0]
	v_pk_fma_f16 v42, v43, v109, v42 op_sel:[1,0,0]
	s_waitcnt vmcnt(32)
	v_cvt_scalef32_pk_f16_fp4 v43, v98, 1.0
	v_pk_fma_f16 v43, v44, v43, v117 op_sel_hi:[0,1,1]
	v_cvt_scalef32_pk_f16_fp4 v109, v98, 1.0 op_sel:[1,0,0]
	v_cvt_scalef32_pk_f16_fp4 v117, v98, 1.0 op_sel:[0,1,0]
	v_cvt_scalef32_pk_f16_fp4 v98, v98, 1.0 op_sel:[1,1,0]
	v_pk_fma_f16 v98, v44, v98, v106 op_sel_hi:[0,1,1]
	v_cvt_scalef32_pk_f16_fp4 v106, v99, 1.0
	v_pk_fma_f16 v109, v44, v109, v118 op_sel_hi:[0,1,1]
	v_pk_fma_f16 v106, v44, v106, v114 op_sel_hi:[0,1,1]
	v_cvt_scalef32_pk_f16_fp4 v114, v99, 1.0 op_sel:[1,0,0]
	v_cvt_scalef32_pk_f16_fp4 v118, v99, 1.0 op_sel:[0,1,0]
	v_cvt_scalef32_pk_f16_fp4 v99, v99, 1.0 op_sel:[1,1,0]
	v_pk_fma_f16 v99, v44, v99, v107 op_sel_hi:[0,1,1]
	v_cvt_scalef32_pk_f16_fp4 v107, v100, 1.0
	v_pk_fma_f16 v117, v44, v117, v119 op_sel_hi:[0,1,1]
	v_pk_fma_f16 v107, v44, v107, v115 op_sel_hi:[0,1,1]
	v_cvt_scalef32_pk_f16_fp4 v115, v100, 1.0 op_sel:[1,0,0]
	v_cvt_scalef32_pk_f16_fp4 v119, v100, 1.0 op_sel:[0,1,0]
	v_cvt_scalef32_pk_f16_fp4 v100, v100, 1.0 op_sel:[1,1,0]
	v_pk_fma_f16 v100, v44, v100, v108 op_sel_hi:[0,1,1]
	v_cvt_scalef32_pk_f16_fp4 v108, v101, 1.0
	v_pk_fma_f16 v114, v44, v114, v120 op_sel_hi:[0,1,1]
	v_pk_fma_f16 v108, v44, v108, v116 op_sel_hi:[0,1,1]
	v_cvt_scalef32_pk_f16_fp4 v116, v101, 1.0 op_sel:[1,0,0]
	v_cvt_scalef32_pk_f16_fp4 v120, v101, 1.0 op_sel:[0,1,0]
	v_cvt_scalef32_pk_f16_fp4 v101, v101, 1.0 op_sel:[1,1,0]
	v_pk_fma_f16 v42, v44, v101, v42 op_sel_hi:[0,1,1]
	v_cvt_scalef32_pk_f16_fp4 v101, v82, 1.0
	v_pk_fma_f16 v43, v44, v101, v43 op_sel:[1,0,0]
	v_cvt_scalef32_pk_f16_fp4 v101, v82, 1.0 op_sel:[1,0,0]
	v_pk_fma_f16 v101, v44, v101, v109 op_sel:[1,0,0]
	v_cvt_scalef32_pk_f16_fp4 v109, v82, 1.0 op_sel:[0,1,0]
	v_cvt_scalef32_pk_f16_fp4 v82, v82, 1.0 op_sel:[1,1,0]
	v_pk_fma_f16 v82, v44, v82, v98 op_sel:[1,0,0]
	v_cvt_scalef32_pk_f16_fp4 v98, v83, 1.0
	v_pk_fma_f16 v98, v44, v98, v106 op_sel:[1,0,0]
	v_cvt_scalef32_pk_f16_fp4 v106, v83, 1.0 op_sel:[1,0,0]
	v_pk_fma_f16 v106, v44, v106, v114 op_sel:[1,0,0]
	v_cvt_scalef32_pk_f16_fp4 v114, v83, 1.0 op_sel:[0,1,0]
	v_cvt_scalef32_pk_f16_fp4 v83, v83, 1.0 op_sel:[1,1,0]
	v_pk_fma_f16 v83, v44, v83, v99 op_sel:[1,0,0]
	v_cvt_scalef32_pk_f16_fp4 v99, v84, 1.0
	v_pk_fma_f16 v115, v44, v115, v122 op_sel_hi:[0,1,1]
	v_pk_fma_f16 v99, v44, v99, v107 op_sel:[1,0,0]
	v_cvt_scalef32_pk_f16_fp4 v107, v84, 1.0 op_sel:[1,0,0]
	v_pk_fma_f16 v107, v44, v107, v115 op_sel:[1,0,0]
	v_cvt_scalef32_pk_f16_fp4 v115, v84, 1.0 op_sel:[0,1,0]
	v_cvt_scalef32_pk_f16_fp4 v84, v84, 1.0 op_sel:[1,1,0]
	v_pk_fma_f16 v84, v44, v84, v100 op_sel:[1,0,0]
	v_cvt_scalef32_pk_f16_fp4 v100, v85, 1.0
	v_pk_fma_f16 v116, v44, v116, v124 op_sel_hi:[0,1,1]
	v_pk_fma_f16 v100, v44, v100, v108 op_sel:[1,0,0]
	v_cvt_scalef32_pk_f16_fp4 v108, v85, 1.0 op_sel:[1,0,0]
	v_pk_fma_f16 v118, v44, v118, v121 op_sel_hi:[0,1,1]
	v_pk_fma_f16 v119, v44, v119, v123 op_sel_hi:[0,1,1]
	v_pk_fma_f16 v120, v44, v120, v125 op_sel_hi:[0,1,1]
	v_pk_fma_f16 v108, v44, v108, v116 op_sel:[1,0,0]
	v_cvt_scalef32_pk_f16_fp4 v116, v85, 1.0 op_sel:[0,1,0]
	v_cvt_scalef32_pk_f16_fp4 v85, v85, 1.0 op_sel:[1,1,0]
	v_pk_fma_f16 v109, v44, v109, v117 op_sel:[1,0,0]
	v_pk_fma_f16 v114, v44, v114, v118 op_sel:[1,0,0]
	v_pk_fma_f16 v115, v44, v115, v119 op_sel:[1,0,0]
	v_pk_fma_f16 v116, v44, v116, v120 op_sel:[1,0,0]
	v_pk_fma_f16 v42, v44, v85, v42 op_sel:[1,0,0]
	v_cvt_scalef32_pk_f16_fp4 v44, v74, 1.0
	v_pk_fma_f16 v43, v45, v44, v43 op_sel_hi:[0,1,1]
	v_cvt_scalef32_pk_f16_fp4 v44, v74, 1.0 op_sel:[1,0,0]
	v_cvt_scalef32_pk_f16_fp4 v85, v74, 1.0 op_sel:[0,1,0]
	v_cvt_scalef32_pk_f16_fp4 v74, v74, 1.0 op_sel:[1,1,0]
	v_pk_fma_f16 v74, v45, v74, v82 op_sel_hi:[0,1,1]
	v_cvt_scalef32_pk_f16_fp4 v82, v75, 1.0
	v_pk_fma_f16 v44, v45, v44, v101 op_sel_hi:[0,1,1]
	v_pk_fma_f16 v82, v45, v82, v98 op_sel_hi:[0,1,1]
	v_cvt_scalef32_pk_f16_fp4 v98, v75, 1.0 op_sel:[1,0,0]
	v_cvt_scalef32_pk_f16_fp4 v101, v75, 1.0 op_sel:[0,1,0]
	v_cvt_scalef32_pk_f16_fp4 v75, v75, 1.0 op_sel:[1,1,0]
	v_pk_fma_f16 v75, v45, v75, v83 op_sel_hi:[0,1,1]
	v_cvt_scalef32_pk_f16_fp4 v83, v76, 1.0
	v_pk_fma_f16 v98, v45, v98, v106 op_sel_hi:[0,1,1]
	v_pk_fma_f16 v83, v45, v83, v99 op_sel_hi:[0,1,1]
	v_cvt_scalef32_pk_f16_fp4 v99, v76, 1.0 op_sel:[1,0,0]
	v_cvt_scalef32_pk_f16_fp4 v106, v76, 1.0 op_sel:[0,1,0]
	v_cvt_scalef32_pk_f16_fp4 v76, v76, 1.0 op_sel:[1,1,0]
	v_pk_fma_f16 v76, v45, v76, v84 op_sel_hi:[0,1,1]
	v_cvt_scalef32_pk_f16_fp4 v84, v77, 1.0
	v_pk_fma_f16 v99, v45, v99, v107 op_sel_hi:[0,1,1]
	v_pk_fma_f16 v84, v45, v84, v100 op_sel_hi:[0,1,1]
	v_cvt_scalef32_pk_f16_fp4 v100, v77, 1.0 op_sel:[1,0,0]
	v_cvt_scalef32_pk_f16_fp4 v107, v77, 1.0 op_sel:[0,1,0]
	v_cvt_scalef32_pk_f16_fp4 v77, v77, 1.0 op_sel:[1,1,0]
	v_pk_fma_f16 v42, v45, v77, v42 op_sel_hi:[0,1,1]
	v_cvt_scalef32_pk_f16_fp4 v77, v66, 1.0
	v_pk_fma_f16 v43, v45, v77, v43 op_sel:[1,0,0]
	v_cvt_scalef32_pk_f16_fp4 v77, v66, 1.0 op_sel:[1,0,0]
	v_pk_fma_f16 v44, v45, v77, v44 op_sel:[1,0,0]
	v_cvt_scalef32_pk_f16_fp4 v77, v66, 1.0 op_sel:[0,1,0]
	v_cvt_scalef32_pk_f16_fp4 v66, v66, 1.0 op_sel:[1,1,0]
	v_pk_fma_f16 v85, v45, v85, v109 op_sel_hi:[0,1,1]
	v_pk_fma_f16 v66, v45, v66, v74 op_sel:[1,0,0]
	v_cvt_scalef32_pk_f16_fp4 v74, v67, 1.0
	v_pk_fma_f16 v77, v45, v77, v85 op_sel:[1,0,0]
	v_pk_fma_f16 v74, v45, v74, v82 op_sel:[1,0,0]
	v_cvt_scalef32_pk_f16_fp4 v82, v67, 1.0 op_sel:[1,0,0]
	v_cvt_scalef32_pk_f16_fp4 v85, v67, 1.0 op_sel:[0,1,0]
	v_cvt_scalef32_pk_f16_fp4 v67, v67, 1.0 op_sel:[1,1,0]
	v_pk_fma_f16 v67, v45, v67, v75 op_sel:[1,0,0]
	v_cvt_scalef32_pk_f16_fp4 v75, v68, 1.0
	v_pk_fma_f16 v82, v45, v82, v98 op_sel:[1,0,0]
	v_pk_fma_f16 v75, v45, v75, v83 op_sel:[1,0,0]
	v_cvt_scalef32_pk_f16_fp4 v83, v68, 1.0 op_sel:[1,0,0]
	v_cvt_scalef32_pk_f16_fp4 v98, v68, 1.0 op_sel:[0,1,0]
	v_cvt_scalef32_pk_f16_fp4 v68, v68, 1.0 op_sel:[1,1,0]
	v_pk_fma_f16 v68, v45, v68, v76 op_sel:[1,0,0]
	v_cvt_scalef32_pk_f16_fp4 v76, v69, 1.0
	v_pk_fma_f16 v101, v45, v101, v114 op_sel_hi:[0,1,1]
	v_pk_fma_f16 v106, v45, v106, v115 op_sel_hi:[0,1,1]
	v_pk_fma_f16 v100, v45, v100, v108 op_sel_hi:[0,1,1]
	v_pk_fma_f16 v107, v45, v107, v116 op_sel_hi:[0,1,1]
	v_pk_fma_f16 v83, v45, v83, v99 op_sel:[1,0,0]
	v_pk_fma_f16 v76, v45, v76, v84 op_sel:[1,0,0]
	v_cvt_scalef32_pk_f16_fp4 v84, v69, 1.0 op_sel:[1,0,0]
	v_cvt_scalef32_pk_f16_fp4 v99, v69, 1.0 op_sel:[0,1,0]
	v_cvt_scalef32_pk_f16_fp4 v69, v69, 1.0 op_sel:[1,1,0]
	v_pk_fma_f16 v85, v45, v85, v101 op_sel:[1,0,0]
	v_pk_fma_f16 v98, v45, v98, v106 op_sel:[1,0,0]
	v_pk_fma_f16 v84, v45, v84, v100 op_sel:[1,0,0]
	v_pk_fma_f16 v99, v45, v99, v107 op_sel:[1,0,0]
	v_pk_fma_f16 v42, v45, v69, v42 op_sel:[1,0,0]
	s_waitcnt vmcnt(31)
	v_cvt_scalef32_pk_f16_fp4 v45, v62, 1.0
	v_pk_fma_f16 v43, v6, v45, v43 op_sel_hi:[0,1,1]
	v_cvt_scalef32_pk_f16_fp4 v45, v62, 1.0 op_sel:[1,0,0]
	v_pk_fma_f16 v44, v6, v45, v44 op_sel_hi:[0,1,1]
	v_cvt_scalef32_pk_f16_fp4 v45, v62, 1.0 op_sel:[0,1,0]
	v_cvt_scalef32_pk_f16_fp4 v62, v62, 1.0 op_sel:[1,1,0]
	v_pk_fma_f16 v62, v6, v62, v66 op_sel_hi:[0,1,1]
	v_cvt_scalef32_pk_f16_fp4 v66, v63, 1.0
	v_pk_fma_f16 v66, v6, v66, v74 op_sel_hi:[0,1,1]
	v_cvt_scalef32_pk_f16_fp4 v69, v63, 1.0 op_sel:[1,0,0]
	v_cvt_scalef32_pk_f16_fp4 v74, v63, 1.0 op_sel:[0,1,0]
	v_cvt_scalef32_pk_f16_fp4 v63, v63, 1.0 op_sel:[1,1,0]
	v_pk_fma_f16 v63, v6, v63, v67 op_sel_hi:[0,1,1]
	v_cvt_scalef32_pk_f16_fp4 v67, v64, 1.0
	v_pk_fma_f16 v45, v6, v45, v77 op_sel_hi:[0,1,1]
	v_pk_fma_f16 v67, v6, v67, v75 op_sel_hi:[0,1,1]
	v_cvt_scalef32_pk_f16_fp4 v75, v64, 1.0 op_sel:[1,0,0]
	v_cvt_scalef32_pk_f16_fp4 v77, v64, 1.0 op_sel:[0,1,0]
	v_cvt_scalef32_pk_f16_fp4 v64, v64, 1.0 op_sel:[1,1,0]
	v_pk_fma_f16 v64, v6, v64, v68 op_sel_hi:[0,1,1]
	v_cvt_scalef32_pk_f16_fp4 v68, v65, 1.0
	v_pk_fma_f16 v69, v6, v69, v82 op_sel_hi:[0,1,1]
	v_pk_fma_f16 v68, v6, v68, v76 op_sel_hi:[0,1,1]
	v_cvt_scalef32_pk_f16_fp4 v76, v65, 1.0 op_sel:[1,0,0]
	v_cvt_scalef32_pk_f16_fp4 v82, v65, 1.0 op_sel:[0,1,0]
	v_cvt_scalef32_pk_f16_fp4 v65, v65, 1.0 op_sel:[1,1,0]
	v_pk_fma_f16 v42, v6, v65, v42 op_sel_hi:[0,1,1]
	s_waitcnt vmcnt(30)
	v_cvt_scalef32_pk_f16_fp4 v65, v54, 1.0
	v_pk_fma_f16 v43, v6, v65, v43 op_sel:[1,0,0]
	v_cvt_scalef32_pk_f16_fp4 v65, v54, 1.0 op_sel:[1,0,0]
	v_pk_fma_f16 v44, v6, v65, v44 op_sel:[1,0,0]
	v_cvt_scalef32_pk_f16_fp4 v65, v54, 1.0 op_sel:[0,1,0]
	v_cvt_scalef32_pk_f16_fp4 v54, v54, 1.0 op_sel:[1,1,0]
	v_pk_fma_f16 v54, v6, v54, v62 op_sel:[1,0,0]
	v_cvt_scalef32_pk_f16_fp4 v62, v55, 1.0
	v_pk_fma_f16 v45, v6, v65, v45 op_sel:[1,0,0]
	v_pk_fma_f16 v62, v6, v62, v66 op_sel:[1,0,0]
	v_cvt_scalef32_pk_f16_fp4 v65, v55, 1.0 op_sel:[1,0,0]
	v_cvt_scalef32_pk_f16_fp4 v66, v55, 1.0 op_sel:[0,1,0]
	v_cvt_scalef32_pk_f16_fp4 v55, v55, 1.0 op_sel:[1,1,0]
	v_pk_fma_f16 v55, v6, v55, v63 op_sel:[1,0,0]
	v_cvt_scalef32_pk_f16_fp4 v63, v56, 1.0
	v_pk_fma_f16 v65, v6, v65, v69 op_sel:[1,0,0]
	v_pk_fma_f16 v63, v6, v63, v67 op_sel:[1,0,0]
	v_cvt_scalef32_pk_f16_fp4 v67, v56, 1.0 op_sel:[1,0,0]
	v_cvt_scalef32_pk_f16_fp4 v69, v56, 1.0 op_sel:[0,1,0]
	v_cvt_scalef32_pk_f16_fp4 v56, v56, 1.0 op_sel:[1,1,0]
	v_pk_fma_f16 v74, v6, v74, v85 op_sel_hi:[0,1,1]
	v_pk_fma_f16 v56, v6, v56, v64 op_sel:[1,0,0]
	v_cvt_scalef32_pk_f16_fp4 v64, v57, 1.0
	v_pk_fma_f16 v75, v6, v75, v83 op_sel_hi:[0,1,1]
	v_pk_fma_f16 v77, v6, v77, v98 op_sel_hi:[0,1,1]
	v_pk_fma_f16 v76, v6, v76, v84 op_sel_hi:[0,1,1]
	v_pk_fma_f16 v82, v6, v82, v99 op_sel_hi:[0,1,1]
	v_pk_fma_f16 v66, v6, v66, v74 op_sel:[1,0,0]
	v_pk_fma_f16 v64, v6, v64, v68 op_sel:[1,0,0]
	v_cvt_scalef32_pk_f16_fp4 v68, v57, 1.0 op_sel:[1,0,0]
	v_cvt_scalef32_pk_f16_fp4 v74, v57, 1.0 op_sel:[0,1,0]
	v_cvt_scalef32_pk_f16_fp4 v57, v57, 1.0 op_sel:[1,1,0]
	v_pk_fma_f16 v67, v6, v67, v75 op_sel:[1,0,0]
	v_pk_fma_f16 v69, v6, v69, v77 op_sel:[1,0,0]
	v_pk_fma_f16 v68, v6, v68, v76 op_sel:[1,0,0]
	v_pk_fma_f16 v74, v6, v74, v82 op_sel:[1,0,0]
	v_pk_fma_f16 v6, v6, v57, v42 op_sel:[1,0,0]
	s_waitcnt vmcnt(29)
	v_cvt_scalef32_pk_f16_fp4 v42, v46, 1.0
	v_pk_fma_f16 v42, v7, v42, v43 op_sel_hi:[0,1,1]
	v_cvt_scalef32_pk_f16_fp4 v43, v46, 1.0 op_sel:[1,0,0]
	v_pk_fma_f16 v43, v7, v43, v44 op_sel_hi:[0,1,1]
	v_cvt_scalef32_pk_f16_fp4 v44, v46, 1.0 op_sel:[0,1,0]
	v_pk_fma_f16 v44, v7, v44, v45 op_sel_hi:[0,1,1]
	v_cvt_scalef32_pk_f16_fp4 v45, v46, 1.0 op_sel:[1,1,0]
	v_pk_fma_f16 v45, v7, v45, v54 op_sel_hi:[0,1,1]
	v_cvt_scalef32_pk_f16_fp4 v46, v47, 1.0
	v_cvt_scalef32_pk_f16_fp4 v54, v47, 1.0 op_sel:[1,0,0]
	v_cvt_scalef32_pk_f16_fp4 v57, v47, 1.0 op_sel:[0,1,0]
	v_cvt_scalef32_pk_f16_fp4 v47, v47, 1.0 op_sel:[1,1,0]
	v_pk_fma_f16 v47, v7, v47, v55 op_sel_hi:[0,1,1]
	v_cvt_scalef32_pk_f16_fp4 v55, v48, 1.0
	v_pk_fma_f16 v46, v7, v46, v62 op_sel_hi:[0,1,1]
	v_pk_fma_f16 v55, v7, v55, v63 op_sel_hi:[0,1,1]
	v_cvt_scalef32_pk_f16_fp4 v62, v48, 1.0 op_sel:[1,0,0]
	v_cvt_scalef32_pk_f16_fp4 v63, v48, 1.0 op_sel:[0,1,0]
	v_cvt_scalef32_pk_f16_fp4 v48, v48, 1.0 op_sel:[1,1,0]
	v_pk_fma_f16 v48, v7, v48, v56 op_sel_hi:[0,1,1]
	v_cvt_scalef32_pk_f16_fp4 v56, v49, 1.0
	v_pk_fma_f16 v54, v7, v54, v65 op_sel_hi:[0,1,1]
	v_pk_fma_f16 v56, v7, v56, v64 op_sel_hi:[0,1,1]
	v_cvt_scalef32_pk_f16_fp4 v64, v49, 1.0 op_sel:[1,0,0]
	v_cvt_scalef32_pk_f16_fp4 v65, v49, 1.0 op_sel:[0,1,0]
	v_cvt_scalef32_pk_f16_fp4 v49, v49, 1.0 op_sel:[1,1,0]
	v_pk_fma_f16 v6, v7, v49, v6 op_sel_hi:[0,1,1]
	s_waitcnt vmcnt(28)
	v_cvt_scalef32_pk_f16_fp4 v49, v34, 1.0
	v_pk_fma_f16 v42, v7, v49, v42 op_sel:[1,0,0]
	v_cvt_scalef32_pk_f16_fp4 v49, v34, 1.0 op_sel:[1,0,0]
	v_pk_fma_f16 v43, v7, v49, v43 op_sel:[1,0,0]
	v_cvt_scalef32_pk_f16_fp4 v49, v34, 1.0 op_sel:[0,1,0]
	v_cvt_scalef32_pk_f16_fp4 v34, v34, 1.0 op_sel:[1,1,0]
	v_pk_fma_f16 v34, v7, v34, v45 op_sel:[1,0,0]
	v_cvt_scalef32_pk_f16_fp4 v45, v35, 1.0
	v_pk_fma_f16 v44, v7, v49, v44 op_sel:[1,0,0]
	v_pk_fma_f16 v45, v7, v45, v46 op_sel:[1,0,0]
	v_cvt_scalef32_pk_f16_fp4 v46, v35, 1.0 op_sel:[1,0,0]
	v_cvt_scalef32_pk_f16_fp4 v49, v35, 1.0 op_sel:[0,1,0]
	v_cvt_scalef32_pk_f16_fp4 v35, v35, 1.0 op_sel:[1,1,0]
	v_pk_fma_f16 v35, v7, v35, v47 op_sel:[1,0,0]
	v_cvt_scalef32_pk_f16_fp4 v47, v36, 1.0
	v_pk_fma_f16 v46, v7, v46, v54 op_sel:[1,0,0]
	v_pk_fma_f16 v47, v7, v47, v55 op_sel:[1,0,0]
	v_cvt_scalef32_pk_f16_fp4 v54, v36, 1.0 op_sel:[1,0,0]
	v_cvt_scalef32_pk_f16_fp4 v55, v36, 1.0 op_sel:[0,1,0]
	v_cvt_scalef32_pk_f16_fp4 v36, v36, 1.0 op_sel:[1,1,0]
	v_pk_fma_f16 v57, v7, v57, v66 op_sel_hi:[0,1,1]
	v_pk_fma_f16 v36, v7, v36, v48 op_sel:[1,0,0]
	v_cvt_scalef32_pk_f16_fp4 v48, v37, 1.0
	v_pk_fma_f16 v62, v7, v62, v67 op_sel_hi:[0,1,1]
	v_pk_fma_f16 v63, v7, v63, v69 op_sel_hi:[0,1,1]
	v_pk_fma_f16 v64, v7, v64, v68 op_sel_hi:[0,1,1]
	v_pk_fma_f16 v65, v7, v65, v74 op_sel_hi:[0,1,1]
	v_pk_fma_f16 v49, v7, v49, v57 op_sel:[1,0,0]
	v_pk_fma_f16 v48, v7, v48, v56 op_sel:[1,0,0]
	v_cvt_scalef32_pk_f16_fp4 v56, v37, 1.0 op_sel:[1,0,0]
	v_cvt_scalef32_pk_f16_fp4 v57, v37, 1.0 op_sel:[0,1,0]
	v_cvt_scalef32_pk_f16_fp4 v37, v37, 1.0 op_sel:[1,1,0]
	v_pk_fma_f16 v54, v7, v54, v62 op_sel:[1,0,0]
	v_pk_fma_f16 v55, v7, v55, v63 op_sel:[1,0,0]
	v_pk_fma_f16 v56, v7, v56, v64 op_sel:[1,0,0]
	v_pk_fma_f16 v57, v7, v57, v65 op_sel:[1,0,0]
	v_pk_fma_f16 v6, v7, v37, v6 op_sel:[1,0,0]
	s_waitcnt vmcnt(27)
	v_cvt_scalef32_pk_f16_fp4 v7, v26, 1.0
	v_pk_fma_f16 v7, v8, v7, v42 op_sel_hi:[0,1,1]
	v_cvt_scalef32_pk_f16_fp4 v37, v26, 1.0 op_sel:[1,0,0]
	v_cvt_scalef32_pk_f16_fp4 v42, v26, 1.0 op_sel:[0,1,0]
	v_cvt_scalef32_pk_f16_fp4 v26, v26, 1.0 op_sel:[1,1,0]
	v_pk_fma_f16 v37, v8, v37, v43 op_sel_hi:[0,1,1]
	v_pk_fma_f16 v42, v8, v42, v44 op_sel_hi:[0,1,1]
	v_pk_fma_f16 v26, v8, v26, v34 op_sel_hi:[0,1,1]
	v_cvt_scalef32_pk_f16_fp4 v34, v27, 1.0
	v_cvt_scalef32_pk_f16_fp4 v43, v27, 1.0 op_sel:[1,0,0]
	v_cvt_scalef32_pk_f16_fp4 v44, v27, 1.0 op_sel:[0,1,0]
	v_cvt_scalef32_pk_f16_fp4 v27, v27, 1.0 op_sel:[1,1,0]
	v_pk_fma_f16 v34, v8, v34, v45 op_sel_hi:[0,1,1]
	v_pk_fma_f16 v43, v8, v43, v46 op_sel_hi:[0,1,1]
	v_pk_fma_f16 v27, v8, v27, v35 op_sel_hi:[0,1,1]
	v_cvt_scalef32_pk_f16_fp4 v35, v28, 1.0
	v_cvt_scalef32_pk_f16_fp4 v45, v28, 1.0 op_sel:[1,0,0]
	v_cvt_scalef32_pk_f16_fp4 v46, v28, 1.0 op_sel:[0,1,0]
	v_cvt_scalef32_pk_f16_fp4 v28, v28, 1.0 op_sel:[1,1,0]
	v_pk_fma_f16 v28, v8, v28, v36 op_sel_hi:[0,1,1]
	v_cvt_scalef32_pk_f16_fp4 v36, v29, 1.0
	v_pk_fma_f16 v35, v8, v35, v47 op_sel_hi:[0,1,1]
	v_pk_fma_f16 v36, v8, v36, v48 op_sel_hi:[0,1,1]
	v_cvt_scalef32_pk_f16_fp4 v47, v29, 1.0 op_sel:[1,0,0]
	v_cvt_scalef32_pk_f16_fp4 v48, v29, 1.0 op_sel:[0,1,0]
	v_cvt_scalef32_pk_f16_fp4 v29, v29, 1.0 op_sel:[1,1,0]
	v_pk_fma_f16 v6, v8, v29, v6 op_sel_hi:[0,1,1]
	s_waitcnt vmcnt(26)
	v_cvt_scalef32_pk_f16_fp4 v29, v22, 1.0
	v_pk_fma_f16 v7, v8, v29, v7 op_sel:[1,0,0]
	v_cvt_scalef32_pk_f16_fp4 v29, v22, 1.0 op_sel:[1,0,0]
	v_pk_fma_f16 v29, v8, v29, v37 op_sel:[1,0,0]
	v_cvt_scalef32_pk_f16_fp4 v37, v22, 1.0 op_sel:[0,1,0]
	v_cvt_scalef32_pk_f16_fp4 v22, v22, 1.0 op_sel:[1,1,0]
	v_pk_fma_f16 v22, v8, v22, v26 op_sel:[1,0,0]
	v_cvt_scalef32_pk_f16_fp4 v26, v23, 1.0
	v_pk_fma_f16 v37, v8, v37, v42 op_sel:[1,0,0]
	v_pk_fma_f16 v26, v8, v26, v34 op_sel:[1,0,0]
	v_cvt_scalef32_pk_f16_fp4 v34, v23, 1.0 op_sel:[1,0,0]
	v_cvt_scalef32_pk_f16_fp4 v42, v23, 1.0 op_sel:[0,1,0]
	v_cvt_scalef32_pk_f16_fp4 v23, v23, 1.0 op_sel:[1,1,0]
	v_pk_fma_f16 v23, v8, v23, v27 op_sel:[1,0,0]
	v_cvt_scalef32_pk_f16_fp4 v27, v24, 1.0
	v_pk_fma_f16 v34, v8, v34, v43 op_sel:[1,0,0]
	v_pk_fma_f16 v27, v8, v27, v35 op_sel:[1,0,0]
	v_cvt_scalef32_pk_f16_fp4 v35, v24, 1.0 op_sel:[1,0,0]
	v_cvt_scalef32_pk_f16_fp4 v43, v24, 1.0 op_sel:[0,1,0]
	v_cvt_scalef32_pk_f16_fp4 v24, v24, 1.0 op_sel:[1,1,0]
	v_pk_fma_f16 v44, v8, v44, v49 op_sel_hi:[0,1,1]
	v_pk_fma_f16 v24, v8, v24, v28 op_sel:[1,0,0]
	v_cvt_scalef32_pk_f16_fp4 v28, v25, 1.0
	v_pk_fma_f16 v45, v8, v45, v54 op_sel_hi:[0,1,1]
	v_pk_fma_f16 v46, v8, v46, v55 op_sel_hi:[0,1,1]
	v_pk_fma_f16 v47, v8, v47, v56 op_sel_hi:[0,1,1]
	v_pk_fma_f16 v48, v8, v48, v57 op_sel_hi:[0,1,1]
	v_pk_fma_f16 v42, v8, v42, v44 op_sel:[1,0,0]
	v_pk_fma_f16 v28, v8, v28, v36 op_sel:[1,0,0]
	v_cvt_scalef32_pk_f16_fp4 v36, v25, 1.0 op_sel:[1,0,0]
	v_cvt_scalef32_pk_f16_fp4 v44, v25, 1.0 op_sel:[0,1,0]
	v_cvt_scalef32_pk_f16_fp4 v25, v25, 1.0 op_sel:[1,1,0]
	v_pk_fma_f16 v35, v8, v35, v45 op_sel:[1,0,0]
	v_pk_fma_f16 v43, v8, v43, v46 op_sel:[1,0,0]
	v_pk_fma_f16 v36, v8, v36, v47 op_sel:[1,0,0]
	v_pk_fma_f16 v44, v8, v44, v48 op_sel:[1,0,0]
	v_pk_fma_f16 v6, v8, v25, v6 op_sel:[1,0,0]
	s_waitcnt vmcnt(25)
	v_cvt_scalef32_pk_f16_fp4 v8, v14, 1.0
	v_pk_fma_f16 v7, v9, v8, v7 op_sel_hi:[0,1,1]
	v_cvt_scalef32_pk_f16_fp4 v8, v14, 1.0 op_sel:[1,0,0]
	v_cvt_scalef32_pk_f16_fp4 v25, v14, 1.0 op_sel:[0,1,0]
	v_cvt_scalef32_pk_f16_fp4 v14, v14, 1.0 op_sel:[1,1,0]
	v_pk_fma_f16 v14, v9, v14, v22 op_sel_hi:[0,1,1]
	v_cvt_scalef32_pk_f16_fp4 v22, v15, 1.0
	v_pk_fma_f16 v8, v9, v8, v29 op_sel_hi:[0,1,1]
	v_pk_fma_f16 v22, v9, v22, v26 op_sel_hi:[0,1,1]
	v_cvt_scalef32_pk_f16_fp4 v26, v15, 1.0 op_sel:[1,0,0]
	v_cvt_scalef32_pk_f16_fp4 v29, v15, 1.0 op_sel:[0,1,0]
	v_cvt_scalef32_pk_f16_fp4 v15, v15, 1.0 op_sel:[1,1,0]
	v_pk_fma_f16 v15, v9, v15, v23 op_sel_hi:[0,1,1]
	v_cvt_scalef32_pk_f16_fp4 v23, v16, 1.0
	v_pk_fma_f16 v26, v9, v26, v34 op_sel_hi:[0,1,1]
	v_pk_fma_f16 v23, v9, v23, v27 op_sel_hi:[0,1,1]
	v_cvt_scalef32_pk_f16_fp4 v27, v16, 1.0 op_sel:[1,0,0]
	v_cvt_scalef32_pk_f16_fp4 v34, v16, 1.0 op_sel:[0,1,0]
	v_cvt_scalef32_pk_f16_fp4 v16, v16, 1.0 op_sel:[1,1,0]
	v_pk_fma_f16 v16, v9, v16, v24 op_sel_hi:[0,1,1]
	v_cvt_scalef32_pk_f16_fp4 v24, v17, 1.0
	v_pk_fma_f16 v27, v9, v27, v35 op_sel_hi:[0,1,1]
	v_pk_fma_f16 v24, v9, v24, v28 op_sel_hi:[0,1,1]
	v_cvt_scalef32_pk_f16_fp4 v28, v17, 1.0 op_sel:[1,0,0]
	v_cvt_scalef32_pk_f16_fp4 v35, v17, 1.0 op_sel:[0,1,0]
	v_cvt_scalef32_pk_f16_fp4 v17, v17, 1.0 op_sel:[1,1,0]
	v_pk_fma_f16 v6, v9, v17, v6 op_sel_hi:[0,1,1]
	s_waitcnt vmcnt(24)
	v_cvt_scalef32_pk_f16_fp4 v17, v10, 1.0
	v_pk_fma_f16 v7, v9, v17, v7 op_sel:[1,0,0]
	v_cvt_scalef32_pk_f16_fp4 v17, v10, 1.0 op_sel:[1,0,0]
	v_pk_fma_f16 v8, v9, v17, v8 op_sel:[1,0,0]
	v_cvt_scalef32_pk_f16_fp4 v17, v10, 1.0 op_sel:[0,1,0]
	v_cvt_scalef32_pk_f16_fp4 v10, v10, 1.0 op_sel:[1,1,0]
	v_pk_fma_f16 v25, v9, v25, v37 op_sel_hi:[0,1,1]
	v_pk_fma_f16 v10, v9, v10, v14 op_sel:[1,0,0]
	v_cvt_scalef32_pk_f16_fp4 v14, v11, 1.0
	v_pk_fma_f16 v17, v9, v17, v25 op_sel:[1,0,0]
	v_pk_fma_f16 v14, v9, v14, v22 op_sel:[1,0,0]
	v_cvt_scalef32_pk_f16_fp4 v22, v11, 1.0 op_sel:[1,0,0]
	v_cvt_scalef32_pk_f16_fp4 v25, v11, 1.0 op_sel:[0,1,0]
	v_cvt_scalef32_pk_f16_fp4 v11, v11, 1.0 op_sel:[1,1,0]
	v_pk_fma_f16 v11, v9, v11, v15 op_sel:[1,0,0]
	v_cvt_scalef32_pk_f16_fp4 v15, v12, 1.0
	v_pk_fma_f16 v22, v9, v22, v26 op_sel:[1,0,0]
	v_pk_fma_f16 v15, v9, v15, v23 op_sel:[1,0,0]
	v_cvt_scalef32_pk_f16_fp4 v23, v12, 1.0 op_sel:[1,0,0]
	v_cvt_scalef32_pk_f16_fp4 v26, v12, 1.0 op_sel:[0,1,0]
	v_cvt_scalef32_pk_f16_fp4 v12, v12, 1.0 op_sel:[1,1,0]
	v_pk_fma_f16 v29, v9, v29, v42 op_sel_hi:[0,1,1]
	v_pk_fma_f16 v34, v9, v34, v43 op_sel_hi:[0,1,1]
	v_pk_fma_f16 v35, v9, v35, v44 op_sel_hi:[0,1,1]
	v_pk_fma_f16 v23, v9, v23, v27 op_sel:[1,0,0]
	v_pk_fma_f16 v12, v9, v12, v16 op_sel:[1,0,0]
	v_cvt_scalef32_pk_f16_fp4 v16, v13, 1.0
	v_cvt_scalef32_pk_f16_fp4 v27, v13, 1.0 op_sel:[0,1,0]
	v_pk_fma_f16 v25, v9, v25, v29 op_sel:[1,0,0]
	v_pk_fma_f16 v26, v9, v26, v34 op_sel:[1,0,0]
	v_pk_fma_f16 v16, v9, v16, v24 op_sel:[1,0,0]
	v_cvt_scalef32_pk_f16_fp4 v24, v13, 1.0 op_sel:[1,0,0]
	v_pk_fma_f16 v27, v9, v27, v35 op_sel:[1,0,0]
	v_cvt_scalef32_pk_f16_fp4 v13, v13, 1.0 op_sel:[1,1,0]
	v_pk_fma_f16 v28, v9, v28, v36 op_sel_hi:[0,1,1]
	v_pk_fma_f16 v6, v9, v13, v6 op_sel:[1,0,0]
	v_permlane32_swap_b32_e32 v7, v15
	v_permlane32_swap_b32_e32 v17, v26
	v_permlane32_swap_b32_e32 v10, v12
	v_permlane32_swap_b32_e32 v14, v16
	v_permlane32_swap_b32_e32 v25, v27
	v_pk_fma_f16 v24, v9, v24, v28 op_sel:[1,0,0]
	v_pk_add_f16 v7, v7, v15
	v_pk_add_f16 v9, v17, v26
	v_pk_add_f16 v10, v10, v12
	v_pk_add_f16 v12, v14, v16
	v_pk_add_f16 v14, v25, v27
	v_permlane32_swap_b32_e32 v11, v6
	v_permlane32_swap_b32_e32 v8, v23
	v_permlane32_swap_b32_e32 v22, v24
	v_pk_add_f16 v6, v11, v6
	v_permlane16_swap_b32_e32 v7, v12
	v_permlane16_swap_b32_e32 v9, v14
	v_pk_add_f16 v8, v8, v23
	v_pk_add_f16 v13, v22, v24
	v_pk_add_f16 v7, v7, v12
	v_pk_add_f16 v9, v9, v14
	v_permlane16_swap_b32_e32 v10, v6
	v_permlane16_swap_b32_e32 v8, v13
	v_pk_add_f16 v6, v10, v6
	v_cndmask_b32_e64 v10, v9, v7, s[10:11]
	v_cndmask_b32_e64 v7, v7, v9, s[10:11]
	v_pk_add_f16 v8, v8, v13
	v_cvt_f32_f16_sdwa v13, v189 dst_sel:DWORD dst_unused:UNUSED_PAD src0_sel:WORD_1
	v_mov_b32_dpp v7, v7 row_ror:8 row_mask:0xf bank_mask:0xf bound_ctrl:1
	v_pk_add_f16 v9, v10, v7
	v_cndmask_b32_e64 v10, v6, v8, s[10:11]
	v_cndmask_b32_e64 v6, v8, v6, s[10:11]
	v_cvt_f32_f16_sdwa v7, v188 dst_sel:DWORD dst_unused:UNUSED_PAD src0_sel:WORD_1
	v_cvt_f32_f16_e32 v8, v9
	v_mov_b32_dpp v11, v6 row_ror:8 row_mask:0xf bank_mask:0xf bound_ctrl:1
	v_cvt_f32_f16_e32 v6, v188
	v_cvt_f32_f16_sdwa v9, v9 dst_sel:DWORD dst_unused:UNUSED_PAD src0_sel:WORD_1
	v_pk_add_f16 v15, v10, v11
	v_cvt_f32_f16_sdwa v11, v194 dst_sel:DWORD dst_unused:UNUSED_PAD src0_sel:WORD_1
	v_cvt_f32_f16_e32 v10, v194
	v_cvt_f32_f16_e32 v12, v189
	v_cvt_f32_f16_e32 v14, v15
	v_cvt_f32_f16_sdwa v15, v15 dst_sel:DWORD dst_unused:UNUSED_PAD src0_sel:WORD_1
	v_pk_fma_f32 v[6:7], v[2:3], v[8:9], v[6:7]
	v_cvt_f32_f16_sdwa v9, v195 dst_sel:DWORD dst_unused:UNUSED_PAD src0_sel:WORD_1
	v_cvt_f32_f16_e32 v8, v195
	v_pk_add_f32 v[6:7], v[6:7], v[10:11]
	v_pk_fma_f32 v[10:11], v[4:5], v[14:15], v[12:13]
	v_cvt_pk_f16_f32 v6, v6, v7
	v_pk_add_f32 v[8:9], v[10:11], v[8:9]
	s_nop 0
	v_cvt_pk_f16_f32 v7, v8, v9
	v_lshl_add_u64 v[8:9], v[190:191], 0, s[20:21]
	global_store_dwordx2 v[8:9], v[6:7], off
	v_lshl_add_u64 v[6:7], v[184:185], 0, s[22:23]
	v_lshl_add_u64 v[10:11], v[186:187], 0, s[26:27]
	global_load_dwordx4 v[118:121], v[6:7], off offset:48
	global_load_dwordx4 v[122:125], v[6:7], off offset:32
	global_load_dwordx4 v[130:133], v[6:7], off offset:16
	global_load_dwordx4 v[138:141], v[6:7], off
	s_nop 0
	global_load_dwordx4 v[6:9], v[10:11], off offset:16
	global_load_dwordx4 v[42:45], v[10:11], off
	v_lshl_add_u64 v[10:11], v[190:191], 0, s[24:25]
	v_lshl_add_u64 v[12:13], v[192:193], 0, s[24:25]
	global_load_dwordx2 v[194:195], v[10:11], off
	global_load_dwordx2 v[188:189], v[12:13], off
	s_waitcnt vmcnt(29)
	v_lshl_add_u32 v10, v178, 7, v207
	v_lshl_add_u32 v11, v179, 7, v207
	global_load_dwordx4 v[146:149], v10, s[12:13]
	global_load_dwordx4 v[134:137], v11, s[12:13]
	v_lshl_add_u32 v10, v180, 7, v207
	v_lshl_add_u32 v11, v181, 7, v207
	global_load_dwordx4 v[114:117], v10, s[12:13]
	global_load_dwordx4 v[106:109], v11, s[12:13]
	v_lshl_add_u32 v10, v174, 7, v207
	v_lshl_add_u32 v11, v175, 7, v207
	global_load_dwordx4 v[98:101], v10, s[12:13]
	global_load_dwordx4 v[82:85], v11, s[12:13]
	v_lshl_add_u32 v10, v176, 7, v207
	v_lshl_add_u32 v11, v177, 7, v207
	global_load_dwordx4 v[74:77], v10, s[12:13]
	global_load_dwordx4 v[66:69], v11, s[12:13]
	v_lshl_add_u32 v10, v170, 7, v207
	v_lshl_add_u32 v11, v171, 7, v207
	global_load_dwordx4 v[62:65], v10, s[12:13]
	global_load_dwordx4 v[54:57], v11, s[12:13]
	v_lshl_add_u32 v10, v172, 7, v207
	v_lshl_add_u32 v11, v173, 7, v207
	global_load_dwordx4 v[46:49], v10, s[12:13]
	global_load_dwordx4 v[34:37], v11, s[12:13]
	v_lshl_add_u32 v10, v166, 7, v207
	v_lshl_add_u32 v11, v167, 7, v207
	global_load_dwordx4 v[26:29], v10, s[12:13]
	global_load_dwordx4 v[22:25], v11, s[12:13]
	v_lshl_add_u32 v10, v168, 7, v207
	v_lshl_add_u32 v11, v169, 7, v207
	global_load_dwordx4 v[14:17], v10, s[12:13]
	s_nop 0
	global_load_dwordx4 v[10:13], v11, s[12:13]
	s_waitcnt vmcnt(40)
	v_cvt_scalef32_pk_f16_fp4 v166, v162, 1.0
	v_pk_fma_f16 v166, v90, v166, 0 op_sel_hi:[0,1,1]
	v_cvt_scalef32_pk_f16_fp4 v167, v162, 1.0 op_sel:[1,0,0]
	s_waitcnt vmcnt(39)
	v_cvt_scalef32_pk_f16_fp4 v178, v158, 1.0
	v_pk_fma_f16 v167, v90, v167, 0 op_sel_hi:[0,1,1]
	v_cvt_scalef32_pk_f16_fp4 v168, v162, 1.0 op_sel:[0,1,0]
	v_cvt_scalef32_pk_f16_fp4 v162, v162, 1.0 op_sel:[1,1,0]
	v_pk_fma_f16 v166, v90, v178, v166 op_sel:[1,0,0]
	v_cvt_scalef32_pk_f16_fp4 v178, v158, 1.0 op_sel:[1,0,0]
	v_pk_fma_f16 v162, v90, v162, 0 op_sel_hi:[0,1,1]
	v_cvt_scalef32_pk_f16_fp4 v169, v163, 1.0
	v_pk_fma_f16 v167, v90, v178, v167 op_sel:[1,0,0]
	v_cvt_scalef32_pk_f16_fp4 v178, v158, 1.0 op_sel:[0,1,0]
	v_cvt_scalef32_pk_f16_fp4 v158, v158, 1.0 op_sel:[1,1,0]
	v_pk_fma_f16 v169, v90, v169, 0 op_sel_hi:[0,1,1]
	v_cvt_scalef32_pk_f16_fp4 v170, v163, 1.0 op_sel:[1,0,0]
	v_pk_fma_f16 v158, v90, v158, v162 op_sel:[1,0,0]
	v_cvt_scalef32_pk_f16_fp4 v162, v159, 1.0
	v_pk_fma_f16 v170, v90, v170, 0 op_sel_hi:[0,1,1]
	v_cvt_scalef32_pk_f16_fp4 v171, v163, 1.0 op_sel:[0,1,0]
	v_cvt_scalef32_pk_f16_fp4 v163, v163, 1.0 op_sel:[1,1,0]
	v_pk_fma_f16 v162, v90, v162, v169 op_sel:[1,0,0]
	v_cvt_scalef32_pk_f16_fp4 v169, v159, 1.0 op_sel:[1,0,0]
	v_pk_fma_f16 v163, v90, v163, 0 op_sel_hi:[0,1,1]
	v_cvt_scalef32_pk_f16_fp4 v172, v164, 1.0
	v_pk_fma_f16 v169, v90, v169, v170 op_sel:[1,0,0]
	v_cvt_scalef32_pk_f16_fp4 v170, v159, 1.0 op_sel:[0,1,0]
	v_cvt_scalef32_pk_f16_fp4 v159, v159, 1.0 op_sel:[1,1,0]
	v_pk_fma_f16 v171, v90, v171, 0 op_sel_hi:[0,1,1]
	v_pk_fma_f16 v172, v90, v172, 0 op_sel_hi:[0,1,1]
	v_cvt_scalef32_pk_f16_fp4 v173, v164, 1.0 op_sel:[1,0,0]
	v_cvt_scalef32_pk_f16_fp4 v174, v164, 1.0 op_sel:[0,1,0]
	v_cvt_scalef32_pk_f16_fp4 v164, v164, 1.0 op_sel:[1,1,0]
	v_pk_fma_f16 v159, v90, v159, v163 op_sel:[1,0,0]
	v_cvt_scalef32_pk_f16_fp4 v163, v160, 1.0
	v_pk_fma_f16 v173, v90, v173, 0 op_sel_hi:[0,1,1]
	v_pk_fma_f16 v174, v90, v174, 0 op_sel_hi:[0,1,1]
	v_pk_fma_f16 v164, v90, v164, 0 op_sel_hi:[0,1,1]
	v_cvt_scalef32_pk_f16_fp4 v175, v165, 1.0
	v_cvt_scalef32_pk_f16_fp4 v176, v165, 1.0 op_sel:[1,0,0]
	v_cvt_scalef32_pk_f16_fp4 v177, v165, 1.0 op_sel:[0,1,0]
	v_cvt_scalef32_pk_f16_fp4 v165, v165, 1.0 op_sel:[1,1,0]
	v_pk_fma_f16 v170, v90, v170, v171 op_sel:[1,0,0]
	v_pk_fma_f16 v163, v90, v163, v172 op_sel:[1,0,0]
	v_cvt_scalef32_pk_f16_fp4 v171, v160, 1.0 op_sel:[1,0,0]
	v_cvt_scalef32_pk_f16_fp4 v172, v160, 1.0 op_sel:[0,1,0]
	v_cvt_scalef32_pk_f16_fp4 v160, v160, 1.0 op_sel:[1,1,0]
	v_pk_fma_f16 v168, v90, v168, 0 op_sel_hi:[0,1,1]
	v_pk_fma_f16 v175, v90, v175, 0 op_sel_hi:[0,1,1]
	v_pk_fma_f16 v176, v90, v176, 0 op_sel_hi:[0,1,1]
	v_pk_fma_f16 v177, v90, v177, 0 op_sel_hi:[0,1,1]
	v_pk_fma_f16 v165, v90, v165, 0 op_sel_hi:[0,1,1]
	v_pk_fma_f16 v171, v90, v171, v173 op_sel:[1,0,0]
	v_pk_fma_f16 v172, v90, v172, v174 op_sel:[1,0,0]
	v_pk_fma_f16 v160, v90, v160, v164 op_sel:[1,0,0]
	v_cvt_scalef32_pk_f16_fp4 v164, v161, 1.0
	v_cvt_scalef32_pk_f16_fp4 v173, v161, 1.0 op_sel:[1,0,0]
	v_cvt_scalef32_pk_f16_fp4 v174, v161, 1.0 op_sel:[0,1,0]
	v_cvt_scalef32_pk_f16_fp4 v161, v161, 1.0 op_sel:[1,1,0]
	v_pk_fma_f16 v168, v90, v178, v168 op_sel:[1,0,0]
	v_pk_fma_f16 v164, v90, v164, v175 op_sel:[1,0,0]
	v_pk_fma_f16 v173, v90, v173, v176 op_sel:[1,0,0]
	v_pk_fma_f16 v174, v90, v174, v177 op_sel:[1,0,0]
	v_pk_fma_f16 v90, v90, v161, v165 op_sel:[1,0,0]
	s_waitcnt vmcnt(38)
	v_cvt_scalef32_pk_f16_fp4 v161, v154, 1.0
	v_pk_fma_f16 v161, v91, v161, v166 op_sel_hi:[0,1,1]
	v_cvt_scalef32_pk_f16_fp4 v165, v154, 1.0 op_sel:[1,0,0]
	v_cvt_scalef32_pk_f16_fp4 v166, v154, 1.0 op_sel:[0,1,0]
	v_cvt_scalef32_pk_f16_fp4 v154, v154, 1.0 op_sel:[1,1,0]
	v_pk_fma_f16 v154, v91, v154, v158 op_sel_hi:[0,1,1]
	v_cvt_scalef32_pk_f16_fp4 v158, v155, 1.0
	v_pk_fma_f16 v165, v91, v165, v167 op_sel_hi:[0,1,1]
	v_pk_fma_f16 v158, v91, v158, v162 op_sel_hi:[0,1,1]
	v_cvt_scalef32_pk_f16_fp4 v162, v155, 1.0 op_sel:[1,0,0]
	v_cvt_scalef32_pk_f16_fp4 v167, v155, 1.0 op_sel:[0,1,0]
	v_cvt_scalef32_pk_f16_fp4 v155, v155, 1.0 op_sel:[1,1,0]
	v_pk_fma_f16 v155, v91, v155, v159 op_sel_hi:[0,1,1]
	v_cvt_scalef32_pk_f16_fp4 v159, v156, 1.0
	v_pk_fma_f16 v166, v91, v166, v168 op_sel_hi:[0,1,1]
	v_pk_fma_f16 v159, v91, v159, v163 op_sel_hi:[0,1,1]
	v_cvt_scalef32_pk_f16_fp4 v163, v156, 1.0 op_sel:[1,0,0]
	v_cvt_scalef32_pk_f16_fp4 v168, v156, 1.0 op_sel:[0,1,0]
	v_cvt_scalef32_pk_f16_fp4 v156, v156, 1.0 op_sel:[1,1,0]
	v_pk_fma_f16 v156, v91, v156, v160 op_sel_hi:[0,1,1]
	v_cvt_scalef32_pk_f16_fp4 v160, v157, 1.0
	v_pk_fma_f16 v162, v91, v162, v169 op_sel_hi:[0,1,1]
	v_pk_fma_f16 v160, v91, v160, v164 op_sel_hi:[0,1,1]
	v_cvt_scalef32_pk_f16_fp4 v164, v157, 1.0 op_sel:[1,0,0]
	v_cvt_scalef32_pk_f16_fp4 v169, v157, 1.0 op_sel:[0,1,0]
	v_cvt_scalef32_pk_f16_fp4 v157, v157, 1.0 op_sel:[1,1,0]
	v_pk_fma_f16 v90, v91, v157, v90 op_sel_hi:[0,1,1]
	s_waitcnt vmcnt(37)
	v_cvt_scalef32_pk_f16_fp4 v157, v150, 1.0
	v_pk_fma_f16 v157, v91, v157, v161 op_sel:[1,0,0]
	v_cvt_scalef32_pk_f16_fp4 v161, v150, 1.0 op_sel:[1,0,0]
	v_pk_fma_f16 v161, v91, v161, v165 op_sel:[1,0,0]
	v_cvt_scalef32_pk_f16_fp4 v165, v150, 1.0 op_sel:[0,1,0]
	v_cvt_scalef32_pk_f16_fp4 v150, v150, 1.0 op_sel:[1,1,0]
	v_pk_fma_f16 v150, v91, v150, v154 op_sel:[1,0,0]
	v_cvt_scalef32_pk_f16_fp4 v154, v151, 1.0
	v_pk_fma_f16 v154, v91, v154, v158 op_sel:[1,0,0]
	v_cvt_scalef32_pk_f16_fp4 v158, v151, 1.0 op_sel:[1,0,0]
	v_pk_fma_f16 v158, v91, v158, v162 op_sel:[1,0,0]
	v_cvt_scalef32_pk_f16_fp4 v162, v151, 1.0 op_sel:[0,1,0]
	v_cvt_scalef32_pk_f16_fp4 v151, v151, 1.0 op_sel:[1,1,0]
	v_pk_fma_f16 v151, v91, v151, v155 op_sel:[1,0,0]
	v_cvt_scalef32_pk_f16_fp4 v155, v152, 1.0
	v_pk_fma_f16 v163, v91, v163, v171 op_sel_hi:[0,1,1]
	v_pk_fma_f16 v155, v91, v155, v159 op_sel:[1,0,0]
	v_cvt_scalef32_pk_f16_fp4 v159, v152, 1.0 op_sel:[1,0,0]
	v_pk_fma_f16 v159, v91, v159, v163 op_sel:[1,0,0]
	v_cvt_scalef32_pk_f16_fp4 v163, v152, 1.0 op_sel:[0,1,0]
	v_cvt_scalef32_pk_f16_fp4 v152, v152, 1.0 op_sel:[1,1,0]
	v_pk_fma_f16 v152, v91, v152, v156 op_sel:[1,0,0]
	v_cvt_scalef32_pk_f16_fp4 v156, v153, 1.0
	v_pk_fma_f16 v164, v91, v164, v173 op_sel_hi:[0,1,1]
	v_pk_fma_f16 v156, v91, v156, v160 op_sel:[1,0,0]
	v_cvt_scalef32_pk_f16_fp4 v160, v153, 1.0 op_sel:[1,0,0]
	v_pk_fma_f16 v167, v91, v167, v170 op_sel_hi:[0,1,1]
	v_pk_fma_f16 v168, v91, v168, v172 op_sel_hi:[0,1,1]
	v_pk_fma_f16 v169, v91, v169, v174 op_sel_hi:[0,1,1]
	v_pk_fma_f16 v160, v91, v160, v164 op_sel:[1,0,0]
	v_cvt_scalef32_pk_f16_fp4 v164, v153, 1.0 op_sel:[0,1,0]
	v_cvt_scalef32_pk_f16_fp4 v153, v153, 1.0 op_sel:[1,1,0]
	v_pk_fma_f16 v165, v91, v165, v166 op_sel:[1,0,0]
	v_pk_fma_f16 v162, v91, v162, v167 op_sel:[1,0,0]
	v_pk_fma_f16 v163, v91, v163, v168 op_sel:[1,0,0]
	v_pk_fma_f16 v164, v91, v164, v169 op_sel:[1,0,0]
	v_pk_fma_f16 v90, v91, v153, v90 op_sel:[1,0,0]
	s_waitcnt vmcnt(36)
	v_cvt_scalef32_pk_f16_fp4 v91, v142, 1.0
	v_pk_fma_f16 v91, v92, v91, v157 op_sel_hi:[0,1,1]
	v_cvt_scalef32_pk_f16_fp4 v153, v142, 1.0 op_sel:[1,0,0]
	v_cvt_scalef32_pk_f16_fp4 v157, v142, 1.0 op_sel:[0,1,0]
	v_cvt_scalef32_pk_f16_fp4 v142, v142, 1.0 op_sel:[1,1,0]
	v_pk_fma_f16 v142, v92, v142, v150 op_sel_hi:[0,1,1]
	v_cvt_scalef32_pk_f16_fp4 v150, v143, 1.0
	v_pk_fma_f16 v150, v92, v150, v154 op_sel_hi:[0,1,1]
	v_cvt_scalef32_pk_f16_fp4 v154, v143, 1.0 op_sel:[1,0,0]
	v_pk_fma_f16 v154, v92, v154, v158 op_sel_hi:[0,1,1]
	v_cvt_scalef32_pk_f16_fp4 v158, v143, 1.0 op_sel:[0,1,0]
	v_cvt_scalef32_pk_f16_fp4 v143, v143, 1.0 op_sel:[1,1,0]
	v_pk_fma_f16 v143, v92, v143, v151 op_sel_hi:[0,1,1]
	v_cvt_scalef32_pk_f16_fp4 v151, v144, 1.0
	v_pk_fma_f16 v151, v92, v151, v155 op_sel_hi:[0,1,1]
	v_cvt_scalef32_pk_f16_fp4 v155, v144, 1.0 op_sel:[1,0,0]
	v_pk_fma_f16 v155, v92, v155, v159 op_sel_hi:[0,1,1]
	v_cvt_scalef32_pk_f16_fp4 v159, v144, 1.0 op_sel:[0,1,0]
	v_cvt_scalef32_pk_f16_fp4 v144, v144, 1.0 op_sel:[1,1,0]
	v_pk_fma_f16 v144, v92, v144, v152 op_sel_hi:[0,1,1]
	v_cvt_scalef32_pk_f16_fp4 v152, v145, 1.0
	v_pk_fma_f16 v152, v92, v152, v156 op_sel_hi:[0,1,1]
	v_cvt_scalef32_pk_f16_fp4 v156, v145, 1.0 op_sel:[1,0,0]
	v_pk_fma_f16 v156, v92, v156, v160 op_sel_hi:[0,1,1]
	v_cvt_scalef32_pk_f16_fp4 v160, v145, 1.0 op_sel:[0,1,0]
	v_cvt_scalef32_pk_f16_fp4 v145, v145, 1.0 op_sel:[1,1,0]
	v_pk_fma_f16 v90, v92, v145, v90 op_sel_hi:[0,1,1]
	s_waitcnt vmcnt(35)
	v_cvt_scalef32_pk_f16_fp4 v145, v126, 1.0
	v_pk_fma_f16 v153, v92, v153, v161 op_sel_hi:[0,1,1]
	v_pk_fma_f16 v91, v92, v145, v91 op_sel:[1,0,0]
	v_cvt_scalef32_pk_f16_fp4 v145, v126, 1.0 op_sel:[1,0,0]
	v_pk_fma_f16 v145, v92, v145, v153 op_sel:[1,0,0]
	v_cvt_scalef32_pk_f16_fp4 v153, v126, 1.0 op_sel:[0,1,0]
	v_cvt_scalef32_pk_f16_fp4 v126, v126, 1.0 op_sel:[1,1,0]
	v_pk_fma_f16 v126, v92, v126, v142 op_sel:[1,0,0]
	v_cvt_scalef32_pk_f16_fp4 v142, v127, 1.0
	v_pk_fma_f16 v142, v92, v142, v150 op_sel:[1,0,0]
	v_cvt_scalef32_pk_f16_fp4 v150, v127, 1.0 op_sel:[1,0,0]
	v_pk_fma_f16 v150, v92, v150, v154 op_sel:[1,0,0]
	v_cvt_scalef32_pk_f16_fp4 v154, v127, 1.0 op_sel:[0,1,0]
	v_cvt_scalef32_pk_f16_fp4 v127, v127, 1.0 op_sel:[1,1,0]
	v_pk_fma_f16 v127, v92, v127, v143 op_sel:[1,0,0]
	v_cvt_scalef32_pk_f16_fp4 v143, v128, 1.0
	v_pk_fma_f16 v143, v92, v143, v151 op_sel:[1,0,0]
	v_cvt_scalef32_pk_f16_fp4 v151, v128, 1.0 op_sel:[1,0,0]
	v_pk_fma_f16 v151, v92, v151, v155 op_sel:[1,0,0]
	v_cvt_scalef32_pk_f16_fp4 v155, v128, 1.0 op_sel:[0,1,0]
	v_cvt_scalef32_pk_f16_fp4 v128, v128, 1.0 op_sel:[1,1,0]
	v_pk_fma_f16 v128, v92, v128, v144 op_sel:[1,0,0]
	v_cvt_scalef32_pk_f16_fp4 v144, v129, 1.0
	v_pk_fma_f16 v144, v92, v144, v152 op_sel:[1,0,0]
	v_cvt_scalef32_pk_f16_fp4 v152, v129, 1.0 op_sel:[1,0,0]
	v_pk_fma_f16 v157, v92, v157, v165 op_sel_hi:[0,1,1]
	v_pk_fma_f16 v158, v92, v158, v162 op_sel_hi:[0,1,1]
	v_pk_fma_f16 v159, v92, v159, v163 op_sel_hi:[0,1,1]
	v_pk_fma_f16 v160, v92, v160, v164 op_sel_hi:[0,1,1]
	v_pk_fma_f16 v152, v92, v152, v156 op_sel:[1,0,0]
	v_cvt_scalef32_pk_f16_fp4 v156, v129, 1.0 op_sel:[0,1,0]
	v_cvt_scalef32_pk_f16_fp4 v129, v129, 1.0 op_sel:[1,1,0]
	v_pk_fma_f16 v153, v92, v153, v157 op_sel:[1,0,0]
	v_pk_fma_f16 v154, v92, v154, v158 op_sel:[1,0,0]
	v_pk_fma_f16 v155, v92, v155, v159 op_sel:[1,0,0]
	v_pk_fma_f16 v156, v92, v156, v160 op_sel:[1,0,0]
	v_pk_fma_f16 v90, v92, v129, v90 op_sel:[1,0,0]
	s_waitcnt vmcnt(34)
	v_cvt_scalef32_pk_f16_fp4 v92, v110, 1.0
	v_pk_fma_f16 v91, v93, v92, v91 op_sel_hi:[0,1,1]
	v_cvt_scalef32_pk_f16_fp4 v92, v110, 1.0 op_sel:[1,0,0]
	v_cvt_scalef32_pk_f16_fp4 v129, v110, 1.0 op_sel:[0,1,0]
	v_cvt_scalef32_pk_f16_fp4 v110, v110, 1.0 op_sel:[1,1,0]
	v_pk_fma_f16 v110, v93, v110, v126 op_sel_hi:[0,1,1]
	v_cvt_scalef32_pk_f16_fp4 v126, v111, 1.0
	v_pk_fma_f16 v92, v93, v92, v145 op_sel_hi:[0,1,1]
	v_pk_fma_f16 v126, v93, v126, v142 op_sel_hi:[0,1,1]
	v_cvt_scalef32_pk_f16_fp4 v142, v111, 1.0 op_sel:[1,0,0]
	v_cvt_scalef32_pk_f16_fp4 v145, v111, 1.0 op_sel:[0,1,0]
	v_cvt_scalef32_pk_f16_fp4 v111, v111, 1.0 op_sel:[1,1,0]
	v_pk_fma_f16 v111, v93, v111, v127 op_sel_hi:[0,1,1]
	v_cvt_scalef32_pk_f16_fp4 v127, v112, 1.0
	v_pk_fma_f16 v142, v93, v142, v150 op_sel_hi:[0,1,1]
	v_pk_fma_f16 v127, v93, v127, v143 op_sel_hi:[0,1,1]
	v_cvt_scalef32_pk_f16_fp4 v143, v112, 1.0 op_sel:[1,0,0]
	v_cvt_scalef32_pk_f16_fp4 v150, v112, 1.0 op_sel:[0,1,0]
	v_cvt_scalef32_pk_f16_fp4 v112, v112, 1.0 op_sel:[1,1,0]
	v_pk_fma_f16 v112, v93, v112, v128 op_sel_hi:[0,1,1]
	v_cvt_scalef32_pk_f16_fp4 v128, v113, 1.0
	v_pk_fma_f16 v143, v93, v143, v151 op_sel_hi:[0,1,1]
	v_pk_fma_f16 v128, v93, v128, v144 op_sel_hi:[0,1,1]
	v_cvt_scalef32_pk_f16_fp4 v144, v113, 1.0 op_sel:[1,0,0]
	v_cvt_scalef32_pk_f16_fp4 v151, v113, 1.0 op_sel:[0,1,0]
	v_cvt_scalef32_pk_f16_fp4 v113, v113, 1.0 op_sel:[1,1,0]
	v_pk_fma_f16 v90, v93, v113, v90 op_sel_hi:[0,1,1]
	s_waitcnt vmcnt(33)
	v_cvt_scalef32_pk_f16_fp4 v113, v102, 1.0
	v_pk_fma_f16 v91, v93, v113, v91 op_sel:[1,0,0]
	v_cvt_scalef32_pk_f16_fp4 v113, v102, 1.0 op_sel:[1,0,0]
	v_pk_fma_f16 v92, v93, v113, v92 op_sel:[1,0,0]
	v_cvt_scalef32_pk_f16_fp4 v113, v102, 1.0 op_sel:[0,1,0]
	v_cvt_scalef32_pk_f16_fp4 v102, v102, 1.0 op_sel:[1,1,0]
	v_pk_fma_f16 v129, v93, v129, v153 op_sel_hi:[0,1,1]
	v_pk_fma_f16 v102, v93, v102, v110 op_sel:[1,0,0]
	v_cvt_scalef32_pk_f16_fp4 v110, v103, 1.0
	v_pk_fma_f16 v113, v93, v113, v129 op_sel:[1,0,0]
	v_pk_fma_f16 v110, v93, v110, v126 op_sel:[1,0,0]
	v_cvt_scalef32_pk_f16_fp4 v126, v103, 1.0 op_sel:[1,0,0]
	v_cvt_scalef32_pk_f16_fp4 v129, v103, 1.0 op_sel:[0,1,0]
	v_cvt_scalef32_pk_f16_fp4 v103, v103, 1.0 op_sel:[1,1,0]
	v_pk_fma_f16 v103, v93, v103, v111 op_sel:[1,0,0]
	v_cvt_scalef32_pk_f16_fp4 v111, v104, 1.0
	v_pk_fma_f16 v126, v93, v126, v142 op_sel:[1,0,0]
	v_pk_fma_f16 v111, v93, v111, v127 op_sel:[1,0,0]
	v_cvt_scalef32_pk_f16_fp4 v127, v104, 1.0 op_sel:[1,0,0]
	v_cvt_scalef32_pk_f16_fp4 v142, v104, 1.0 op_sel:[0,1,0]
	v_cvt_scalef32_pk_f16_fp4 v104, v104, 1.0 op_sel:[1,1,0]
	v_pk_fma_f16 v104, v93, v104, v112 op_sel:[1,0,0]
	v_cvt_scalef32_pk_f16_fp4 v112, v105, 1.0
	v_pk_fma_f16 v145, v93, v145, v154 op_sel_hi:[0,1,1]
	v_pk_fma_f16 v150, v93, v150, v155 op_sel_hi:[0,1,1]
	v_pk_fma_f16 v144, v93, v144, v152 op_sel_hi:[0,1,1]
	v_pk_fma_f16 v151, v93, v151, v156 op_sel_hi:[0,1,1]
	v_pk_fma_f16 v127, v93, v127, v143 op_sel:[1,0,0]
	v_pk_fma_f16 v112, v93, v112, v128 op_sel:[1,0,0]
	v_cvt_scalef32_pk_f16_fp4 v128, v105, 1.0 op_sel:[1,0,0]
	v_cvt_scalef32_pk_f16_fp4 v143, v105, 1.0 op_sel:[0,1,0]
	v_cvt_scalef32_pk_f16_fp4 v105, v105, 1.0 op_sel:[1,1,0]
	v_pk_fma_f16 v129, v93, v129, v145 op_sel:[1,0,0]
	v_pk_fma_f16 v142, v93, v142, v150 op_sel:[1,0,0]
	v_pk_fma_f16 v128, v93, v128, v144 op_sel:[1,0,0]
	v_pk_fma_f16 v143, v93, v143, v151 op_sel:[1,0,0]
	v_pk_fma_f16 v90, v93, v105, v90 op_sel:[1,0,0]
	s_waitcnt vmcnt(32)
	v_cvt_scalef32_pk_f16_fp4 v93, v94, 1.0
	v_pk_fma_f16 v91, v18, v93, v91 op_sel_hi:[0,1,1]
	v_cvt_scalef32_pk_f16_fp4 v93, v94, 1.0 op_sel:[1,0,0]
	v_pk_fma_f16 v92, v18, v93, v92 op_sel_hi:[0,1,1]
	v_cvt_scalef32_pk_f16_fp4 v93, v94, 1.0 op_sel:[0,1,0]
	v_cvt_scalef32_pk_f16_fp4 v94, v94, 1.0 op_sel:[1,1,0]
	v_pk_fma_f16 v94, v18, v94, v102 op_sel_hi:[0,1,1]
	v_cvt_scalef32_pk_f16_fp4 v102, v95, 1.0
	v_pk_fma_f16 v102, v18, v102, v110 op_sel_hi:[0,1,1]
	v_cvt_scalef32_pk_f16_fp4 v105, v95, 1.0 op_sel:[1,0,0]
	v_cvt_scalef32_pk_f16_fp4 v110, v95, 1.0 op_sel:[0,1,0]
	v_cvt_scalef32_pk_f16_fp4 v95, v95, 1.0 op_sel:[1,1,0]
	v_pk_fma_f16 v95, v18, v95, v103 op_sel_hi:[0,1,1]
	v_cvt_scalef32_pk_f16_fp4 v103, v96, 1.0
	v_pk_fma_f16 v93, v18, v93, v113 op_sel_hi:[0,1,1]
	v_pk_fma_f16 v103, v18, v103, v111 op_sel_hi:[0,1,1]
	v_cvt_scalef32_pk_f16_fp4 v111, v96, 1.0 op_sel:[1,0,0]
	v_cvt_scalef32_pk_f16_fp4 v113, v96, 1.0 op_sel:[0,1,0]
	v_cvt_scalef32_pk_f16_fp4 v96, v96, 1.0 op_sel:[1,1,0]
	v_pk_fma_f16 v96, v18, v96, v104 op_sel_hi:[0,1,1]
	v_cvt_scalef32_pk_f16_fp4 v104, v97, 1.0
	v_pk_fma_f16 v105, v18, v105, v126 op_sel_hi:[0,1,1]
	v_pk_fma_f16 v104, v18, v104, v112 op_sel_hi:[0,1,1]
	v_cvt_scalef32_pk_f16_fp4 v112, v97, 1.0 op_sel:[1,0,0]
	v_cvt_scalef32_pk_f16_fp4 v126, v97, 1.0 op_sel:[0,1,0]
	v_cvt_scalef32_pk_f16_fp4 v97, v97, 1.0 op_sel:[1,1,0]
	v_pk_fma_f16 v90, v18, v97, v90 op_sel_hi:[0,1,1]
	s_waitcnt vmcnt(31)
	v_cvt_scalef32_pk_f16_fp4 v97, v86, 1.0
	v_pk_fma_f16 v91, v18, v97, v91 op_sel:[1,0,0]
	v_cvt_scalef32_pk_f16_fp4 v97, v86, 1.0 op_sel:[1,0,0]
	v_pk_fma_f16 v92, v18, v97, v92 op_sel:[1,0,0]
	v_cvt_scalef32_pk_f16_fp4 v97, v86, 1.0 op_sel:[0,1,0]
	v_cvt_scalef32_pk_f16_fp4 v86, v86, 1.0 op_sel:[1,1,0]
	v_pk_fma_f16 v86, v18, v86, v94 op_sel:[1,0,0]
	v_cvt_scalef32_pk_f16_fp4 v94, v87, 1.0
	v_pk_fma_f16 v93, v18, v97, v93 op_sel:[1,0,0]
	v_pk_fma_f16 v94, v18, v94, v102 op_sel:[1,0,0]
	v_cvt_scalef32_pk_f16_fp4 v97, v87, 1.0 op_sel:[1,0,0]
	v_cvt_scalef32_pk_f16_fp4 v102, v87, 1.0 op_sel:[0,1,0]
	v_cvt_scalef32_pk_f16_fp4 v87, v87, 1.0 op_sel:[1,1,0]
	v_pk_fma_f16 v87, v18, v87, v95 op_sel:[1,0,0]
	v_cvt_scalef32_pk_f16_fp4 v95, v88, 1.0
	v_pk_fma_f16 v97, v18, v97, v105 op_sel:[1,0,0]
	v_pk_fma_f16 v95, v18, v95, v103 op_sel:[1,0,0]
	v_cvt_scalef32_pk_f16_fp4 v103, v88, 1.0 op_sel:[1,0,0]
	v_cvt_scalef32_pk_f16_fp4 v105, v88, 1.0 op_sel:[0,1,0]
	v_cvt_scalef32_pk_f16_fp4 v88, v88, 1.0 op_sel:[1,1,0]
	v_pk_fma_f16 v110, v18, v110, v129 op_sel_hi:[0,1,1]
	v_pk_fma_f16 v88, v18, v88, v96 op_sel:[1,0,0]
	v_cvt_scalef32_pk_f16_fp4 v96, v89, 1.0
	v_pk_fma_f16 v111, v18, v111, v127 op_sel_hi:[0,1,1]
	v_pk_fma_f16 v113, v18, v113, v142 op_sel_hi:[0,1,1]
	v_pk_fma_f16 v112, v18, v112, v128 op_sel_hi:[0,1,1]
	v_pk_fma_f16 v126, v18, v126, v143 op_sel_hi:[0,1,1]
	v_pk_fma_f16 v102, v18, v102, v110 op_sel:[1,0,0]
	v_pk_fma_f16 v96, v18, v96, v104 op_sel:[1,0,0]
	v_cvt_scalef32_pk_f16_fp4 v104, v89, 1.0 op_sel:[1,0,0]
	v_cvt_scalef32_pk_f16_fp4 v110, v89, 1.0 op_sel:[0,1,0]
	v_cvt_scalef32_pk_f16_fp4 v89, v89, 1.0 op_sel:[1,1,0]
	v_pk_fma_f16 v103, v18, v103, v111 op_sel:[1,0,0]
	v_pk_fma_f16 v105, v18, v105, v113 op_sel:[1,0,0]
	v_pk_fma_f16 v104, v18, v104, v112 op_sel:[1,0,0]
	v_pk_fma_f16 v110, v18, v110, v126 op_sel:[1,0,0]
	v_pk_fma_f16 v18, v18, v89, v90 op_sel:[1,0,0]
	s_waitcnt vmcnt(30)
	v_cvt_scalef32_pk_f16_fp4 v89, v78, 1.0
	v_pk_fma_f16 v89, v19, v89, v91 op_sel_hi:[0,1,1]
	v_cvt_scalef32_pk_f16_fp4 v90, v78, 1.0 op_sel:[1,0,0]
	v_cvt_scalef32_pk_f16_fp4 v91, v78, 1.0 op_sel:[0,1,0]
	v_cvt_scalef32_pk_f16_fp4 v78, v78, 1.0 op_sel:[1,1,0]
	v_pk_fma_f16 v90, v19, v90, v92 op_sel_hi:[0,1,1]
	v_pk_fma_f16 v91, v19, v91, v93 op_sel_hi:[0,1,1]
	v_pk_fma_f16 v78, v19, v78, v86 op_sel_hi:[0,1,1]
	v_cvt_scalef32_pk_f16_fp4 v86, v79, 1.0
	v_cvt_scalef32_pk_f16_fp4 v92, v79, 1.0 op_sel:[1,0,0]
	v_cvt_scalef32_pk_f16_fp4 v93, v79, 1.0 op_sel:[0,1,0]
	v_cvt_scalef32_pk_f16_fp4 v79, v79, 1.0 op_sel:[1,1,0]
	v_pk_fma_f16 v79, v19, v79, v87 op_sel_hi:[0,1,1]
	v_cvt_scalef32_pk_f16_fp4 v87, v80, 1.0
	v_pk_fma_f16 v86, v19, v86, v94 op_sel_hi:[0,1,1]
	v_pk_fma_f16 v87, v19, v87, v95 op_sel_hi:[0,1,1]
	v_cvt_scalef32_pk_f16_fp4 v94, v80, 1.0 op_sel:[1,0,0]
	v_cvt_scalef32_pk_f16_fp4 v95, v80, 1.0 op_sel:[0,1,0]
	v_cvt_scalef32_pk_f16_fp4 v80, v80, 1.0 op_sel:[1,1,0]
	v_pk_fma_f16 v80, v19, v80, v88 op_sel_hi:[0,1,1]
	v_cvt_scalef32_pk_f16_fp4 v88, v81, 1.0
	v_pk_fma_f16 v92, v19, v92, v97 op_sel_hi:[0,1,1]
	v_pk_fma_f16 v88, v19, v88, v96 op_sel_hi:[0,1,1]
	v_cvt_scalef32_pk_f16_fp4 v96, v81, 1.0 op_sel:[1,0,0]
	v_cvt_scalef32_pk_f16_fp4 v97, v81, 1.0 op_sel:[0,1,0]
	v_cvt_scalef32_pk_f16_fp4 v81, v81, 1.0 op_sel:[1,1,0]
	v_pk_fma_f16 v18, v19, v81, v18 op_sel_hi:[0,1,1]
	s_waitcnt vmcnt(29)
	v_cvt_scalef32_pk_f16_fp4 v81, v70, 1.0
	v_pk_fma_f16 v81, v19, v81, v89 op_sel:[1,0,0]
	v_cvt_scalef32_pk_f16_fp4 v89, v70, 1.0 op_sel:[1,0,0]
	v_pk_fma_f16 v89, v19, v89, v90 op_sel:[1,0,0]
	v_cvt_scalef32_pk_f16_fp4 v90, v70, 1.0 op_sel:[0,1,0]
	v_cvt_scalef32_pk_f16_fp4 v70, v70, 1.0 op_sel:[1,1,0]
	v_pk_fma_f16 v70, v19, v70, v78 op_sel:[1,0,0]
	v_cvt_scalef32_pk_f16_fp4 v78, v71, 1.0
	v_pk_fma_f16 v90, v19, v90, v91 op_sel:[1,0,0]
	v_pk_fma_f16 v78, v19, v78, v86 op_sel:[1,0,0]
	v_cvt_scalef32_pk_f16_fp4 v86, v71, 1.0 op_sel:[1,0,0]
	v_cvt_scalef32_pk_f16_fp4 v91, v71, 1.0 op_sel:[0,1,0]
	v_cvt_scalef32_pk_f16_fp4 v71, v71, 1.0 op_sel:[1,1,0]
	v_pk_fma_f16 v71, v19, v71, v79 op_sel:[1,0,0]
	v_cvt_scalef32_pk_f16_fp4 v79, v72, 1.0
	v_pk_fma_f16 v86, v19, v86, v92 op_sel:[1,0,0]
	v_pk_fma_f16 v79, v19, v79, v87 op_sel:[1,0,0]
	v_cvt_scalef32_pk_f16_fp4 v87, v72, 1.0 op_sel:[1,0,0]
	v_cvt_scalef32_pk_f16_fp4 v92, v72, 1.0 op_sel:[0,1,0]
	v_cvt_scalef32_pk_f16_fp4 v72, v72, 1.0 op_sel:[1,1,0]
	v_pk_fma_f16 v93, v19, v93, v102 op_sel_hi:[0,1,1]
	v_pk_fma_f16 v72, v19, v72, v80 op_sel:[1,0,0]
	v_cvt_scalef32_pk_f16_fp4 v80, v73, 1.0
	v_pk_fma_f16 v94, v19, v94, v103 op_sel_hi:[0,1,1]
	v_pk_fma_f16 v95, v19, v95, v105 op_sel_hi:[0,1,1]
	v_pk_fma_f16 v96, v19, v96, v104 op_sel_hi:[0,1,1]
	v_pk_fma_f16 v97, v19, v97, v110 op_sel_hi:[0,1,1]
	v_pk_fma_f16 v91, v19, v91, v93 op_sel:[1,0,0]
	v_pk_fma_f16 v80, v19, v80, v88 op_sel:[1,0,0]
	v_cvt_scalef32_pk_f16_fp4 v88, v73, 1.0 op_sel:[1,0,0]
	v_cvt_scalef32_pk_f16_fp4 v93, v73, 1.0 op_sel:[0,1,0]
	v_cvt_scalef32_pk_f16_fp4 v73, v73, 1.0 op_sel:[1,1,0]
	v_pk_fma_f16 v87, v19, v87, v94 op_sel:[1,0,0]
	v_pk_fma_f16 v92, v19, v92, v95 op_sel:[1,0,0]
	v_pk_fma_f16 v88, v19, v88, v96 op_sel:[1,0,0]
	v_pk_fma_f16 v93, v19, v93, v97 op_sel:[1,0,0]
	v_pk_fma_f16 v18, v19, v73, v18 op_sel:[1,0,0]
	s_waitcnt vmcnt(28)
	v_cvt_scalef32_pk_f16_fp4 v19, v58, 1.0
	v_pk_fma_f16 v19, v20, v19, v81 op_sel_hi:[0,1,1]
	v_cvt_scalef32_pk_f16_fp4 v73, v58, 1.0 op_sel:[1,0,0]
	v_cvt_scalef32_pk_f16_fp4 v81, v58, 1.0 op_sel:[0,1,0]
	v_cvt_scalef32_pk_f16_fp4 v58, v58, 1.0 op_sel:[1,1,0]
	v_pk_fma_f16 v58, v20, v58, v70 op_sel_hi:[0,1,1]
	v_cvt_scalef32_pk_f16_fp4 v70, v59, 1.0
	v_pk_fma_f16 v70, v20, v70, v78 op_sel_hi:[0,1,1]
	v_cvt_scalef32_pk_f16_fp4 v78, v59, 1.0 op_sel:[1,0,0]
	v_pk_fma_f16 v78, v20, v78, v86 op_sel_hi:[0,1,1]
	v_cvt_scalef32_pk_f16_fp4 v86, v59, 1.0 op_sel:[0,1,0]
	v_cvt_scalef32_pk_f16_fp4 v59, v59, 1.0 op_sel:[1,1,0]
	v_pk_fma_f16 v59, v20, v59, v71 op_sel_hi:[0,1,1]
	v_cvt_scalef32_pk_f16_fp4 v71, v60, 1.0
	v_pk_fma_f16 v71, v20, v71, v79 op_sel_hi:[0,1,1]
	v_cvt_scalef32_pk_f16_fp4 v79, v60, 1.0 op_sel:[1,0,0]
	v_pk_fma_f16 v79, v20, v79, v87 op_sel_hi:[0,1,1]
	v_cvt_scalef32_pk_f16_fp4 v87, v60, 1.0 op_sel:[0,1,0]
	v_cvt_scalef32_pk_f16_fp4 v60, v60, 1.0 op_sel:[1,1,0]
	v_pk_fma_f16 v60, v20, v60, v72 op_sel_hi:[0,1,1]
	v_cvt_scalef32_pk_f16_fp4 v72, v61, 1.0
	v_pk_fma_f16 v72, v20, v72, v80 op_sel_hi:[0,1,1]
	v_cvt_scalef32_pk_f16_fp4 v80, v61, 1.0 op_sel:[1,0,0]
	v_pk_fma_f16 v80, v20, v80, v88 op_sel_hi:[0,1,1]
	v_cvt_scalef32_pk_f16_fp4 v88, v61, 1.0 op_sel:[0,1,0]
	v_cvt_scalef32_pk_f16_fp4 v61, v61, 1.0 op_sel:[1,1,0]
	v_pk_fma_f16 v18, v20, v61, v18 op_sel_hi:[0,1,1]
	s_waitcnt vmcnt(27)
	v_cvt_scalef32_pk_f16_fp4 v61, v50, 1.0
	v_pk_fma_f16 v73, v20, v73, v89 op_sel_hi:[0,1,1]
	v_pk_fma_f16 v19, v20, v61, v19 op_sel:[1,0,0]
	v_cvt_scalef32_pk_f16_fp4 v61, v50, 1.0 op_sel:[1,0,0]
	v_pk_fma_f16 v61, v20, v61, v73 op_sel:[1,0,0]
	v_cvt_scalef32_pk_f16_fp4 v73, v50, 1.0 op_sel:[0,1,0]
	v_cvt_scalef32_pk_f16_fp4 v50, v50, 1.0 op_sel:[1,1,0]
	v_pk_fma_f16 v50, v20, v50, v58 op_sel:[1,0,0]
	v_cvt_scalef32_pk_f16_fp4 v58, v51, 1.0
	v_pk_fma_f16 v58, v20, v58, v70 op_sel:[1,0,0]
	v_cvt_scalef32_pk_f16_fp4 v70, v51, 1.0 op_sel:[1,0,0]
	v_pk_fma_f16 v70, v20, v70, v78 op_sel:[1,0,0]
	v_cvt_scalef32_pk_f16_fp4 v78, v51, 1.0 op_sel:[0,1,0]
	v_cvt_scalef32_pk_f16_fp4 v51, v51, 1.0 op_sel:[1,1,0]
	v_pk_fma_f16 v51, v20, v51, v59 op_sel:[1,0,0]
	v_cvt_scalef32_pk_f16_fp4 v59, v52, 1.0
	v_pk_fma_f16 v59, v20, v59, v71 op_sel:[1,0,0]
	v_cvt_scalef32_pk_f16_fp4 v71, v52, 1.0 op_sel:[1,0,0]
	v_pk_fma_f16 v71, v20, v71, v79 op_sel:[1,0,0]
	v_cvt_scalef32_pk_f16_fp4 v79, v52, 1.0 op_sel:[0,1,0]
	v_cvt_scalef32_pk_f16_fp4 v52, v52, 1.0 op_sel:[1,1,0]
	v_pk_fma_f16 v52, v20, v52, v60 op_sel:[1,0,0]
	v_cvt_scalef32_pk_f16_fp4 v60, v53, 1.0
	v_pk_fma_f16 v60, v20, v60, v72 op_sel:[1,0,0]
	v_cvt_scalef32_pk_f16_fp4 v72, v53, 1.0 op_sel:[1,0,0]
	v_pk_fma_f16 v81, v20, v81, v90 op_sel_hi:[0,1,1]
	v_pk_fma_f16 v86, v20, v86, v91 op_sel_hi:[0,1,1]
	v_pk_fma_f16 v87, v20, v87, v92 op_sel_hi:[0,1,1]
	v_pk_fma_f16 v88, v20, v88, v93 op_sel_hi:[0,1,1]
	v_pk_fma_f16 v72, v20, v72, v80 op_sel:[1,0,0]
	v_cvt_scalef32_pk_f16_fp4 v80, v53, 1.0 op_sel:[0,1,0]
	v_cvt_scalef32_pk_f16_fp4 v53, v53, 1.0 op_sel:[1,1,0]
	v_pk_fma_f16 v73, v20, v73, v81 op_sel:[1,0,0]
	v_pk_fma_f16 v78, v20, v78, v86 op_sel:[1,0,0]
	v_pk_fma_f16 v79, v20, v79, v87 op_sel:[1,0,0]
	v_pk_fma_f16 v80, v20, v80, v88 op_sel:[1,0,0]
	v_pk_fma_f16 v18, v20, v53, v18 op_sel:[1,0,0]
	s_waitcnt vmcnt(26)
	v_cvt_scalef32_pk_f16_fp4 v20, v38, 1.0
	v_pk_fma_f16 v19, v21, v20, v19 op_sel_hi:[0,1,1]
	v_cvt_scalef32_pk_f16_fp4 v20, v38, 1.0 op_sel:[1,0,0]
	v_cvt_scalef32_pk_f16_fp4 v53, v38, 1.0 op_sel:[0,1,0]
	v_cvt_scalef32_pk_f16_fp4 v38, v38, 1.0 op_sel:[1,1,0]
	v_pk_fma_f16 v38, v21, v38, v50 op_sel_hi:[0,1,1]
	v_cvt_scalef32_pk_f16_fp4 v50, v39, 1.0
	v_pk_fma_f16 v20, v21, v20, v61 op_sel_hi:[0,1,1]
	v_pk_fma_f16 v50, v21, v50, v58 op_sel_hi:[0,1,1]
	v_cvt_scalef32_pk_f16_fp4 v58, v39, 1.0 op_sel:[1,0,0]
	v_cvt_scalef32_pk_f16_fp4 v61, v39, 1.0 op_sel:[0,1,0]
	v_cvt_scalef32_pk_f16_fp4 v39, v39, 1.0 op_sel:[1,1,0]
	v_pk_fma_f16 v39, v21, v39, v51 op_sel_hi:[0,1,1]
	v_cvt_scalef32_pk_f16_fp4 v51, v40, 1.0
	v_pk_fma_f16 v58, v21, v58, v70 op_sel_hi:[0,1,1]
	v_pk_fma_f16 v51, v21, v51, v59 op_sel_hi:[0,1,1]
	v_cvt_scalef32_pk_f16_fp4 v59, v40, 1.0 op_sel:[1,0,0]
	v_cvt_scalef32_pk_f16_fp4 v70, v40, 1.0 op_sel:[0,1,0]
	v_cvt_scalef32_pk_f16_fp4 v40, v40, 1.0 op_sel:[1,1,0]
	v_pk_fma_f16 v40, v21, v40, v52 op_sel_hi:[0,1,1]
	v_cvt_scalef32_pk_f16_fp4 v52, v41, 1.0
	v_pk_fma_f16 v59, v21, v59, v71 op_sel_hi:[0,1,1]
	v_pk_fma_f16 v52, v21, v52, v60 op_sel_hi:[0,1,1]
	v_cvt_scalef32_pk_f16_fp4 v60, v41, 1.0 op_sel:[1,0,0]
	v_cvt_scalef32_pk_f16_fp4 v71, v41, 1.0 op_sel:[0,1,0]
	v_cvt_scalef32_pk_f16_fp4 v41, v41, 1.0 op_sel:[1,1,0]
	v_pk_fma_f16 v18, v21, v41, v18 op_sel_hi:[0,1,1]
	s_waitcnt vmcnt(25)
	v_cvt_scalef32_pk_f16_fp4 v41, v30, 1.0
	v_pk_fma_f16 v19, v21, v41, v19 op_sel:[1,0,0]
	v_cvt_scalef32_pk_f16_fp4 v41, v30, 1.0 op_sel:[1,0,0]
	v_pk_fma_f16 v20, v21, v41, v20 op_sel:[1,0,0]
	v_cvt_scalef32_pk_f16_fp4 v41, v30, 1.0 op_sel:[0,1,0]
	v_cvt_scalef32_pk_f16_fp4 v30, v30, 1.0 op_sel:[1,1,0]
	v_pk_fma_f16 v53, v21, v53, v73 op_sel_hi:[0,1,1]
	v_pk_fma_f16 v30, v21, v30, v38 op_sel:[1,0,0]
	v_cvt_scalef32_pk_f16_fp4 v38, v31, 1.0
	v_pk_fma_f16 v41, v21, v41, v53 op_sel:[1,0,0]
	v_pk_fma_f16 v38, v21, v38, v50 op_sel:[1,0,0]
	v_cvt_scalef32_pk_f16_fp4 v50, v31, 1.0 op_sel:[1,0,0]
	v_cvt_scalef32_pk_f16_fp4 v53, v31, 1.0 op_sel:[0,1,0]
	v_cvt_scalef32_pk_f16_fp4 v31, v31, 1.0 op_sel:[1,1,0]
	v_pk_fma_f16 v31, v21, v31, v39 op_sel:[1,0,0]
	v_cvt_scalef32_pk_f16_fp4 v39, v32, 1.0
	v_pk_fma_f16 v50, v21, v50, v58 op_sel:[1,0,0]
	v_pk_fma_f16 v39, v21, v39, v51 op_sel:[1,0,0]
	v_cvt_scalef32_pk_f16_fp4 v51, v32, 1.0 op_sel:[1,0,0]
	v_cvt_scalef32_pk_f16_fp4 v58, v32, 1.0 op_sel:[0,1,0]
	v_cvt_scalef32_pk_f16_fp4 v32, v32, 1.0 op_sel:[1,1,0]
	v_pk_fma_f16 v61, v21, v61, v78 op_sel_hi:[0,1,1]
	v_pk_fma_f16 v70, v21, v70, v79 op_sel_hi:[0,1,1]
	v_pk_fma_f16 v71, v21, v71, v80 op_sel_hi:[0,1,1]
	v_pk_fma_f16 v51, v21, v51, v59 op_sel:[1,0,0]
	v_pk_fma_f16 v32, v21, v32, v40 op_sel:[1,0,0]
	v_cvt_scalef32_pk_f16_fp4 v40, v33, 1.0
	v_cvt_scalef32_pk_f16_fp4 v59, v33, 1.0 op_sel:[0,1,0]
	v_pk_fma_f16 v53, v21, v53, v61 op_sel:[1,0,0]
	v_pk_fma_f16 v58, v21, v58, v70 op_sel:[1,0,0]
	v_pk_fma_f16 v40, v21, v40, v52 op_sel:[1,0,0]
	v_cvt_scalef32_pk_f16_fp4 v52, v33, 1.0 op_sel:[1,0,0]
	v_pk_fma_f16 v59, v21, v59, v71 op_sel:[1,0,0]
	v_cvt_scalef32_pk_f16_fp4 v33, v33, 1.0 op_sel:[1,1,0]
	v_pk_fma_f16 v60, v21, v60, v72 op_sel_hi:[0,1,1]
	v_pk_fma_f16 v18, v21, v33, v18 op_sel:[1,0,0]
	v_permlane32_swap_b32_e32 v19, v39
	v_permlane32_swap_b32_e32 v41, v58
	v_permlane32_swap_b32_e32 v30, v32
	v_permlane32_swap_b32_e32 v38, v40
	v_permlane32_swap_b32_e32 v53, v59
	v_pk_fma_f16 v52, v21, v52, v60 op_sel:[1,0,0]
	v_pk_add_f16 v19, v19, v39
	v_pk_add_f16 v21, v41, v58
	v_pk_add_f16 v30, v30, v32
	v_pk_add_f16 v32, v38, v40
	v_pk_add_f16 v38, v53, v59
	v_permlane32_swap_b32_e32 v31, v18
	v_permlane32_swap_b32_e32 v20, v51
	v_permlane32_swap_b32_e32 v50, v52
	v_pk_add_f16 v18, v31, v18
	v_permlane16_swap_b32_e32 v19, v32
	v_permlane16_swap_b32_e32 v21, v38
	v_pk_add_f16 v20, v20, v51
	v_pk_add_f16 v33, v50, v52
	v_pk_add_f16 v19, v19, v32
	v_pk_add_f16 v21, v21, v38
	v_permlane16_swap_b32_e32 v30, v18
	v_permlane16_swap_b32_e32 v20, v33
	v_pk_add_f16 v18, v30, v18
	v_cndmask_b32_e64 v30, v21, v19, s[10:11]
	v_cndmask_b32_e64 v19, v19, v21, s[10:11]
	v_pk_add_f16 v20, v20, v33
	v_cvt_f32_f16_e32 v32, v201
	v_mov_b32_dpp v19, v19 row_ror:8 row_mask:0xf bank_mask:0xf bound_ctrl:1
	v_pk_add_f16 v21, v30, v19
	v_cndmask_b32_e64 v30, v18, v20, s[10:11]
	v_cndmask_b32_e64 v18, v20, v18, s[10:11]
	v_cvt_f32_f16_sdwa v19, v200 dst_sel:DWORD dst_unused:UNUSED_PAD src0_sel:WORD_1
	v_cvt_f32_f16_e32 v20, v21
	v_mov_b32_dpp v31, v18 row_ror:8 row_mask:0xf bank_mask:0xf bound_ctrl:1
	v_cvt_f32_f16_e32 v18, v200
	v_cvt_f32_f16_sdwa v21, v21 dst_sel:DWORD dst_unused:UNUSED_PAD src0_sel:WORD_1
	v_pk_add_f16 v39, v30, v31
	v_cvt_f32_f16_e32 v30, v198
	v_cvt_f32_f16_sdwa v31, v198 dst_sel:DWORD dst_unused:UNUSED_PAD src0_sel:WORD_1
	v_cvt_f32_f16_sdwa v33, v201 dst_sel:DWORD dst_unused:UNUSED_PAD src0_sel:WORD_1
	v_cvt_f32_f16_e32 v38, v39
	v_cvt_f32_f16_sdwa v39, v39 dst_sel:DWORD dst_unused:UNUSED_PAD src0_sel:WORD_1
	v_pk_fma_f32 v[18:19], v[2:3], v[20:21], v[18:19]
	v_cvt_f32_f16_e32 v20, v199
	v_cvt_f32_f16_sdwa v21, v199 dst_sel:DWORD dst_unused:UNUSED_PAD src0_sel:WORD_1
	v_pk_add_f32 v[18:19], v[18:19], v[30:31]
	v_pk_fma_f32 v[30:31], v[4:5], v[38:39], v[32:33]
	v_cvt_pk_f16_f32 v18, v18, v19
	v_pk_add_f32 v[20:21], v[30:31], v[20:21]
	s_nop 0
	v_cvt_pk_f16_f32 v19, v20, v21
	global_store_dwordx2 v[196:197], v[18:19], off
	s_mov_b32 s30, s19
	s_cbranch_scc0 .LBB0_3109
	s_mov_b64 s[20:21], 0

.LBB0_4083:
	s_or_b64 exec, exec, s[0:1]
	s_mov_b64 s[0:1], 0
	s_mov_b64 s[2:3], 0
	s_waitcnt lgkmcnt(0)
	s_barrier
	s_mov_b64 s[2:3], 0
	s_mov_b64 s[12:13], 0
	s_mov_b64 s[6:7], 0
	s_mov_b64 s[2:3], 0
	s_add_u32 s0, s54, s0
	s_mov_b64 s[4:5], 0
	s_addc_u32 s1, s55, s1
	s_mov_b64 s[10:11], 0
	s_mov_b64 s[2:3], 0
	s_mov_b64 s[8:9], 0
	v_mov_b32_e32 v2, v0
	s_add_u32 s0, s0, 0x7800
	s_getreg_b32 s22, hwreg(HW_REG_XCC_ID, 0, 4)
	v_and_b32_e32 v3, 63, v2
	s_addc_u32 s1, s1, 0
	s_and_b32 s20, s22, 7
	v_mov_b32_e32 v202, 0
	v_cmp_eq_u32_e64 s[2:3], 0, v3
	s_and_saveexec_b64 s[14:15], s[2:3]
	s_cbranch_execz .LBB0_4087
	s_mov_b64 s[18:19], exec
	v_mbcnt_lo_u32_b32 v4, s18, 0
	v_mbcnt_hi_u32_b32 v4, s19, v4
	v_cmp_eq_u32_e32 vcc, 0, v4
	s_and_saveexec_b64 s[16:17], vcc
	s_cbranch_execz .LBB0_4086
	s_bcnt1_i32_b64 s18, s[18:19]
	s_lshl_b32 s21, s20, 8
	s_lshl_b32 s18, s18, 5
	v_mov_b32_e32 v5, s21
	v_mov_b32_e32 v6, s18
	global_atomic_add v5, v5, v6, s[0:1] sc0
.LBB0_4086:
	s_or_b64 exec, exec, s[16:17]
	s_waitcnt vmcnt(0)
	v_readfirstlane_b32 s16, v5
	s_nop 1
	v_lshl_add_u32 v202, v4, 5, s16
.LBB0_4087:
	s_or_b64 exec, exec, s[14:15]
	s_add_u32 s12, s54, s12
	s_addc_u32 s13, s55, s13
	s_add_u32 s14, s54, s6
	s_addc_u32 s15, s55, s7
	s_add_u32 s6, s54, s10
	s_addc_u32 s7, s55, s11
	s_add_u32 s6, s6, 0x3fd06000
	s_addc_u32 s7, s7, 0
	s_add_u32 s8, s54, s8
	s_addc_u32 s9, s55, s9
	s_add_u32 s8, s8, 0x4c618000
	s_addc_u32 s9, s9, 0
	s_add_u32 s4, s54, s4
	s_addc_u32 s5, s55, s5
	v_lshlrev_b32_e32 v203, 2, v3
	v_lshlrev_b32_e32 v4, 4, v3
	v_lshlrev_b32_e32 v3, 3, v3
	s_add_u32 s10, s4, 0x50e18000
	v_and_b32_e32 v182, 0x1c0, v3
	v_mov_b32_e32 v183, 0
	v_and_b32_e32 v3, 56, v2
	s_addc_u32 s11, s5, 0
	v_and_b32_e32 v204, 0x70, v4
	v_lshl_add_u64 v[4:5], s[12:13], 0, v[182:183]
	s_mov_b64 s[4:5], 0x2ade6000
	v_lshlrev_b32_e32 v182, 2, v3
	v_lshl_add_u64 v[184:185], v[4:5], 0, s[4:5]
	v_lshl_add_u64 v[4:5], s[14:15], 0, v[182:183]
	s_mov_b64 s[4:5], 0x4c198000
	v_and_b32_e32 v2, 8, v2
	v_lshl_add_u64 v[186:187], v[4:5], 0, s[4:5]
	s_mov_b32 s24, 0
	v_cmp_eq_u32_e64 s[4:5], 0, v2
	v_mov_b32_e32 v206, s20
	v_mov_b32_e32 v205, 32
	s_mov_b32 s23, 0xa000
	s_branch .LBB0_4090

.LBB0_4094:
	s_add_i32 s18, s12, s25
	s_add_i32 s13, s18, 2
	s_add_i32 s20, s18, 1
	s_add_i32 s15, s18, 3
	s_cmp_lt_u32 s25, 30
	s_cselect_b32 s14, s13, s18
	s_cselect_b32 s16, s15, s20
	s_ashr_i32 s15, s14, 31
	s_ashr_i32 s21, s20, 31
	s_ashr_i32 s19, s18, 31
	s_lshl_b64 s[26:27], s[14:15], 9
	s_lshl_b64 s[28:29], s[20:21], 8
	s_lshl_b64 s[14:15], s[18:19], 12
	s_add_i32 s13, s25, 1
	s_cmp_lt_u32 s13, 31
	s_cselect_b64 s[30:31], -1, 0
	s_ashr_i32 s17, s16, 31
	s_lshl_b64 s[16:17], s[16:17], 9
	s_cmp_lg_u64 s[30:31], 0
	s_addc_u32 s18, s18, 1
	s_lshl_b64 s[20:21], s[20:21], 12
	v_lshl_add_u64 v[22:23], v[184:185], 0, s[26:27]
	v_lshl_add_u64 v[30:31], v[186:187], 0, s[28:29]
	global_load_dwordx4 v[166:169], v[22:23], off offset:48
	global_load_dwordx4 v[170:173], v[22:23], off offset:32
	global_load_dwordx4 v[174:177], v[22:23], off offset:16
	global_load_dwordx4 v[178:181], v[22:23], off
	s_nop 0
	global_load_dwordx4 v[22:25], v[30:31], off offset:16
	global_load_dwordx4 v[94:97], v[30:31], off
	v_lshl_add_u64 v[196:197], v[190:191], 0, s[20:21]
	v_lshl_add_u64 v[30:31], v[192:193], 0, s[20:21]
	global_load_dwordx2 v[198:199], v[196:197], off
	global_load_dwordx2 v[200:201], v[30:31], off
	s_waitcnt vmcnt(29)
	v_lshl_add_u32 v30, v134, 7, v207
	v_lshl_add_u32 v31, v135, 7, v207
	global_load_dwordx4 v[162:165], v30, s[6:7]
	global_load_dwordx4 v[158:161], v31, s[6:7]
	v_lshl_add_u32 v30, v136, 7, v207
	v_lshl_add_u32 v31, v137, 7, v207
	global_load_dwordx4 v[154:157], v30, s[6:7]
	global_load_dwordx4 v[150:153], v31, s[6:7]
	v_lshl_add_u32 v30, v126, 7, v207
	v_lshl_add_u32 v31, v127, 7, v207
	global_load_dwordx4 v[146:149], v30, s[6:7]
	global_load_dwordx4 v[138:141], v31, s[6:7]
	v_lshl_add_u32 v30, v128, 7, v207
	v_lshl_add_u32 v31, v129, 7, v207
	global_load_dwordx4 v[122:125], v30, s[6:7]
	global_load_dwordx4 v[106:109], v31, s[6:7]
	v_lshl_add_u32 v30, v118, 7, v207
	v_lshl_add_u32 v31, v119, 7, v207
	global_load_dwordx4 v[98:101], v30, s[6:7]
	global_load_dwordx4 v[86:89], v31, s[6:7]
	v_lshl_add_u32 v30, v120, 7, v207
	v_lshl_add_u32 v31, v121, 7, v207
	global_load_dwordx4 v[78:81], v30, s[6:7]
	global_load_dwordx4 v[70:73], v31, s[6:7]
	s_waitcnt vmcnt(40)
	v_lshl_add_u32 v30, v114, 7, v207
	v_lshl_add_u32 v31, v115, 7, v207
	global_load_dwordx4 v[58:61], v30, s[6:7]
	global_load_dwordx4 v[50:53], v31, s[6:7]
	v_lshl_add_u32 v30, v116, 7, v207
	v_lshl_add_u32 v31, v117, 7, v207
	global_load_dwordx4 v[42:45], v30, s[6:7]
	s_nop 0
	global_load_dwordx4 v[30:33], v31, s[6:7]
	s_ashr_i32 s19, s18, 31
	s_lshl_b64 s[20:21], s[18:19], 8
	s_lshl_b64 s[18:19], s[18:19], 12
	s_add_i32 s13, s25, 2
	s_cmp_gt_u32 s25, 29
	s_waitcnt vmcnt(36)
	v_cvt_scalef32_pk_f16_fp4 v114, v142, 1.0
	v_pk_fma_f16 v114, v38, v114, 0 op_sel_hi:[0,1,1]
	v_cvt_scalef32_pk_f16_fp4 v115, v142, 1.0 op_sel:[1,0,0]
	v_cvt_scalef32_pk_f16_fp4 v116, v142, 1.0 op_sel:[0,1,0]
	v_cvt_scalef32_pk_f16_fp4 v117, v142, 1.0 op_sel:[1,1,0]
	s_waitcnt vmcnt(35)
	v_cvt_scalef32_pk_f16_fp4 v142, v130, 1.0
	v_pk_fma_f16 v115, v38, v115, 0 op_sel_hi:[0,1,1]
	v_pk_fma_f16 v114, v38, v142, v114 op_sel:[1,0,0]
	v_cvt_scalef32_pk_f16_fp4 v142, v130, 1.0 op_sel:[1,0,0]
	v_pk_fma_f16 v117, v38, v117, 0 op_sel_hi:[0,1,1]
	v_cvt_scalef32_pk_f16_fp4 v118, v143, 1.0
	v_pk_fma_f16 v115, v38, v142, v115 op_sel:[1,0,0]
	v_cvt_scalef32_pk_f16_fp4 v142, v130, 1.0 op_sel:[0,1,0]
	v_cvt_scalef32_pk_f16_fp4 v130, v130, 1.0 op_sel:[1,1,0]
	v_pk_fma_f16 v118, v38, v118, 0 op_sel_hi:[0,1,1]
	v_cvt_scalef32_pk_f16_fp4 v119, v143, 1.0 op_sel:[1,0,0]
	v_pk_fma_f16 v117, v38, v130, v117 op_sel:[1,0,0]
	v_cvt_scalef32_pk_f16_fp4 v130, v131, 1.0
	v_pk_fma_f16 v119, v38, v119, 0 op_sel_hi:[0,1,1]
	v_cvt_scalef32_pk_f16_fp4 v120, v143, 1.0 op_sel:[0,1,0]
	v_pk_fma_f16 v118, v38, v130, v118 op_sel:[1,0,0]
	v_cvt_scalef32_pk_f16_fp4 v130, v131, 1.0 op_sel:[1,0,0]
	v_pk_fma_f16 v120, v38, v120, 0 op_sel_hi:[0,1,1]
	v_cvt_scalef32_pk_f16_fp4 v121, v143, 1.0 op_sel:[1,1,0]
	v_pk_fma_f16 v119, v38, v130, v119 op_sel:[1,0,0]
	v_cvt_scalef32_pk_f16_fp4 v130, v131, 1.0 op_sel:[0,1,0]
	v_pk_fma_f16 v121, v38, v121, 0 op_sel_hi:[0,1,1]
	v_cvt_scalef32_pk_f16_fp4 v126, v144, 1.0
	v_pk_fma_f16 v120, v38, v130, v120 op_sel:[1,0,0]
	v_cvt_scalef32_pk_f16_fp4 v130, v131, 1.0 op_sel:[1,1,0]
	v_pk_fma_f16 v126, v38, v126, 0 op_sel_hi:[0,1,1]
	v_cvt_scalef32_pk_f16_fp4 v127, v144, 1.0 op_sel:[1,0,0]
	v_pk_fma_f16 v121, v38, v130, v121 op_sel:[1,0,0]
	v_cvt_scalef32_pk_f16_fp4 v130, v132, 1.0
	v_pk_fma_f16 v127, v38, v127, 0 op_sel_hi:[0,1,1]
	v_cvt_scalef32_pk_f16_fp4 v128, v144, 1.0 op_sel:[0,1,0]
	v_pk_fma_f16 v126, v38, v130, v126 op_sel:[1,0,0]
	v_cvt_scalef32_pk_f16_fp4 v130, v132, 1.0 op_sel:[1,0,0]
	v_pk_fma_f16 v128, v38, v128, 0 op_sel_hi:[0,1,1]
	v_cvt_scalef32_pk_f16_fp4 v129, v144, 1.0 op_sel:[1,1,0]
	v_pk_fma_f16 v127, v38, v130, v127 op_sel:[1,0,0]
	v_cvt_scalef32_pk_f16_fp4 v130, v132, 1.0 op_sel:[0,1,0]
	v_pk_fma_f16 v129, v38, v129, 0 op_sel_hi:[0,1,1]
	v_cvt_scalef32_pk_f16_fp4 v134, v145, 1.0
	v_cvt_scalef32_pk_f16_fp4 v135, v145, 1.0 op_sel:[1,0,0]
	v_cvt_scalef32_pk_f16_fp4 v136, v145, 1.0 op_sel:[0,1,0]
	v_cvt_scalef32_pk_f16_fp4 v137, v145, 1.0 op_sel:[1,1,0]
	v_pk_fma_f16 v128, v38, v130, v128 op_sel:[1,0,0]
	v_cvt_scalef32_pk_f16_fp4 v130, v132, 1.0 op_sel:[1,1,0]
	v_pk_fma_f16 v116, v38, v116, 0 op_sel_hi:[0,1,1]
	v_pk_fma_f16 v134, v38, v134, 0 op_sel_hi:[0,1,1]
	v_pk_fma_f16 v135, v38, v135, 0 op_sel_hi:[0,1,1]
	v_pk_fma_f16 v136, v38, v136, 0 op_sel_hi:[0,1,1]
	v_pk_fma_f16 v137, v38, v137, 0 op_sel_hi:[0,1,1]
	v_pk_fma_f16 v129, v38, v130, v129 op_sel:[1,0,0]
	v_cvt_scalef32_pk_f16_fp4 v130, v133, 1.0
	v_cvt_scalef32_pk_f16_fp4 v131, v133, 1.0 op_sel:[1,0,0]
	v_cvt_scalef32_pk_f16_fp4 v132, v133, 1.0 op_sel:[0,1,0]
	v_cvt_scalef32_pk_f16_fp4 v133, v133, 1.0 op_sel:[1,1,0]
	v_pk_fma_f16 v116, v38, v142, v116 op_sel:[1,0,0]
	v_pk_fma_f16 v130, v38, v130, v134 op_sel:[1,0,0]
	v_pk_fma_f16 v131, v38, v131, v135 op_sel:[1,0,0]
	v_pk_fma_f16 v132, v38, v132, v136 op_sel:[1,0,0]
	v_pk_fma_f16 v38, v38, v133, v137 op_sel:[1,0,0]
	s_waitcnt vmcnt(34)
	v_cvt_scalef32_pk_f16_fp4 v133, v110, 1.0
	v_pk_fma_f16 v114, v39, v133, v114 op_sel_hi:[0,1,1]
	v_cvt_scalef32_pk_f16_fp4 v133, v110, 1.0 op_sel:[1,0,0]
	v_pk_fma_f16 v115, v39, v133, v115 op_sel_hi:[0,1,1]
	v_cvt_scalef32_pk_f16_fp4 v133, v110, 1.0 op_sel:[0,1,0]
	v_cvt_scalef32_pk_f16_fp4 v110, v110, 1.0 op_sel:[1,1,0]
	v_pk_fma_f16 v110, v39, v110, v117 op_sel_hi:[0,1,1]
	v_cvt_scalef32_pk_f16_fp4 v117, v111, 1.0
	v_pk_fma_f16 v117, v39, v117, v118 op_sel_hi:[0,1,1]
	v_cvt_scalef32_pk_f16_fp4 v118, v111, 1.0 op_sel:[1,0,0]
	v_pk_fma_f16 v118, v39, v118, v119 op_sel_hi:[0,1,1]
	v_cvt_scalef32_pk_f16_fp4 v119, v111, 1.0 op_sel:[0,1,0]
	v_pk_fma_f16 v119, v39, v119, v120 op_sel_hi:[0,1,1]
	v_cvt_scalef32_pk_f16_fp4 v111, v111, 1.0 op_sel:[1,1,0]
	v_cvt_scalef32_pk_f16_fp4 v120, v112, 1.0
	v_pk_fma_f16 v111, v39, v111, v121 op_sel_hi:[0,1,1]
	v_pk_fma_f16 v120, v39, v120, v126 op_sel_hi:[0,1,1]
	v_cvt_scalef32_pk_f16_fp4 v121, v112, 1.0 op_sel:[1,0,0]
	v_cvt_scalef32_pk_f16_fp4 v126, v112, 1.0 op_sel:[0,1,0]
	v_cvt_scalef32_pk_f16_fp4 v112, v112, 1.0 op_sel:[1,1,0]
	v_pk_fma_f16 v121, v39, v121, v127 op_sel_hi:[0,1,1]
	v_pk_fma_f16 v126, v39, v126, v128 op_sel_hi:[0,1,1]
	v_pk_fma_f16 v112, v39, v112, v129 op_sel_hi:[0,1,1]
	v_cvt_scalef32_pk_f16_fp4 v127, v113, 1.0
	v_cvt_scalef32_pk_f16_fp4 v128, v113, 1.0 op_sel:[1,0,0]
	v_cvt_scalef32_pk_f16_fp4 v129, v113, 1.0 op_sel:[0,1,0]
	v_cvt_scalef32_pk_f16_fp4 v113, v113, 1.0 op_sel:[1,1,0]
	v_pk_fma_f16 v38, v39, v113, v38 op_sel_hi:[0,1,1]
	s_waitcnt vmcnt(33)
	v_cvt_scalef32_pk_f16_fp4 v113, v102, 1.0
	v_pk_fma_f16 v113, v39, v113, v114 op_sel:[1,0,0]
	v_cvt_scalef32_pk_f16_fp4 v114, v102, 1.0 op_sel:[1,0,0]
	v_pk_fma_f16 v114, v39, v114, v115 op_sel:[1,0,0]
	v_cvt_scalef32_pk_f16_fp4 v115, v102, 1.0 op_sel:[0,1,0]
	v_cvt_scalef32_pk_f16_fp4 v102, v102, 1.0 op_sel:[1,1,0]
	v_pk_fma_f16 v116, v39, v133, v116 op_sel_hi:[0,1,1]
	v_pk_fma_f16 v102, v39, v102, v110 op_sel:[1,0,0]
	v_cvt_scalef32_pk_f16_fp4 v110, v103, 1.0
	v_pk_fma_f16 v115, v39, v115, v116 op_sel:[1,0,0]
	v_pk_fma_f16 v110, v39, v110, v117 op_sel:[1,0,0]
	v_cvt_scalef32_pk_f16_fp4 v116, v103, 1.0 op_sel:[1,0,0]
	v_cvt_scalef32_pk_f16_fp4 v117, v103, 1.0 op_sel:[0,1,0]
	v_cvt_scalef32_pk_f16_fp4 v103, v103, 1.0 op_sel:[1,1,0]
	v_pk_fma_f16 v116, v39, v116, v118 op_sel:[1,0,0]
	v_pk_fma_f16 v117, v39, v117, v119 op_sel:[1,0,0]
	v_pk_fma_f16 v103, v39, v103, v111 op_sel:[1,0,0]
	v_cvt_scalef32_pk_f16_fp4 v111, v104, 1.0
	v_cvt_scalef32_pk_f16_fp4 v118, v104, 1.0 op_sel:[1,0,0]
	v_cvt_scalef32_pk_f16_fp4 v119, v104, 1.0 op_sel:[0,1,0]
	v_cvt_scalef32_pk_f16_fp4 v104, v104, 1.0 op_sel:[1,1,0]
	v_pk_fma_f16 v127, v39, v127, v130 op_sel_hi:[0,1,1]
	v_pk_fma_f16 v128, v39, v128, v131 op_sel_hi:[0,1,1]
	v_pk_fma_f16 v129, v39, v129, v132 op_sel_hi:[0,1,1]
	v_pk_fma_f16 v111, v39, v111, v120 op_sel:[1,0,0]
	v_pk_fma_f16 v118, v39, v118, v121 op_sel:[1,0,0]
	v_pk_fma_f16 v104, v39, v104, v112 op_sel:[1,0,0]
	v_cvt_scalef32_pk_f16_fp4 v112, v105, 1.0
	v_cvt_scalef32_pk_f16_fp4 v120, v105, 1.0 op_sel:[1,0,0]
	v_cvt_scalef32_pk_f16_fp4 v121, v105, 1.0 op_sel:[0,1,0]
	v_cvt_scalef32_pk_f16_fp4 v105, v105, 1.0 op_sel:[1,1,0]
	v_pk_fma_f16 v119, v39, v119, v126 op_sel:[1,0,0]
	v_pk_fma_f16 v112, v39, v112, v127 op_sel:[1,0,0]
	v_pk_fma_f16 v120, v39, v120, v128 op_sel:[1,0,0]
	v_pk_fma_f16 v121, v39, v121, v129 op_sel:[1,0,0]
	v_pk_fma_f16 v38, v39, v105, v38 op_sel:[1,0,0]
	s_waitcnt vmcnt(32)
	v_cvt_scalef32_pk_f16_fp4 v39, v90, 1.0
	v_pk_fma_f16 v39, v40, v39, v113 op_sel_hi:[0,1,1]
	v_cvt_scalef32_pk_f16_fp4 v105, v90, 1.0 op_sel:[1,0,0]
	v_cvt_scalef32_pk_f16_fp4 v113, v90, 1.0 op_sel:[0,1,0]
	v_cvt_scalef32_pk_f16_fp4 v90, v90, 1.0 op_sel:[1,1,0]
	v_pk_fma_f16 v90, v40, v90, v102 op_sel_hi:[0,1,1]
	v_cvt_scalef32_pk_f16_fp4 v102, v91, 1.0
	v_pk_fma_f16 v105, v40, v105, v114 op_sel_hi:[0,1,1]
	v_pk_fma_f16 v102, v40, v102, v110 op_sel_hi:[0,1,1]
	v_cvt_scalef32_pk_f16_fp4 v110, v91, 1.0 op_sel:[1,0,0]
	v_cvt_scalef32_pk_f16_fp4 v114, v91, 1.0 op_sel:[0,1,0]
	v_cvt_scalef32_pk_f16_fp4 v91, v91, 1.0 op_sel:[1,1,0]
	v_pk_fma_f16 v91, v40, v91, v103 op_sel_hi:[0,1,1]
	v_cvt_scalef32_pk_f16_fp4 v103, v92, 1.0
	v_pk_fma_f16 v113, v40, v113, v115 op_sel_hi:[0,1,1]
	v_pk_fma_f16 v103, v40, v103, v111 op_sel_hi:[0,1,1]
	v_cvt_scalef32_pk_f16_fp4 v111, v92, 1.0 op_sel:[1,0,0]
	v_cvt_scalef32_pk_f16_fp4 v115, v92, 1.0 op_sel:[0,1,0]
	v_cvt_scalef32_pk_f16_fp4 v92, v92, 1.0 op_sel:[1,1,0]
	v_pk_fma_f16 v92, v40, v92, v104 op_sel_hi:[0,1,1]
	v_cvt_scalef32_pk_f16_fp4 v104, v93, 1.0
	v_pk_fma_f16 v110, v40, v110, v116 op_sel_hi:[0,1,1]
	v_pk_fma_f16 v104, v40, v104, v112 op_sel_hi:[0,1,1]
	v_cvt_scalef32_pk_f16_fp4 v112, v93, 1.0 op_sel:[1,0,0]
	v_cvt_scalef32_pk_f16_fp4 v116, v93, 1.0 op_sel:[0,1,0]
	v_cvt_scalef32_pk_f16_fp4 v93, v93, 1.0 op_sel:[1,1,0]
	v_pk_fma_f16 v38, v40, v93, v38 op_sel_hi:[0,1,1]
	v_cvt_scalef32_pk_f16_fp4 v93, v82, 1.0
	v_pk_fma_f16 v39, v40, v93, v39 op_sel:[1,0,0]
	v_cvt_scalef32_pk_f16_fp4 v93, v82, 1.0 op_sel:[1,0,0]
	v_pk_fma_f16 v93, v40, v93, v105 op_sel:[1,0,0]
	v_cvt_scalef32_pk_f16_fp4 v105, v82, 1.0 op_sel:[0,1,0]
	v_cvt_scalef32_pk_f16_fp4 v82, v82, 1.0 op_sel:[1,1,0]
	v_pk_fma_f16 v82, v40, v82, v90 op_sel:[1,0,0]
	v_cvt_scalef32_pk_f16_fp4 v90, v83, 1.0
	v_pk_fma_f16 v90, v40, v90, v102 op_sel:[1,0,0]
	v_cvt_scalef32_pk_f16_fp4 v102, v83, 1.0 op_sel:[1,0,0]
	v_pk_fma_f16 v102, v40, v102, v110 op_sel:[1,0,0]
	v_cvt_scalef32_pk_f16_fp4 v110, v83, 1.0 op_sel:[0,1,0]
	v_cvt_scalef32_pk_f16_fp4 v83, v83, 1.0 op_sel:[1,1,0]
	v_pk_fma_f16 v83, v40, v83, v91 op_sel:[1,0,0]
	v_cvt_scalef32_pk_f16_fp4 v91, v84, 1.0
	v_pk_fma_f16 v111, v40, v111, v118 op_sel_hi:[0,1,1]
	v_pk_fma_f16 v91, v40, v91, v103 op_sel:[1,0,0]
	v_cvt_scalef32_pk_f16_fp4 v103, v84, 1.0 op_sel:[1,0,0]
	v_pk_fma_f16 v103, v40, v103, v111 op_sel:[1,0,0]
	v_cvt_scalef32_pk_f16_fp4 v111, v84, 1.0 op_sel:[0,1,0]
	v_cvt_scalef32_pk_f16_fp4 v84, v84, 1.0 op_sel:[1,1,0]
	v_pk_fma_f16 v84, v40, v84, v92 op_sel:[1,0,0]
	v_cvt_scalef32_pk_f16_fp4 v92, v85, 1.0
	v_pk_fma_f16 v112, v40, v112, v120 op_sel_hi:[0,1,1]
	v_pk_fma_f16 v92, v40, v92, v104 op_sel:[1,0,0]
	v_cvt_scalef32_pk_f16_fp4 v104, v85, 1.0 op_sel:[1,0,0]
	v_pk_fma_f16 v114, v40, v114, v117 op_sel_hi:[0,1,1]
	v_pk_fma_f16 v115, v40, v115, v119 op_sel_hi:[0,1,1]
	v_pk_fma_f16 v116, v40, v116, v121 op_sel_hi:[0,1,1]
	v_pk_fma_f16 v104, v40, v104, v112 op_sel:[1,0,0]
	v_cvt_scalef32_pk_f16_fp4 v112, v85, 1.0 op_sel:[0,1,0]
	v_cvt_scalef32_pk_f16_fp4 v85, v85, 1.0 op_sel:[1,1,0]
	v_pk_fma_f16 v105, v40, v105, v113 op_sel:[1,0,0]
	v_pk_fma_f16 v110, v40, v110, v114 op_sel:[1,0,0]
	v_pk_fma_f16 v111, v40, v111, v115 op_sel:[1,0,0]
	v_pk_fma_f16 v112, v40, v112, v116 op_sel:[1,0,0]
	v_pk_fma_f16 v38, v40, v85, v38 op_sel:[1,0,0]
	v_cvt_scalef32_pk_f16_fp4 v40, v74, 1.0
	v_pk_fma_f16 v39, v41, v40, v39 op_sel_hi:[0,1,1]
	v_cvt_scalef32_pk_f16_fp4 v40, v74, 1.0 op_sel:[1,0,0]
	v_cvt_scalef32_pk_f16_fp4 v85, v74, 1.0 op_sel:[0,1,0]
	v_cvt_scalef32_pk_f16_fp4 v74, v74, 1.0 op_sel:[1,1,0]
	v_pk_fma_f16 v74, v41, v74, v82 op_sel_hi:[0,1,1]
	v_cvt_scalef32_pk_f16_fp4 v82, v75, 1.0
	v_pk_fma_f16 v40, v41, v40, v93 op_sel_hi:[0,1,1]
	v_pk_fma_f16 v82, v41, v82, v90 op_sel_hi:[0,1,1]
	v_cvt_scalef32_pk_f16_fp4 v90, v75, 1.0 op_sel:[1,0,0]
	v_cvt_scalef32_pk_f16_fp4 v93, v75, 1.0 op_sel:[0,1,0]
	v_cvt_scalef32_pk_f16_fp4 v75, v75, 1.0 op_sel:[1,1,0]
	v_pk_fma_f16 v75, v41, v75, v83 op_sel_hi:[0,1,1]
	v_cvt_scalef32_pk_f16_fp4 v83, v76, 1.0
	v_pk_fma_f16 v90, v41, v90, v102 op_sel_hi:[0,1,1]
	v_pk_fma_f16 v83, v41, v83, v91 op_sel_hi:[0,1,1]
	v_cvt_scalef32_pk_f16_fp4 v91, v76, 1.0 op_sel:[1,0,0]
	v_cvt_scalef32_pk_f16_fp4 v102, v76, 1.0 op_sel:[0,1,0]
	v_cvt_scalef32_pk_f16_fp4 v76, v76, 1.0 op_sel:[1,1,0]
	v_pk_fma_f16 v76, v41, v76, v84 op_sel_hi:[0,1,1]
	v_cvt_scalef32_pk_f16_fp4 v84, v77, 1.0
	v_pk_fma_f16 v91, v41, v91, v103 op_sel_hi:[0,1,1]
	v_pk_fma_f16 v84, v41, v84, v92 op_sel_hi:[0,1,1]
	v_cvt_scalef32_pk_f16_fp4 v92, v77, 1.0 op_sel:[1,0,0]
	v_cvt_scalef32_pk_f16_fp4 v103, v77, 1.0 op_sel:[0,1,0]
	v_cvt_scalef32_pk_f16_fp4 v77, v77, 1.0 op_sel:[1,1,0]
	v_pk_fma_f16 v38, v41, v77, v38 op_sel_hi:[0,1,1]
	v_cvt_scalef32_pk_f16_fp4 v77, v66, 1.0
	v_pk_fma_f16 v39, v41, v77, v39 op_sel:[1,0,0]
	v_cvt_scalef32_pk_f16_fp4 v77, v66, 1.0 op_sel:[1,0,0]
	v_pk_fma_f16 v40, v41, v77, v40 op_sel:[1,0,0]
	v_cvt_scalef32_pk_f16_fp4 v77, v66, 1.0 op_sel:[0,1,0]
	v_cvt_scalef32_pk_f16_fp4 v66, v66, 1.0 op_sel:[1,1,0]
	v_pk_fma_f16 v85, v41, v85, v105 op_sel_hi:[0,1,1]
	v_pk_fma_f16 v66, v41, v66, v74 op_sel:[1,0,0]
	v_cvt_scalef32_pk_f16_fp4 v74, v67, 1.0
	v_pk_fma_f16 v77, v41, v77, v85 op_sel:[1,0,0]
	v_pk_fma_f16 v74, v41, v74, v82 op_sel:[1,0,0]
	v_cvt_scalef32_pk_f16_fp4 v82, v67, 1.0 op_sel:[1,0,0]
	v_cvt_scalef32_pk_f16_fp4 v85, v67, 1.0 op_sel:[0,1,0]
	v_cvt_scalef32_pk_f16_fp4 v67, v67, 1.0 op_sel:[1,1,0]
	v_pk_fma_f16 v67, v41, v67, v75 op_sel:[1,0,0]
	v_cvt_scalef32_pk_f16_fp4 v75, v68, 1.0
	v_pk_fma_f16 v82, v41, v82, v90 op_sel:[1,0,0]
	v_pk_fma_f16 v75, v41, v75, v83 op_sel:[1,0,0]
	v_cvt_scalef32_pk_f16_fp4 v83, v68, 1.0 op_sel:[1,0,0]
	v_cvt_scalef32_pk_f16_fp4 v90, v68, 1.0 op_sel:[0,1,0]
	v_cvt_scalef32_pk_f16_fp4 v68, v68, 1.0 op_sel:[1,1,0]
	v_pk_fma_f16 v68, v41, v68, v76 op_sel:[1,0,0]
	v_cvt_scalef32_pk_f16_fp4 v76, v69, 1.0
	v_pk_fma_f16 v93, v41, v93, v110 op_sel_hi:[0,1,1]
	v_pk_fma_f16 v102, v41, v102, v111 op_sel_hi:[0,1,1]
	v_pk_fma_f16 v92, v41, v92, v104 op_sel_hi:[0,1,1]
	v_pk_fma_f16 v103, v41, v103, v112 op_sel_hi:[0,1,1]
	v_pk_fma_f16 v83, v41, v83, v91 op_sel:[1,0,0]
	v_pk_fma_f16 v76, v41, v76, v84 op_sel:[1,0,0]
	v_cvt_scalef32_pk_f16_fp4 v84, v69, 1.0 op_sel:[1,0,0]
	v_cvt_scalef32_pk_f16_fp4 v91, v69, 1.0 op_sel:[0,1,0]
	v_cvt_scalef32_pk_f16_fp4 v69, v69, 1.0 op_sel:[1,1,0]
	v_pk_fma_f16 v85, v41, v85, v93 op_sel:[1,0,0]
	v_pk_fma_f16 v90, v41, v90, v102 op_sel:[1,0,0]
	v_pk_fma_f16 v84, v41, v84, v92 op_sel:[1,0,0]
	v_pk_fma_f16 v91, v41, v91, v103 op_sel:[1,0,0]
	v_pk_fma_f16 v38, v41, v69, v38 op_sel:[1,0,0]
	s_waitcnt vmcnt(31)
	v_cvt_scalef32_pk_f16_fp4 v41, v62, 1.0
	v_pk_fma_f16 v39, v6, v41, v39 op_sel_hi:[0,1,1]
	v_cvt_scalef32_pk_f16_fp4 v41, v62, 1.0 op_sel:[1,0,0]
	v_pk_fma_f16 v40, v6, v41, v40 op_sel_hi:[0,1,1]
	v_cvt_scalef32_pk_f16_fp4 v41, v62, 1.0 op_sel:[0,1,0]
	v_cvt_scalef32_pk_f16_fp4 v62, v62, 1.0 op_sel:[1,1,0]
	v_pk_fma_f16 v62, v6, v62, v66 op_sel_hi:[0,1,1]
	v_cvt_scalef32_pk_f16_fp4 v66, v63, 1.0
	v_pk_fma_f16 v66, v6, v66, v74 op_sel_hi:[0,1,1]
	v_cvt_scalef32_pk_f16_fp4 v69, v63, 1.0 op_sel:[1,0,0]
	v_cvt_scalef32_pk_f16_fp4 v74, v63, 1.0 op_sel:[0,1,0]
	v_cvt_scalef32_pk_f16_fp4 v63, v63, 1.0 op_sel:[1,1,0]
	v_pk_fma_f16 v63, v6, v63, v67 op_sel_hi:[0,1,1]
	v_cvt_scalef32_pk_f16_fp4 v67, v64, 1.0
	v_pk_fma_f16 v41, v6, v41, v77 op_sel_hi:[0,1,1]
	v_pk_fma_f16 v67, v6, v67, v75 op_sel_hi:[0,1,1]
	v_cvt_scalef32_pk_f16_fp4 v75, v64, 1.0 op_sel:[1,0,0]
	v_cvt_scalef32_pk_f16_fp4 v77, v64, 1.0 op_sel:[0,1,0]
	v_cvt_scalef32_pk_f16_fp4 v64, v64, 1.0 op_sel:[1,1,0]
	v_pk_fma_f16 v64, v6, v64, v68 op_sel_hi:[0,1,1]
	v_cvt_scalef32_pk_f16_fp4 v68, v65, 1.0
	v_pk_fma_f16 v69, v6, v69, v82 op_sel_hi:[0,1,1]
	v_pk_fma_f16 v68, v6, v68, v76 op_sel_hi:[0,1,1]
	v_cvt_scalef32_pk_f16_fp4 v76, v65, 1.0 op_sel:[1,0,0]
	v_cvt_scalef32_pk_f16_fp4 v82, v65, 1.0 op_sel:[0,1,0]
	v_cvt_scalef32_pk_f16_fp4 v65, v65, 1.0 op_sel:[1,1,0]
	v_pk_fma_f16 v38, v6, v65, v38 op_sel_hi:[0,1,1]
	s_waitcnt vmcnt(30)
	v_cvt_scalef32_pk_f16_fp4 v65, v54, 1.0
	v_pk_fma_f16 v39, v6, v65, v39 op_sel:[1,0,0]
	v_cvt_scalef32_pk_f16_fp4 v65, v54, 1.0 op_sel:[1,0,0]
	v_pk_fma_f16 v40, v6, v65, v40 op_sel:[1,0,0]
	v_cvt_scalef32_pk_f16_fp4 v65, v54, 1.0 op_sel:[0,1,0]
	v_cvt_scalef32_pk_f16_fp4 v54, v54, 1.0 op_sel:[1,1,0]
	v_pk_fma_f16 v54, v6, v54, v62 op_sel:[1,0,0]
	v_cvt_scalef32_pk_f16_fp4 v62, v55, 1.0
	v_pk_fma_f16 v41, v6, v65, v41 op_sel:[1,0,0]
	v_pk_fma_f16 v62, v6, v62, v66 op_sel:[1,0,0]
	v_cvt_scalef32_pk_f16_fp4 v65, v55, 1.0 op_sel:[1,0,0]
	v_cvt_scalef32_pk_f16_fp4 v66, v55, 1.0 op_sel:[0,1,0]
	v_cvt_scalef32_pk_f16_fp4 v55, v55, 1.0 op_sel:[1,1,0]
	v_pk_fma_f16 v55, v6, v55, v63 op_sel:[1,0,0]
	v_cvt_scalef32_pk_f16_fp4 v63, v56, 1.0
	v_pk_fma_f16 v65, v6, v65, v69 op_sel:[1,0,0]
	v_pk_fma_f16 v63, v6, v63, v67 op_sel:[1,0,0]
	v_cvt_scalef32_pk_f16_fp4 v67, v56, 1.0 op_sel:[1,0,0]
	v_cvt_scalef32_pk_f16_fp4 v69, v56, 1.0 op_sel:[0,1,0]
	v_cvt_scalef32_pk_f16_fp4 v56, v56, 1.0 op_sel:[1,1,0]
	v_pk_fma_f16 v74, v6, v74, v85 op_sel_hi:[0,1,1]
	v_pk_fma_f16 v56, v6, v56, v64 op_sel:[1,0,0]
	v_cvt_scalef32_pk_f16_fp4 v64, v57, 1.0
	v_pk_fma_f16 v75, v6, v75, v83 op_sel_hi:[0,1,1]
	v_pk_fma_f16 v77, v6, v77, v90 op_sel_hi:[0,1,1]
	v_pk_fma_f16 v76, v6, v76, v84 op_sel_hi:[0,1,1]
	v_pk_fma_f16 v82, v6, v82, v91 op_sel_hi:[0,1,1]
	v_pk_fma_f16 v66, v6, v66, v74 op_sel:[1,0,0]
	v_pk_fma_f16 v64, v6, v64, v68 op_sel:[1,0,0]
	v_cvt_scalef32_pk_f16_fp4 v68, v57, 1.0 op_sel:[1,0,0]
	v_cvt_scalef32_pk_f16_fp4 v74, v57, 1.0 op_sel:[0,1,0]
	v_cvt_scalef32_pk_f16_fp4 v57, v57, 1.0 op_sel:[1,1,0]
	v_pk_fma_f16 v67, v6, v67, v75 op_sel:[1,0,0]
	v_pk_fma_f16 v69, v6, v69, v77 op_sel:[1,0,0]
	v_pk_fma_f16 v68, v6, v68, v76 op_sel:[1,0,0]
	v_pk_fma_f16 v74, v6, v74, v82 op_sel:[1,0,0]
	v_pk_fma_f16 v6, v6, v57, v38 op_sel:[1,0,0]
	s_waitcnt vmcnt(29)
	v_cvt_scalef32_pk_f16_fp4 v38, v46, 1.0
	v_pk_fma_f16 v38, v7, v38, v39 op_sel_hi:[0,1,1]
	v_cvt_scalef32_pk_f16_fp4 v39, v46, 1.0 op_sel:[1,0,0]
	v_pk_fma_f16 v39, v7, v39, v40 op_sel_hi:[0,1,1]
	v_cvt_scalef32_pk_f16_fp4 v40, v46, 1.0 op_sel:[0,1,0]
	v_pk_fma_f16 v40, v7, v40, v41 op_sel_hi:[0,1,1]
	v_cvt_scalef32_pk_f16_fp4 v41, v46, 1.0 op_sel:[1,1,0]
	v_pk_fma_f16 v41, v7, v41, v54 op_sel_hi:[0,1,1]
	v_cvt_scalef32_pk_f16_fp4 v46, v47, 1.0
	v_cvt_scalef32_pk_f16_fp4 v54, v47, 1.0 op_sel:[1,0,0]
	v_cvt_scalef32_pk_f16_fp4 v57, v47, 1.0 op_sel:[0,1,0]
	v_cvt_scalef32_pk_f16_fp4 v47, v47, 1.0 op_sel:[1,1,0]
	v_pk_fma_f16 v47, v7, v47, v55 op_sel_hi:[0,1,1]
	v_cvt_scalef32_pk_f16_fp4 v55, v48, 1.0
	v_pk_fma_f16 v46, v7, v46, v62 op_sel_hi:[0,1,1]
	v_pk_fma_f16 v55, v7, v55, v63 op_sel_hi:[0,1,1]
	v_cvt_scalef32_pk_f16_fp4 v62, v48, 1.0 op_sel:[1,0,0]
	v_cvt_scalef32_pk_f16_fp4 v63, v48, 1.0 op_sel:[0,1,0]
	v_cvt_scalef32_pk_f16_fp4 v48, v48, 1.0 op_sel:[1,1,0]
	v_pk_fma_f16 v48, v7, v48, v56 op_sel_hi:[0,1,1]
	v_cvt_scalef32_pk_f16_fp4 v56, v49, 1.0
	v_pk_fma_f16 v54, v7, v54, v65 op_sel_hi:[0,1,1]
	v_pk_fma_f16 v56, v7, v56, v64 op_sel_hi:[0,1,1]
	v_cvt_scalef32_pk_f16_fp4 v64, v49, 1.0 op_sel:[1,0,0]
	v_cvt_scalef32_pk_f16_fp4 v65, v49, 1.0 op_sel:[0,1,0]
	v_cvt_scalef32_pk_f16_fp4 v49, v49, 1.0 op_sel:[1,1,0]
	v_pk_fma_f16 v6, v7, v49, v6 op_sel_hi:[0,1,1]
	s_waitcnt vmcnt(28)
	v_cvt_scalef32_pk_f16_fp4 v49, v34, 1.0
	v_pk_fma_f16 v38, v7, v49, v38 op_sel:[1,0,0]
	v_cvt_scalef32_pk_f16_fp4 v49, v34, 1.0 op_sel:[1,0,0]
	v_pk_fma_f16 v39, v7, v49, v39 op_sel:[1,0,0]
	v_cvt_scalef32_pk_f16_fp4 v49, v34, 1.0 op_sel:[0,1,0]
	v_cvt_scalef32_pk_f16_fp4 v34, v34, 1.0 op_sel:[1,1,0]
	v_pk_fma_f16 v34, v7, v34, v41 op_sel:[1,0,0]
	v_cvt_scalef32_pk_f16_fp4 v41, v35, 1.0
	v_pk_fma_f16 v40, v7, v49, v40 op_sel:[1,0,0]
	v_pk_fma_f16 v41, v7, v41, v46 op_sel:[1,0,0]
	v_cvt_scalef32_pk_f16_fp4 v46, v35, 1.0 op_sel:[1,0,0]
	v_cvt_scalef32_pk_f16_fp4 v49, v35, 1.0 op_sel:[0,1,0]
	v_cvt_scalef32_pk_f16_fp4 v35, v35, 1.0 op_sel:[1,1,0]
	v_pk_fma_f16 v35, v7, v35, v47 op_sel:[1,0,0]
	v_cvt_scalef32_pk_f16_fp4 v47, v36, 1.0
	v_pk_fma_f16 v46, v7, v46, v54 op_sel:[1,0,0]
	v_pk_fma_f16 v47, v7, v47, v55 op_sel:[1,0,0]
	v_cvt_scalef32_pk_f16_fp4 v54, v36, 1.0 op_sel:[1,0,0]
	v_cvt_scalef32_pk_f16_fp4 v55, v36, 1.0 op_sel:[0,1,0]
	v_cvt_scalef32_pk_f16_fp4 v36, v36, 1.0 op_sel:[1,1,0]
	v_pk_fma_f16 v57, v7, v57, v66 op_sel_hi:[0,1,1]
	v_pk_fma_f16 v36, v7, v36, v48 op_sel:[1,0,0]
	v_cvt_scalef32_pk_f16_fp4 v48, v37, 1.0
	v_pk_fma_f16 v62, v7, v62, v67 op_sel_hi:[0,1,1]
	v_pk_fma_f16 v63, v7, v63, v69 op_sel_hi:[0,1,1]
	v_pk_fma_f16 v64, v7, v64, v68 op_sel_hi:[0,1,1]
	v_pk_fma_f16 v65, v7, v65, v74 op_sel_hi:[0,1,1]
	v_pk_fma_f16 v49, v7, v49, v57 op_sel:[1,0,0]
	v_pk_fma_f16 v48, v7, v48, v56 op_sel:[1,0,0]
	v_cvt_scalef32_pk_f16_fp4 v56, v37, 1.0 op_sel:[1,0,0]
	v_cvt_scalef32_pk_f16_fp4 v57, v37, 1.0 op_sel:[0,1,0]
	v_cvt_scalef32_pk_f16_fp4 v37, v37, 1.0 op_sel:[1,1,0]
	v_pk_fma_f16 v54, v7, v54, v62 op_sel:[1,0,0]
	v_pk_fma_f16 v55, v7, v55, v63 op_sel:[1,0,0]
	v_pk_fma_f16 v56, v7, v56, v64 op_sel:[1,0,0]
	v_pk_fma_f16 v57, v7, v57, v65 op_sel:[1,0,0]
	v_pk_fma_f16 v6, v7, v37, v6 op_sel:[1,0,0]
	s_waitcnt vmcnt(27)
	v_cvt_scalef32_pk_f16_fp4 v7, v26, 1.0
	v_pk_fma_f16 v7, v8, v7, v38 op_sel_hi:[0,1,1]
	v_cvt_scalef32_pk_f16_fp4 v37, v26, 1.0 op_sel:[1,0,0]
	v_cvt_scalef32_pk_f16_fp4 v38, v26, 1.0 op_sel:[0,1,0]
	v_cvt_scalef32_pk_f16_fp4 v26, v26, 1.0 op_sel:[1,1,0]
	v_pk_fma_f16 v37, v8, v37, v39 op_sel_hi:[0,1,1]
	v_pk_fma_f16 v38, v8, v38, v40 op_sel_hi:[0,1,1]
	v_pk_fma_f16 v26, v8, v26, v34 op_sel_hi:[0,1,1]
	v_cvt_scalef32_pk_f16_fp4 v34, v27, 1.0
	v_cvt_scalef32_pk_f16_fp4 v39, v27, 1.0 op_sel:[1,0,0]
	v_cvt_scalef32_pk_f16_fp4 v40, v27, 1.0 op_sel:[0,1,0]
	v_cvt_scalef32_pk_f16_fp4 v27, v27, 1.0 op_sel:[1,1,0]
	v_pk_fma_f16 v34, v8, v34, v41 op_sel_hi:[0,1,1]
	v_pk_fma_f16 v39, v8, v39, v46 op_sel_hi:[0,1,1]
	v_pk_fma_f16 v27, v8, v27, v35 op_sel_hi:[0,1,1]
	v_cvt_scalef32_pk_f16_fp4 v35, v28, 1.0
	v_cvt_scalef32_pk_f16_fp4 v41, v28, 1.0 op_sel:[1,0,0]
	v_cvt_scalef32_pk_f16_fp4 v46, v28, 1.0 op_sel:[0,1,0]
	v_cvt_scalef32_pk_f16_fp4 v28, v28, 1.0 op_sel:[1,1,0]
	v_pk_fma_f16 v28, v8, v28, v36 op_sel_hi:[0,1,1]
	v_cvt_scalef32_pk_f16_fp4 v36, v29, 1.0
	v_pk_fma_f16 v35, v8, v35, v47 op_sel_hi:[0,1,1]
	v_pk_fma_f16 v36, v8, v36, v48 op_sel_hi:[0,1,1]
	v_cvt_scalef32_pk_f16_fp4 v47, v29, 1.0 op_sel:[1,0,0]
	v_cvt_scalef32_pk_f16_fp4 v48, v29, 1.0 op_sel:[0,1,0]
	v_cvt_scalef32_pk_f16_fp4 v29, v29, 1.0 op_sel:[1,1,0]
	v_pk_fma_f16 v6, v8, v29, v6 op_sel_hi:[0,1,1]
	s_waitcnt vmcnt(26)
	v_cvt_scalef32_pk_f16_fp4 v29, v18, 1.0
	v_pk_fma_f16 v7, v8, v29, v7 op_sel:[1,0,0]
	v_cvt_scalef32_pk_f16_fp4 v29, v18, 1.0 op_sel:[1,0,0]
	v_pk_fma_f16 v29, v8, v29, v37 op_sel:[1,0,0]
	v_cvt_scalef32_pk_f16_fp4 v37, v18, 1.0 op_sel:[0,1,0]
	v_cvt_scalef32_pk_f16_fp4 v18, v18, 1.0 op_sel:[1,1,0]
	v_pk_fma_f16 v18, v8, v18, v26 op_sel:[1,0,0]
	v_cvt_scalef32_pk_f16_fp4 v26, v19, 1.0
	v_pk_fma_f16 v37, v8, v37, v38 op_sel:[1,0,0]
	v_pk_fma_f16 v26, v8, v26, v34 op_sel:[1,0,0]
	v_cvt_scalef32_pk_f16_fp4 v34, v19, 1.0 op_sel:[1,0,0]
	v_cvt_scalef32_pk_f16_fp4 v38, v19, 1.0 op_sel:[0,1,0]
	v_cvt_scalef32_pk_f16_fp4 v19, v19, 1.0 op_sel:[1,1,0]
	v_pk_fma_f16 v19, v8, v19, v27 op_sel:[1,0,0]
	v_cvt_scalef32_pk_f16_fp4 v27, v20, 1.0
	v_pk_fma_f16 v34, v8, v34, v39 op_sel:[1,0,0]
	v_pk_fma_f16 v27, v8, v27, v35 op_sel:[1,0,0]
	v_cvt_scalef32_pk_f16_fp4 v35, v20, 1.0 op_sel:[1,0,0]
	v_cvt_scalef32_pk_f16_fp4 v39, v20, 1.0 op_sel:[0,1,0]
	v_cvt_scalef32_pk_f16_fp4 v20, v20, 1.0 op_sel:[1,1,0]
	v_pk_fma_f16 v40, v8, v40, v49 op_sel_hi:[0,1,1]
	v_pk_fma_f16 v20, v8, v20, v28 op_sel:[1,0,0]
	v_cvt_scalef32_pk_f16_fp4 v28, v21, 1.0
	v_pk_fma_f16 v41, v8, v41, v54 op_sel_hi:[0,1,1]
	v_pk_fma_f16 v46, v8, v46, v55 op_sel_hi:[0,1,1]
	v_pk_fma_f16 v47, v8, v47, v56 op_sel_hi:[0,1,1]
	v_pk_fma_f16 v48, v8, v48, v57 op_sel_hi:[0,1,1]
	v_pk_fma_f16 v38, v8, v38, v40 op_sel:[1,0,0]
	v_pk_fma_f16 v28, v8, v28, v36 op_sel:[1,0,0]
	v_cvt_scalef32_pk_f16_fp4 v36, v21, 1.0 op_sel:[1,0,0]
	v_cvt_scalef32_pk_f16_fp4 v40, v21, 1.0 op_sel:[0,1,0]
	v_cvt_scalef32_pk_f16_fp4 v21, v21, 1.0 op_sel:[1,1,0]
	v_pk_fma_f16 v35, v8, v35, v41 op_sel:[1,0,0]
	v_pk_fma_f16 v39, v8, v39, v46 op_sel:[1,0,0]
	v_pk_fma_f16 v36, v8, v36, v47 op_sel:[1,0,0]
	v_pk_fma_f16 v40, v8, v40, v48 op_sel:[1,0,0]
	v_pk_fma_f16 v6, v8, v21, v6 op_sel:[1,0,0]
	s_waitcnt vmcnt(25)
	v_cvt_scalef32_pk_f16_fp4 v8, v14, 1.0
	v_pk_fma_f16 v7, v9, v8, v7 op_sel_hi:[0,1,1]
	v_cvt_scalef32_pk_f16_fp4 v8, v14, 1.0 op_sel:[1,0,0]
	v_cvt_scalef32_pk_f16_fp4 v21, v14, 1.0 op_sel:[0,1,0]
	v_cvt_scalef32_pk_f16_fp4 v14, v14, 1.0 op_sel:[1,1,0]
	v_pk_fma_f16 v14, v9, v14, v18 op_sel_hi:[0,1,1]
	v_cvt_scalef32_pk_f16_fp4 v18, v15, 1.0
	v_pk_fma_f16 v8, v9, v8, v29 op_sel_hi:[0,1,1]
	v_pk_fma_f16 v18, v9, v18, v26 op_sel_hi:[0,1,1]
	v_cvt_scalef32_pk_f16_fp4 v26, v15, 1.0 op_sel:[1,0,0]
	v_cvt_scalef32_pk_f16_fp4 v29, v15, 1.0 op_sel:[0,1,0]
	v_cvt_scalef32_pk_f16_fp4 v15, v15, 1.0 op_sel:[1,1,0]
	v_pk_fma_f16 v15, v9, v15, v19 op_sel_hi:[0,1,1]
	v_cvt_scalef32_pk_f16_fp4 v19, v16, 1.0
	v_pk_fma_f16 v26, v9, v26, v34 op_sel_hi:[0,1,1]
	v_pk_fma_f16 v19, v9, v19, v27 op_sel_hi:[0,1,1]
	v_cvt_scalef32_pk_f16_fp4 v27, v16, 1.0 op_sel:[1,0,0]
	v_cvt_scalef32_pk_f16_fp4 v34, v16, 1.0 op_sel:[0,1,0]
	v_cvt_scalef32_pk_f16_fp4 v16, v16, 1.0 op_sel:[1,1,0]
	v_pk_fma_f16 v16, v9, v16, v20 op_sel_hi:[0,1,1]
	v_cvt_scalef32_pk_f16_fp4 v20, v17, 1.0
	v_pk_fma_f16 v27, v9, v27, v35 op_sel_hi:[0,1,1]
	v_pk_fma_f16 v20, v9, v20, v28 op_sel_hi:[0,1,1]
	v_cvt_scalef32_pk_f16_fp4 v28, v17, 1.0 op_sel:[1,0,0]
	v_cvt_scalef32_pk_f16_fp4 v35, v17, 1.0 op_sel:[0,1,0]
	v_cvt_scalef32_pk_f16_fp4 v17, v17, 1.0 op_sel:[1,1,0]
	v_pk_fma_f16 v6, v9, v17, v6 op_sel_hi:[0,1,1]
	s_waitcnt vmcnt(24)
	v_cvt_scalef32_pk_f16_fp4 v17, v10, 1.0
	v_pk_fma_f16 v7, v9, v17, v7 op_sel:[1,0,0]
	v_cvt_scalef32_pk_f16_fp4 v17, v10, 1.0 op_sel:[1,0,0]
	v_pk_fma_f16 v8, v9, v17, v8 op_sel:[1,0,0]
	v_cvt_scalef32_pk_f16_fp4 v17, v10, 1.0 op_sel:[0,1,0]
	v_cvt_scalef32_pk_f16_fp4 v10, v10, 1.0 op_sel:[1,1,0]
	v_pk_fma_f16 v21, v9, v21, v37 op_sel_hi:[0,1,1]
	v_pk_fma_f16 v10, v9, v10, v14 op_sel:[1,0,0]
	v_cvt_scalef32_pk_f16_fp4 v14, v11, 1.0
	v_pk_fma_f16 v17, v9, v17, v21 op_sel:[1,0,0]
	v_pk_fma_f16 v14, v9, v14, v18 op_sel:[1,0,0]
	v_cvt_scalef32_pk_f16_fp4 v18, v11, 1.0 op_sel:[1,0,0]
	v_cvt_scalef32_pk_f16_fp4 v21, v11, 1.0 op_sel:[0,1,0]
	v_cvt_scalef32_pk_f16_fp4 v11, v11, 1.0 op_sel:[1,1,0]
	v_pk_fma_f16 v11, v9, v11, v15 op_sel:[1,0,0]
	v_cvt_scalef32_pk_f16_fp4 v15, v12, 1.0
	v_pk_fma_f16 v18, v9, v18, v26 op_sel:[1,0,0]
	v_pk_fma_f16 v15, v9, v15, v19 op_sel:[1,0,0]
	v_cvt_scalef32_pk_f16_fp4 v19, v12, 1.0 op_sel:[1,0,0]
	v_cvt_scalef32_pk_f16_fp4 v26, v12, 1.0 op_sel:[0,1,0]
	v_cvt_scalef32_pk_f16_fp4 v12, v12, 1.0 op_sel:[1,1,0]
	v_pk_fma_f16 v29, v9, v29, v38 op_sel_hi:[0,1,1]
	v_pk_fma_f16 v34, v9, v34, v39 op_sel_hi:[0,1,1]
	v_pk_fma_f16 v35, v9, v35, v40 op_sel_hi:[0,1,1]
	v_pk_fma_f16 v19, v9, v19, v27 op_sel:[1,0,0]
	v_pk_fma_f16 v12, v9, v12, v16 op_sel:[1,0,0]
	v_cvt_scalef32_pk_f16_fp4 v16, v13, 1.0
	v_cvt_scalef32_pk_f16_fp4 v27, v13, 1.0 op_sel:[0,1,0]
	v_pk_fma_f16 v21, v9, v21, v29 op_sel:[1,0,0]
	v_pk_fma_f16 v26, v9, v26, v34 op_sel:[1,0,0]
	v_pk_fma_f16 v16, v9, v16, v20 op_sel:[1,0,0]
	v_cvt_scalef32_pk_f16_fp4 v20, v13, 1.0 op_sel:[1,0,0]
	v_pk_fma_f16 v27, v9, v27, v35 op_sel:[1,0,0]
	v_cvt_scalef32_pk_f16_fp4 v13, v13, 1.0 op_sel:[1,1,0]
	v_pk_fma_f16 v28, v9, v28, v36 op_sel_hi:[0,1,1]
	v_pk_fma_f16 v6, v9, v13, v6 op_sel:[1,0,0]
	v_permlane32_swap_b32_e32 v7, v15
	v_permlane32_swap_b32_e32 v17, v26
	v_permlane32_swap_b32_e32 v10, v12
	v_permlane32_swap_b32_e32 v14, v16
	v_permlane32_swap_b32_e32 v21, v27
	v_pk_fma_f16 v20, v9, v20, v28 op_sel:[1,0,0]
	v_pk_add_f16 v7, v7, v15
	v_pk_add_f16 v9, v17, v26
	v_pk_add_f16 v10, v10, v12
	v_pk_add_f16 v12, v14, v16
	v_pk_add_f16 v14, v21, v27
	v_permlane32_swap_b32_e32 v11, v6
	v_permlane32_swap_b32_e32 v8, v19
	v_permlane32_swap_b32_e32 v18, v20
	v_pk_add_f16 v6, v11, v6
	v_permlane16_swap_b32_e32 v7, v12
	v_permlane16_swap_b32_e32 v9, v14
	v_pk_add_f16 v8, v8, v19
	v_pk_add_f16 v13, v18, v20
	v_pk_add_f16 v7, v7, v12
	v_pk_add_f16 v9, v9, v14
	v_permlane16_swap_b32_e32 v10, v6
	v_permlane16_swap_b32_e32 v8, v13
	v_pk_add_f16 v6, v10, v6
	v_cndmask_b32_e64 v10, v9, v7, s[4:5]
	v_cndmask_b32_e64 v7, v7, v9, s[4:5]
	v_pk_add_f16 v8, v8, v13
	v_cvt_f32_f16_sdwa v13, v189 dst_sel:DWORD dst_unused:UNUSED_PAD src0_sel:WORD_1
	v_mov_b32_dpp v7, v7 row_ror:8 row_mask:0xf bank_mask:0xf bound_ctrl:1
	v_pk_add_f16 v9, v10, v7
	v_cndmask_b32_e64 v10, v6, v8, s[4:5]
	v_cndmask_b32_e64 v6, v8, v6, s[4:5]
	v_cvt_f32_f16_sdwa v7, v188 dst_sel:DWORD dst_unused:UNUSED_PAD src0_sel:WORD_1
	v_cvt_f32_f16_e32 v8, v9
	v_mov_b32_dpp v11, v6 row_ror:8 row_mask:0xf bank_mask:0xf bound_ctrl:1
	v_cvt_f32_f16_e32 v6, v188
	v_cvt_f32_f16_sdwa v9, v9 dst_sel:DWORD dst_unused:UNUSED_PAD src0_sel:WORD_1
	v_pk_add_f16 v15, v10, v11
	v_cvt_f32_f16_sdwa v11, v194 dst_sel:DWORD dst_unused:UNUSED_PAD src0_sel:WORD_1
	v_cvt_f32_f16_e32 v10, v194
	v_cvt_f32_f16_e32 v12, v189
	v_cvt_f32_f16_e32 v14, v15
	v_cvt_f32_f16_sdwa v15, v15 dst_sel:DWORD dst_unused:UNUSED_PAD src0_sel:WORD_1
	v_pk_fma_f32 v[6:7], v[2:3], v[8:9], v[6:7]
	v_cvt_f32_f16_sdwa v9, v195 dst_sel:DWORD dst_unused:UNUSED_PAD src0_sel:WORD_1
	v_cvt_f32_f16_e32 v8, v195
	v_pk_add_f32 v[6:7], v[6:7], v[10:11]
	v_pk_fma_f32 v[10:11], v[4:5], v[14:15], v[12:13]
	v_cvt_pk_f16_f32 v6, v6, v7
	v_pk_add_f32 v[8:9], v[10:11], v[8:9]
	s_nop 0
	v_cvt_pk_f16_f32 v7, v8, v9
	v_lshl_add_u64 v[8:9], v[190:191], 0, s[14:15]
	global_store_dwordx2 v[8:9], v[6:7], off
	v_lshl_add_u64 v[6:7], v[184:185], 0, s[16:17]
	v_lshl_add_u64 v[10:11], v[186:187], 0, s[20:21]
	global_load_dwordx4 v[114:117], v[6:7], off offset:48
	global_load_dwordx4 v[118:121], v[6:7], off offset:32
	global_load_dwordx4 v[126:129], v[6:7], off offset:16
	global_load_dwordx4 v[134:137], v[6:7], off
	s_nop 0
	global_load_dwordx4 v[6:9], v[10:11], off offset:16
	global_load_dwordx4 v[38:41], v[10:11], off
	v_lshl_add_u64 v[10:11], v[190:191], 0, s[18:19]
	v_lshl_add_u64 v[12:13], v[192:193], 0, s[18:19]
	global_load_dwordx2 v[194:195], v[10:11], off
	global_load_dwordx2 v[188:189], v[12:13], off
	s_waitcnt vmcnt(29)
	v_lshl_add_u32 v10, v178, 7, v207
	v_lshl_add_u32 v11, v179, 7, v207
	global_load_dwordx4 v[142:145], v10, s[6:7]
	global_load_dwordx4 v[130:133], v11, s[6:7]
	v_lshl_add_u32 v10, v180, 7, v207
	v_lshl_add_u32 v11, v181, 7, v207
	global_load_dwordx4 v[110:113], v10, s[6:7]
	global_load_dwordx4 v[102:105], v11, s[6:7]
	v_lshl_add_u32 v10, v174, 7, v207
	v_lshl_add_u32 v11, v175, 7, v207
	global_load_dwordx4 v[90:93], v10, s[6:7]
	global_load_dwordx4 v[82:85], v11, s[6:7]
	v_lshl_add_u32 v10, v176, 7, v207
	v_lshl_add_u32 v11, v177, 7, v207
	global_load_dwordx4 v[74:77], v10, s[6:7]
	global_load_dwordx4 v[66:69], v11, s[6:7]
	v_lshl_add_u32 v10, v170, 7, v207
	v_lshl_add_u32 v11, v171, 7, v207
	global_load_dwordx4 v[62:65], v10, s[6:7]
	global_load_dwordx4 v[54:57], v11, s[6:7]
	v_lshl_add_u32 v10, v172, 7, v207
	v_lshl_add_u32 v11, v173, 7, v207
	global_load_dwordx4 v[46:49], v10, s[6:7]
	global_load_dwordx4 v[34:37], v11, s[6:7]
	v_lshl_add_u32 v10, v166, 7, v207
	v_lshl_add_u32 v11, v167, 7, v207
	global_load_dwordx4 v[26:29], v10, s[6:7]
	global_load_dwordx4 v[18:21], v11, s[6:7]
	v_lshl_add_u32 v10, v168, 7, v207
	v_lshl_add_u32 v11, v169, 7, v207
	global_load_dwordx4 v[14:17], v10, s[6:7]
	s_nop 0
	global_load_dwordx4 v[10:13], v11, s[6:7]
	s_waitcnt vmcnt(40)
	v_cvt_scalef32_pk_f16_fp4 v166, v162, 1.0
	v_pk_fma_f16 v166, v94, v166, 0 op_sel_hi:[0,1,1]
	v_cvt_scalef32_pk_f16_fp4 v167, v162, 1.0 op_sel:[1,0,0]
	s_waitcnt vmcnt(39)
	v_cvt_scalef32_pk_f16_fp4 v178, v158, 1.0
	v_pk_fma_f16 v167, v94, v167, 0 op_sel_hi:[0,1,1]
	v_cvt_scalef32_pk_f16_fp4 v168, v162, 1.0 op_sel:[0,1,0]
	v_cvt_scalef32_pk_f16_fp4 v162, v162, 1.0 op_sel:[1,1,0]
	v_pk_fma_f16 v166, v94, v178, v166 op_sel:[1,0,0]
	v_cvt_scalef32_pk_f16_fp4 v178, v158, 1.0 op_sel:[1,0,0]
	v_pk_fma_f16 v162, v94, v162, 0 op_sel_hi:[0,1,1]
	v_cvt_scalef32_pk_f16_fp4 v169, v163, 1.0
	v_pk_fma_f16 v167, v94, v178, v167 op_sel:[1,0,0]
	v_cvt_scalef32_pk_f16_fp4 v178, v158, 1.0 op_sel:[0,1,0]
	v_cvt_scalef32_pk_f16_fp4 v158, v158, 1.0 op_sel:[1,1,0]
	v_pk_fma_f16 v169, v94, v169, 0 op_sel_hi:[0,1,1]
	v_cvt_scalef32_pk_f16_fp4 v170, v163, 1.0 op_sel:[1,0,0]
	v_pk_fma_f16 v158, v94, v158, v162 op_sel:[1,0,0]
	v_cvt_scalef32_pk_f16_fp4 v162, v159, 1.0
	v_pk_fma_f16 v170, v94, v170, 0 op_sel_hi:[0,1,1]
	v_cvt_scalef32_pk_f16_fp4 v171, v163, 1.0 op_sel:[0,1,0]
	v_cvt_scalef32_pk_f16_fp4 v163, v163, 1.0 op_sel:[1,1,0]
	v_pk_fma_f16 v162, v94, v162, v169 op_sel:[1,0,0]
	v_cvt_scalef32_pk_f16_fp4 v169, v159, 1.0 op_sel:[1,0,0]
	v_pk_fma_f16 v163, v94, v163, 0 op_sel_hi:[0,1,1]
	v_cvt_scalef32_pk_f16_fp4 v172, v164, 1.0
	v_pk_fma_f16 v169, v94, v169, v170 op_sel:[1,0,0]
	v_cvt_scalef32_pk_f16_fp4 v170, v159, 1.0 op_sel:[0,1,0]
	v_cvt_scalef32_pk_f16_fp4 v159, v159, 1.0 op_sel:[1,1,0]
	v_pk_fma_f16 v171, v94, v171, 0 op_sel_hi:[0,1,1]
	v_pk_fma_f16 v172, v94, v172, 0 op_sel_hi:[0,1,1]
	v_cvt_scalef32_pk_f16_fp4 v173, v164, 1.0 op_sel:[1,0,0]
	v_cvt_scalef32_pk_f16_fp4 v174, v164, 1.0 op_sel:[0,1,0]
	v_cvt_scalef32_pk_f16_fp4 v164, v164, 1.0 op_sel:[1,1,0]
	v_pk_fma_f16 v159, v94, v159, v163 op_sel:[1,0,0]
	v_cvt_scalef32_pk_f16_fp4 v163, v160, 1.0
	v_pk_fma_f16 v173, v94, v173, 0 op_sel_hi:[0,1,1]
	v_pk_fma_f16 v174, v94, v174, 0 op_sel_hi:[0,1,1]
	v_pk_fma_f16 v164, v94, v164, 0 op_sel_hi:[0,1,1]
	v_cvt_scalef32_pk_f16_fp4 v175, v165, 1.0
	v_cvt_scalef32_pk_f16_fp4 v176, v165, 1.0 op_sel:[1,0,0]
	v_cvt_scalef32_pk_f16_fp4 v177, v165, 1.0 op_sel:[0,1,0]
	v_cvt_scalef32_pk_f16_fp4 v165, v165, 1.0 op_sel:[1,1,0]
	v_pk_fma_f16 v170, v94, v170, v171 op_sel:[1,0,0]
	v_pk_fma_f16 v163, v94, v163, v172 op_sel:[1,0,0]
	v_cvt_scalef32_pk_f16_fp4 v171, v160, 1.0 op_sel:[1,0,0]
	v_cvt_scalef32_pk_f16_fp4 v172, v160, 1.0 op_sel:[0,1,0]
	v_cvt_scalef32_pk_f16_fp4 v160, v160, 1.0 op_sel:[1,1,0]
	v_pk_fma_f16 v168, v94, v168, 0 op_sel_hi:[0,1,1]
	v_pk_fma_f16 v175, v94, v175, 0 op_sel_hi:[0,1,1]
	v_pk_fma_f16 v176, v94, v176, 0 op_sel_hi:[0,1,1]
	v_pk_fma_f16 v177, v94, v177, 0 op_sel_hi:[0,1,1]
	v_pk_fma_f16 v165, v94, v165, 0 op_sel_hi:[0,1,1]
	v_pk_fma_f16 v171, v94, v171, v173 op_sel:[1,0,0]
	v_pk_fma_f16 v172, v94, v172, v174 op_sel:[1,0,0]
	v_pk_fma_f16 v160, v94, v160, v164 op_sel:[1,0,0]
	v_cvt_scalef32_pk_f16_fp4 v164, v161, 1.0
	v_cvt_scalef32_pk_f16_fp4 v173, v161, 1.0 op_sel:[1,0,0]
	v_cvt_scalef32_pk_f16_fp4 v174, v161, 1.0 op_sel:[0,1,0]
	v_cvt_scalef32_pk_f16_fp4 v161, v161, 1.0 op_sel:[1,1,0]
	v_pk_fma_f16 v168, v94, v178, v168 op_sel:[1,0,0]
	v_pk_fma_f16 v164, v94, v164, v175 op_sel:[1,0,0]
	v_pk_fma_f16 v173, v94, v173, v176 op_sel:[1,0,0]
	v_pk_fma_f16 v174, v94, v174, v177 op_sel:[1,0,0]
	v_pk_fma_f16 v94, v94, v161, v165 op_sel:[1,0,0]
	s_waitcnt vmcnt(38)
	v_cvt_scalef32_pk_f16_fp4 v161, v154, 1.0
	v_pk_fma_f16 v161, v95, v161, v166 op_sel_hi:[0,1,1]
	v_cvt_scalef32_pk_f16_fp4 v165, v154, 1.0 op_sel:[1,0,0]
	v_cvt_scalef32_pk_f16_fp4 v166, v154, 1.0 op_sel:[0,1,0]
	v_cvt_scalef32_pk_f16_fp4 v154, v154, 1.0 op_sel:[1,1,0]
	v_pk_fma_f16 v154, v95, v154, v158 op_sel_hi:[0,1,1]
	v_cvt_scalef32_pk_f16_fp4 v158, v155, 1.0
	v_pk_fma_f16 v165, v95, v165, v167 op_sel_hi:[0,1,1]
	v_pk_fma_f16 v158, v95, v158, v162 op_sel_hi:[0,1,1]
	v_cvt_scalef32_pk_f16_fp4 v162, v155, 1.0 op_sel:[1,0,0]
	v_cvt_scalef32_pk_f16_fp4 v167, v155, 1.0 op_sel:[0,1,0]
	v_cvt_scalef32_pk_f16_fp4 v155, v155, 1.0 op_sel:[1,1,0]
	v_pk_fma_f16 v155, v95, v155, v159 op_sel_hi:[0,1,1]
	v_cvt_scalef32_pk_f16_fp4 v159, v156, 1.0
	v_pk_fma_f16 v166, v95, v166, v168 op_sel_hi:[0,1,1]
	v_pk_fma_f16 v159, v95, v159, v163 op_sel_hi:[0,1,1]
	v_cvt_scalef32_pk_f16_fp4 v163, v156, 1.0 op_sel:[1,0,0]
	v_cvt_scalef32_pk_f16_fp4 v168, v156, 1.0 op_sel:[0,1,0]
	v_cvt_scalef32_pk_f16_fp4 v156, v156, 1.0 op_sel:[1,1,0]
	v_pk_fma_f16 v156, v95, v156, v160 op_sel_hi:[0,1,1]
	v_cvt_scalef32_pk_f16_fp4 v160, v157, 1.0
	v_pk_fma_f16 v162, v95, v162, v169 op_sel_hi:[0,1,1]
	v_pk_fma_f16 v160, v95, v160, v164 op_sel_hi:[0,1,1]
	v_cvt_scalef32_pk_f16_fp4 v164, v157, 1.0 op_sel:[1,0,0]
	v_cvt_scalef32_pk_f16_fp4 v169, v157, 1.0 op_sel:[0,1,0]
	v_cvt_scalef32_pk_f16_fp4 v157, v157, 1.0 op_sel:[1,1,0]
	v_pk_fma_f16 v94, v95, v157, v94 op_sel_hi:[0,1,1]
	s_waitcnt vmcnt(37)
	v_cvt_scalef32_pk_f16_fp4 v157, v150, 1.0
	v_pk_fma_f16 v157, v95, v157, v161 op_sel:[1,0,0]
	v_cvt_scalef32_pk_f16_fp4 v161, v150, 1.0 op_sel:[1,0,0]
	v_pk_fma_f16 v161, v95, v161, v165 op_sel:[1,0,0]
	v_cvt_scalef32_pk_f16_fp4 v165, v150, 1.0 op_sel:[0,1,0]
	v_cvt_scalef32_pk_f16_fp4 v150, v150, 1.0 op_sel:[1,1,0]
	v_pk_fma_f16 v150, v95, v150, v154 op_sel:[1,0,0]
	v_cvt_scalef32_pk_f16_fp4 v154, v151, 1.0
	v_pk_fma_f16 v154, v95, v154, v158 op_sel:[1,0,0]
	v_cvt_scalef32_pk_f16_fp4 v158, v151, 1.0 op_sel:[1,0,0]
	v_pk_fma_f16 v158, v95, v158, v162 op_sel:[1,0,0]
	v_cvt_scalef32_pk_f16_fp4 v162, v151, 1.0 op_sel:[0,1,0]
	v_cvt_scalef32_pk_f16_fp4 v151, v151, 1.0 op_sel:[1,1,0]
	v_pk_fma_f16 v151, v95, v151, v155 op_sel:[1,0,0]
	v_cvt_scalef32_pk_f16_fp4 v155, v152, 1.0
	v_pk_fma_f16 v163, v95, v163, v171 op_sel_hi:[0,1,1]
	v_pk_fma_f16 v155, v95, v155, v159 op_sel:[1,0,0]
	v_cvt_scalef32_pk_f16_fp4 v159, v152, 1.0 op_sel:[1,0,0]
	v_pk_fma_f16 v159, v95, v159, v163 op_sel:[1,0,0]
	v_cvt_scalef32_pk_f16_fp4 v163, v152, 1.0 op_sel:[0,1,0]
	v_cvt_scalef32_pk_f16_fp4 v152, v152, 1.0 op_sel:[1,1,0]
	v_pk_fma_f16 v152, v95, v152, v156 op_sel:[1,0,0]
	v_cvt_scalef32_pk_f16_fp4 v156, v153, 1.0
	v_pk_fma_f16 v164, v95, v164, v173 op_sel_hi:[0,1,1]
	v_pk_fma_f16 v156, v95, v156, v160 op_sel:[1,0,0]
	v_cvt_scalef32_pk_f16_fp4 v160, v153, 1.0 op_sel:[1,0,0]
	v_pk_fma_f16 v167, v95, v167, v170 op_sel_hi:[0,1,1]
	v_pk_fma_f16 v168, v95, v168, v172 op_sel_hi:[0,1,1]
	v_pk_fma_f16 v169, v95, v169, v174 op_sel_hi:[0,1,1]
	v_pk_fma_f16 v160, v95, v160, v164 op_sel:[1,0,0]
	v_cvt_scalef32_pk_f16_fp4 v164, v153, 1.0 op_sel:[0,1,0]
	v_cvt_scalef32_pk_f16_fp4 v153, v153, 1.0 op_sel:[1,1,0]
	v_pk_fma_f16 v165, v95, v165, v166 op_sel:[1,0,0]
	v_pk_fma_f16 v162, v95, v162, v167 op_sel:[1,0,0]
	v_pk_fma_f16 v163, v95, v163, v168 op_sel:[1,0,0]
	v_pk_fma_f16 v164, v95, v164, v169 op_sel:[1,0,0]
	v_pk_fma_f16 v94, v95, v153, v94 op_sel:[1,0,0]
	s_waitcnt vmcnt(36)
	v_cvt_scalef32_pk_f16_fp4 v95, v146, 1.0
	v_pk_fma_f16 v95, v96, v95, v157 op_sel_hi:[0,1,1]
	v_cvt_scalef32_pk_f16_fp4 v153, v146, 1.0 op_sel:[1,0,0]
	v_cvt_scalef32_pk_f16_fp4 v157, v146, 1.0 op_sel:[0,1,0]
	v_cvt_scalef32_pk_f16_fp4 v146, v146, 1.0 op_sel:[1,1,0]
	v_pk_fma_f16 v146, v96, v146, v150 op_sel_hi:[0,1,1]
	v_cvt_scalef32_pk_f16_fp4 v150, v147, 1.0
	v_pk_fma_f16 v150, v96, v150, v154 op_sel_hi:[0,1,1]
	v_cvt_scalef32_pk_f16_fp4 v154, v147, 1.0 op_sel:[1,0,0]
	v_pk_fma_f16 v154, v96, v154, v158 op_sel_hi:[0,1,1]
	v_cvt_scalef32_pk_f16_fp4 v158, v147, 1.0 op_sel:[0,1,0]
	v_cvt_scalef32_pk_f16_fp4 v147, v147, 1.0 op_sel:[1,1,0]
	v_pk_fma_f16 v147, v96, v147, v151 op_sel_hi:[0,1,1]
	v_cvt_scalef32_pk_f16_fp4 v151, v148, 1.0
	v_pk_fma_f16 v151, v96, v151, v155 op_sel_hi:[0,1,1]
	v_cvt_scalef32_pk_f16_fp4 v155, v148, 1.0 op_sel:[1,0,0]
	v_pk_fma_f16 v155, v96, v155, v159 op_sel_hi:[0,1,1]
	v_cvt_scalef32_pk_f16_fp4 v159, v148, 1.0 op_sel:[0,1,0]
	v_cvt_scalef32_pk_f16_fp4 v148, v148, 1.0 op_sel:[1,1,0]
	v_pk_fma_f16 v148, v96, v148, v152 op_sel_hi:[0,1,1]
	v_cvt_scalef32_pk_f16_fp4 v152, v149, 1.0
	v_pk_fma_f16 v152, v96, v152, v156 op_sel_hi:[0,1,1]
	v_cvt_scalef32_pk_f16_fp4 v156, v149, 1.0 op_sel:[1,0,0]
	v_pk_fma_f16 v156, v96, v156, v160 op_sel_hi:[0,1,1]
	v_cvt_scalef32_pk_f16_fp4 v160, v149, 1.0 op_sel:[0,1,0]
	v_cvt_scalef32_pk_f16_fp4 v149, v149, 1.0 op_sel:[1,1,0]
	v_pk_fma_f16 v94, v96, v149, v94 op_sel_hi:[0,1,1]
	s_waitcnt vmcnt(35)
	v_cvt_scalef32_pk_f16_fp4 v149, v138, 1.0
	v_pk_fma_f16 v153, v96, v153, v161 op_sel_hi:[0,1,1]
	v_pk_fma_f16 v95, v96, v149, v95 op_sel:[1,0,0]
	v_cvt_scalef32_pk_f16_fp4 v149, v138, 1.0 op_sel:[1,0,0]
	v_pk_fma_f16 v149, v96, v149, v153 op_sel:[1,0,0]
	v_cvt_scalef32_pk_f16_fp4 v153, v138, 1.0 op_sel:[0,1,0]
	v_cvt_scalef32_pk_f16_fp4 v138, v138, 1.0 op_sel:[1,1,0]
	v_pk_fma_f16 v138, v96, v138, v146 op_sel:[1,0,0]
	v_cvt_scalef32_pk_f16_fp4 v146, v139, 1.0
	v_pk_fma_f16 v146, v96, v146, v150 op_sel:[1,0,0]
	v_cvt_scalef32_pk_f16_fp4 v150, v139, 1.0 op_sel:[1,0,0]
	v_pk_fma_f16 v150, v96, v150, v154 op_sel:[1,0,0]
	v_cvt_scalef32_pk_f16_fp4 v154, v139, 1.0 op_sel:[0,1,0]
	v_cvt_scalef32_pk_f16_fp4 v139, v139, 1.0 op_sel:[1,1,0]
	v_pk_fma_f16 v139, v96, v139, v147 op_sel:[1,0,0]
	v_cvt_scalef32_pk_f16_fp4 v147, v140, 1.0
	v_pk_fma_f16 v147, v96, v147, v151 op_sel:[1,0,0]
	v_cvt_scalef32_pk_f16_fp4 v151, v140, 1.0 op_sel:[1,0,0]
	v_pk_fma_f16 v151, v96, v151, v155 op_sel:[1,0,0]
	v_cvt_scalef32_pk_f16_fp4 v155, v140, 1.0 op_sel:[0,1,0]
	v_cvt_scalef32_pk_f16_fp4 v140, v140, 1.0 op_sel:[1,1,0]
	v_pk_fma_f16 v140, v96, v140, v148 op_sel:[1,0,0]
	v_cvt_scalef32_pk_f16_fp4 v148, v141, 1.0
	v_pk_fma_f16 v148, v96, v148, v152 op_sel:[1,0,0]
	v_cvt_scalef32_pk_f16_fp4 v152, v141, 1.0 op_sel:[1,0,0]
	v_pk_fma_f16 v157, v96, v157, v165 op_sel_hi:[0,1,1]
	v_pk_fma_f16 v158, v96, v158, v162 op_sel_hi:[0,1,1]
	v_pk_fma_f16 v159, v96, v159, v163 op_sel_hi:[0,1,1]
	v_pk_fma_f16 v160, v96, v160, v164 op_sel_hi:[0,1,1]
	v_pk_fma_f16 v152, v96, v152, v156 op_sel:[1,0,0]
	v_cvt_scalef32_pk_f16_fp4 v156, v141, 1.0 op_sel:[0,1,0]
	v_cvt_scalef32_pk_f16_fp4 v141, v141, 1.0 op_sel:[1,1,0]
	v_pk_fma_f16 v153, v96, v153, v157 op_sel:[1,0,0]
	v_pk_fma_f16 v154, v96, v154, v158 op_sel:[1,0,0]
	v_pk_fma_f16 v155, v96, v155, v159 op_sel:[1,0,0]
	v_pk_fma_f16 v156, v96, v156, v160 op_sel:[1,0,0]
	v_pk_fma_f16 v94, v96, v141, v94 op_sel:[1,0,0]
	s_waitcnt vmcnt(34)
	v_cvt_scalef32_pk_f16_fp4 v96, v122, 1.0
	v_pk_fma_f16 v95, v97, v96, v95 op_sel_hi:[0,1,1]
	v_cvt_scalef32_pk_f16_fp4 v96, v122, 1.0 op_sel:[1,0,0]
	v_cvt_scalef32_pk_f16_fp4 v141, v122, 1.0 op_sel:[0,1,0]
	v_cvt_scalef32_pk_f16_fp4 v122, v122, 1.0 op_sel:[1,1,0]
	v_pk_fma_f16 v122, v97, v122, v138 op_sel_hi:[0,1,1]
	v_cvt_scalef32_pk_f16_fp4 v138, v123, 1.0
	v_pk_fma_f16 v96, v97, v96, v149 op_sel_hi:[0,1,1]
	v_pk_fma_f16 v138, v97, v138, v146 op_sel_hi:[0,1,1]
	v_cvt_scalef32_pk_f16_fp4 v146, v123, 1.0 op_sel:[1,0,0]
	v_cvt_scalef32_pk_f16_fp4 v149, v123, 1.0 op_sel:[0,1,0]
	v_cvt_scalef32_pk_f16_fp4 v123, v123, 1.0 op_sel:[1,1,0]
	v_pk_fma_f16 v123, v97, v123, v139 op_sel_hi:[0,1,1]
	v_cvt_scalef32_pk_f16_fp4 v139, v124, 1.0
	v_pk_fma_f16 v146, v97, v146, v150 op_sel_hi:[0,1,1]
	v_pk_fma_f16 v139, v97, v139, v147 op_sel_hi:[0,1,1]
	v_cvt_scalef32_pk_f16_fp4 v147, v124, 1.0 op_sel:[1,0,0]
	v_cvt_scalef32_pk_f16_fp4 v150, v124, 1.0 op_sel:[0,1,0]
	v_cvt_scalef32_pk_f16_fp4 v124, v124, 1.0 op_sel:[1,1,0]
	v_pk_fma_f16 v124, v97, v124, v140 op_sel_hi:[0,1,1]
	v_cvt_scalef32_pk_f16_fp4 v140, v125, 1.0
	v_pk_fma_f16 v147, v97, v147, v151 op_sel_hi:[0,1,1]
	v_pk_fma_f16 v140, v97, v140, v148 op_sel_hi:[0,1,1]
	v_cvt_scalef32_pk_f16_fp4 v148, v125, 1.0 op_sel:[1,0,0]
	v_cvt_scalef32_pk_f16_fp4 v151, v125, 1.0 op_sel:[0,1,0]
	v_cvt_scalef32_pk_f16_fp4 v125, v125, 1.0 op_sel:[1,1,0]
	v_pk_fma_f16 v94, v97, v125, v94 op_sel_hi:[0,1,1]
	s_waitcnt vmcnt(33)
	v_cvt_scalef32_pk_f16_fp4 v125, v106, 1.0
	v_pk_fma_f16 v95, v97, v125, v95 op_sel:[1,0,0]
	v_cvt_scalef32_pk_f16_fp4 v125, v106, 1.0 op_sel:[1,0,0]
	v_pk_fma_f16 v96, v97, v125, v96 op_sel:[1,0,0]
	v_cvt_scalef32_pk_f16_fp4 v125, v106, 1.0 op_sel:[0,1,0]
	v_cvt_scalef32_pk_f16_fp4 v106, v106, 1.0 op_sel:[1,1,0]
	v_pk_fma_f16 v141, v97, v141, v153 op_sel_hi:[0,1,1]
	v_pk_fma_f16 v106, v97, v106, v122 op_sel:[1,0,0]
	v_cvt_scalef32_pk_f16_fp4 v122, v107, 1.0
	v_pk_fma_f16 v125, v97, v125, v141 op_sel:[1,0,0]
	v_pk_fma_f16 v122, v97, v122, v138 op_sel:[1,0,0]
	v_cvt_scalef32_pk_f16_fp4 v138, v107, 1.0 op_sel:[1,0,0]
	v_cvt_scalef32_pk_f16_fp4 v141, v107, 1.0 op_sel:[0,1,0]
	v_cvt_scalef32_pk_f16_fp4 v107, v107, 1.0 op_sel:[1,1,0]
	v_pk_fma_f16 v107, v97, v107, v123 op_sel:[1,0,0]
	v_cvt_scalef32_pk_f16_fp4 v123, v108, 1.0
	v_pk_fma_f16 v138, v97, v138, v146 op_sel:[1,0,0]
	v_pk_fma_f16 v123, v97, v123, v139 op_sel:[1,0,0]
	v_cvt_scalef32_pk_f16_fp4 v139, v108, 1.0 op_sel:[1,0,0]
	v_cvt_scalef32_pk_f16_fp4 v146, v108, 1.0 op_sel:[0,1,0]
	v_cvt_scalef32_pk_f16_fp4 v108, v108, 1.0 op_sel:[1,1,0]
	v_pk_fma_f16 v108, v97, v108, v124 op_sel:[1,0,0]
	v_cvt_scalef32_pk_f16_fp4 v124, v109, 1.0
	v_pk_fma_f16 v149, v97, v149, v154 op_sel_hi:[0,1,1]
	v_pk_fma_f16 v150, v97, v150, v155 op_sel_hi:[0,1,1]
	v_pk_fma_f16 v148, v97, v148, v152 op_sel_hi:[0,1,1]
	v_pk_fma_f16 v151, v97, v151, v156 op_sel_hi:[0,1,1]
	v_pk_fma_f16 v139, v97, v139, v147 op_sel:[1,0,0]
	v_pk_fma_f16 v124, v97, v124, v140 op_sel:[1,0,0]
	v_cvt_scalef32_pk_f16_fp4 v140, v109, 1.0 op_sel:[1,0,0]
	v_cvt_scalef32_pk_f16_fp4 v147, v109, 1.0 op_sel:[0,1,0]
	v_cvt_scalef32_pk_f16_fp4 v109, v109, 1.0 op_sel:[1,1,0]
	v_pk_fma_f16 v141, v97, v141, v149 op_sel:[1,0,0]
	v_pk_fma_f16 v146, v97, v146, v150 op_sel:[1,0,0]
	v_pk_fma_f16 v140, v97, v140, v148 op_sel:[1,0,0]
	v_pk_fma_f16 v147, v97, v147, v151 op_sel:[1,0,0]
	v_pk_fma_f16 v94, v97, v109, v94 op_sel:[1,0,0]
	s_waitcnt vmcnt(32)
	v_cvt_scalef32_pk_f16_fp4 v97, v98, 1.0
	v_pk_fma_f16 v95, v22, v97, v95 op_sel_hi:[0,1,1]
	v_cvt_scalef32_pk_f16_fp4 v97, v98, 1.0 op_sel:[1,0,0]
	v_pk_fma_f16 v96, v22, v97, v96 op_sel_hi:[0,1,1]
	v_cvt_scalef32_pk_f16_fp4 v97, v98, 1.0 op_sel:[0,1,0]
	v_cvt_scalef32_pk_f16_fp4 v98, v98, 1.0 op_sel:[1,1,0]
	v_pk_fma_f16 v98, v22, v98, v106 op_sel_hi:[0,1,1]
	v_cvt_scalef32_pk_f16_fp4 v106, v99, 1.0
	v_pk_fma_f16 v106, v22, v106, v122 op_sel_hi:[0,1,1]
	v_cvt_scalef32_pk_f16_fp4 v109, v99, 1.0 op_sel:[1,0,0]
	v_cvt_scalef32_pk_f16_fp4 v122, v99, 1.0 op_sel:[0,1,0]
	v_cvt_scalef32_pk_f16_fp4 v99, v99, 1.0 op_sel:[1,1,0]
	v_pk_fma_f16 v99, v22, v99, v107 op_sel_hi:[0,1,1]
	v_cvt_scalef32_pk_f16_fp4 v107, v100, 1.0
	v_pk_fma_f16 v97, v22, v97, v125 op_sel_hi:[0,1,1]
	v_pk_fma_f16 v107, v22, v107, v123 op_sel_hi:[0,1,1]
	v_cvt_scalef32_pk_f16_fp4 v123, v100, 1.0 op_sel:[1,0,0]
	v_cvt_scalef32_pk_f16_fp4 v125, v100, 1.0 op_sel:[0,1,0]
	v_cvt_scalef32_pk_f16_fp4 v100, v100, 1.0 op_sel:[1,1,0]
	v_pk_fma_f16 v100, v22, v100, v108 op_sel_hi:[0,1,1]
	v_cvt_scalef32_pk_f16_fp4 v108, v101, 1.0
	v_pk_fma_f16 v109, v22, v109, v138 op_sel_hi:[0,1,1]
	v_pk_fma_f16 v108, v22, v108, v124 op_sel_hi:[0,1,1]
	v_cvt_scalef32_pk_f16_fp4 v124, v101, 1.0 op_sel:[1,0,0]
	v_cvt_scalef32_pk_f16_fp4 v138, v101, 1.0 op_sel:[0,1,0]
	v_cvt_scalef32_pk_f16_fp4 v101, v101, 1.0 op_sel:[1,1,0]
	v_pk_fma_f16 v94, v22, v101, v94 op_sel_hi:[0,1,1]
	s_waitcnt vmcnt(31)
	v_cvt_scalef32_pk_f16_fp4 v101, v86, 1.0
	v_pk_fma_f16 v95, v22, v101, v95 op_sel:[1,0,0]
	v_cvt_scalef32_pk_f16_fp4 v101, v86, 1.0 op_sel:[1,0,0]
	v_pk_fma_f16 v96, v22, v101, v96 op_sel:[1,0,0]
	v_cvt_scalef32_pk_f16_fp4 v101, v86, 1.0 op_sel:[0,1,0]
	v_cvt_scalef32_pk_f16_fp4 v86, v86, 1.0 op_sel:[1,1,0]
	v_pk_fma_f16 v86, v22, v86, v98 op_sel:[1,0,0]
	v_cvt_scalef32_pk_f16_fp4 v98, v87, 1.0
	v_pk_fma_f16 v97, v22, v101, v97 op_sel:[1,0,0]
	v_pk_fma_f16 v98, v22, v98, v106 op_sel:[1,0,0]
	v_cvt_scalef32_pk_f16_fp4 v101, v87, 1.0 op_sel:[1,0,0]
	v_cvt_scalef32_pk_f16_fp4 v106, v87, 1.0 op_sel:[0,1,0]
	v_cvt_scalef32_pk_f16_fp4 v87, v87, 1.0 op_sel:[1,1,0]
	v_pk_fma_f16 v87, v22, v87, v99 op_sel:[1,0,0]
	v_cvt_scalef32_pk_f16_fp4 v99, v88, 1.0
	v_pk_fma_f16 v101, v22, v101, v109 op_sel:[1,0,0]
	v_pk_fma_f16 v99, v22, v99, v107 op_sel:[1,0,0]
	v_cvt_scalef32_pk_f16_fp4 v107, v88, 1.0 op_sel:[1,0,0]
	v_cvt_scalef32_pk_f16_fp4 v109, v88, 1.0 op_sel:[0,1,0]
	v_cvt_scalef32_pk_f16_fp4 v88, v88, 1.0 op_sel:[1,1,0]
	v_pk_fma_f16 v122, v22, v122, v141 op_sel_hi:[0,1,1]
	v_pk_fma_f16 v88, v22, v88, v100 op_sel:[1,0,0]
	v_cvt_scalef32_pk_f16_fp4 v100, v89, 1.0
	v_pk_fma_f16 v123, v22, v123, v139 op_sel_hi:[0,1,1]
	v_pk_fma_f16 v125, v22, v125, v146 op_sel_hi:[0,1,1]
	v_pk_fma_f16 v124, v22, v124, v140 op_sel_hi:[0,1,1]
	v_pk_fma_f16 v138, v22, v138, v147 op_sel_hi:[0,1,1]
	v_pk_fma_f16 v106, v22, v106, v122 op_sel:[1,0,0]
	v_pk_fma_f16 v100, v22, v100, v108 op_sel:[1,0,0]
	v_cvt_scalef32_pk_f16_fp4 v108, v89, 1.0 op_sel:[1,0,0]
	v_cvt_scalef32_pk_f16_fp4 v122, v89, 1.0 op_sel:[0,1,0]
	v_cvt_scalef32_pk_f16_fp4 v89, v89, 1.0 op_sel:[1,1,0]
	v_pk_fma_f16 v107, v22, v107, v123 op_sel:[1,0,0]
	v_pk_fma_f16 v109, v22, v109, v125 op_sel:[1,0,0]
	v_pk_fma_f16 v108, v22, v108, v124 op_sel:[1,0,0]
	v_pk_fma_f16 v122, v22, v122, v138 op_sel:[1,0,0]
	v_pk_fma_f16 v22, v22, v89, v94 op_sel:[1,0,0]
	s_waitcnt vmcnt(30)
	v_cvt_scalef32_pk_f16_fp4 v89, v78, 1.0
	v_pk_fma_f16 v89, v23, v89, v95 op_sel_hi:[0,1,1]
	v_cvt_scalef32_pk_f16_fp4 v94, v78, 1.0 op_sel:[1,0,0]
	v_cvt_scalef32_pk_f16_fp4 v95, v78, 1.0 op_sel:[0,1,0]
	v_cvt_scalef32_pk_f16_fp4 v78, v78, 1.0 op_sel:[1,1,0]
	v_pk_fma_f16 v94, v23, v94, v96 op_sel_hi:[0,1,1]
	v_pk_fma_f16 v95, v23, v95, v97 op_sel_hi:[0,1,1]
	v_pk_fma_f16 v78, v23, v78, v86 op_sel_hi:[0,1,1]
	v_cvt_scalef32_pk_f16_fp4 v86, v79, 1.0
	v_cvt_scalef32_pk_f16_fp4 v96, v79, 1.0 op_sel:[1,0,0]
	v_cvt_scalef32_pk_f16_fp4 v97, v79, 1.0 op_sel:[0,1,0]
	v_cvt_scalef32_pk_f16_fp4 v79, v79, 1.0 op_sel:[1,1,0]
	v_pk_fma_f16 v79, v23, v79, v87 op_sel_hi:[0,1,1]
	v_cvt_scalef32_pk_f16_fp4 v87, v80, 1.0
	v_pk_fma_f16 v86, v23, v86, v98 op_sel_hi:[0,1,1]
	v_pk_fma_f16 v87, v23, v87, v99 op_sel_hi:[0,1,1]
	v_cvt_scalef32_pk_f16_fp4 v98, v80, 1.0 op_sel:[1,0,0]
	v_cvt_scalef32_pk_f16_fp4 v99, v80, 1.0 op_sel:[0,1,0]
	v_cvt_scalef32_pk_f16_fp4 v80, v80, 1.0 op_sel:[1,1,0]
	v_pk_fma_f16 v80, v23, v80, v88 op_sel_hi:[0,1,1]
	v_cvt_scalef32_pk_f16_fp4 v88, v81, 1.0
	v_pk_fma_f16 v96, v23, v96, v101 op_sel_hi:[0,1,1]
	v_pk_fma_f16 v88, v23, v88, v100 op_sel_hi:[0,1,1]
	v_cvt_scalef32_pk_f16_fp4 v100, v81, 1.0 op_sel:[1,0,0]
	v_cvt_scalef32_pk_f16_fp4 v101, v81, 1.0 op_sel:[0,1,0]
	v_cvt_scalef32_pk_f16_fp4 v81, v81, 1.0 op_sel:[1,1,0]
	v_pk_fma_f16 v22, v23, v81, v22 op_sel_hi:[0,1,1]
	s_waitcnt vmcnt(29)
	v_cvt_scalef32_pk_f16_fp4 v81, v70, 1.0
	v_pk_fma_f16 v81, v23, v81, v89 op_sel:[1,0,0]
	v_cvt_scalef32_pk_f16_fp4 v89, v70, 1.0 op_sel:[1,0,0]
	v_pk_fma_f16 v89, v23, v89, v94 op_sel:[1,0,0]
	v_cvt_scalef32_pk_f16_fp4 v94, v70, 1.0 op_sel:[0,1,0]
	v_cvt_scalef32_pk_f16_fp4 v70, v70, 1.0 op_sel:[1,1,0]
	v_pk_fma_f16 v70, v23, v70, v78 op_sel:[1,0,0]
	v_cvt_scalef32_pk_f16_fp4 v78, v71, 1.0
	v_pk_fma_f16 v94, v23, v94, v95 op_sel:[1,0,0]
	v_pk_fma_f16 v78, v23, v78, v86 op_sel:[1,0,0]
	v_cvt_scalef32_pk_f16_fp4 v86, v71, 1.0 op_sel:[1,0,0]
	v_cvt_scalef32_pk_f16_fp4 v95, v71, 1.0 op_sel:[0,1,0]
	v_cvt_scalef32_pk_f16_fp4 v71, v71, 1.0 op_sel:[1,1,0]
	v_pk_fma_f16 v71, v23, v71, v79 op_sel:[1,0,0]
	v_cvt_scalef32_pk_f16_fp4 v79, v72, 1.0
	v_pk_fma_f16 v86, v23, v86, v96 op_sel:[1,0,0]
	v_pk_fma_f16 v79, v23, v79, v87 op_sel:[1,0,0]
	v_cvt_scalef32_pk_f16_fp4 v87, v72, 1.0 op_sel:[1,0,0]
	v_cvt_scalef32_pk_f16_fp4 v96, v72, 1.0 op_sel:[0,1,0]
	v_cvt_scalef32_pk_f16_fp4 v72, v72, 1.0 op_sel:[1,1,0]
	v_pk_fma_f16 v97, v23, v97, v106 op_sel_hi:[0,1,1]
	v_pk_fma_f16 v72, v23, v72, v80 op_sel:[1,0,0]
	v_cvt_scalef32_pk_f16_fp4 v80, v73, 1.0
	v_pk_fma_f16 v98, v23, v98, v107 op_sel_hi:[0,1,1]
	v_pk_fma_f16 v99, v23, v99, v109 op_sel_hi:[0,1,1]
	v_pk_fma_f16 v100, v23, v100, v108 op_sel_hi:[0,1,1]
	v_pk_fma_f16 v101, v23, v101, v122 op_sel_hi:[0,1,1]
	v_pk_fma_f16 v95, v23, v95, v97 op_sel:[1,0,0]
	v_pk_fma_f16 v80, v23, v80, v88 op_sel:[1,0,0]
	v_cvt_scalef32_pk_f16_fp4 v88, v73, 1.0 op_sel:[1,0,0]
	v_cvt_scalef32_pk_f16_fp4 v97, v73, 1.0 op_sel:[0,1,0]
	v_cvt_scalef32_pk_f16_fp4 v73, v73, 1.0 op_sel:[1,1,0]
	v_pk_fma_f16 v87, v23, v87, v98 op_sel:[1,0,0]
	v_pk_fma_f16 v96, v23, v96, v99 op_sel:[1,0,0]
	v_pk_fma_f16 v88, v23, v88, v100 op_sel:[1,0,0]
	v_pk_fma_f16 v97, v23, v97, v101 op_sel:[1,0,0]
	v_pk_fma_f16 v22, v23, v73, v22 op_sel:[1,0,0]
	s_waitcnt vmcnt(28)
	v_cvt_scalef32_pk_f16_fp4 v23, v58, 1.0
	v_pk_fma_f16 v23, v24, v23, v81 op_sel_hi:[0,1,1]
	v_cvt_scalef32_pk_f16_fp4 v73, v58, 1.0 op_sel:[1,0,0]
	v_cvt_scalef32_pk_f16_fp4 v81, v58, 1.0 op_sel:[0,1,0]
	v_cvt_scalef32_pk_f16_fp4 v58, v58, 1.0 op_sel:[1,1,0]
	v_pk_fma_f16 v58, v24, v58, v70 op_sel_hi:[0,1,1]
	v_cvt_scalef32_pk_f16_fp4 v70, v59, 1.0
	v_pk_fma_f16 v70, v24, v70, v78 op_sel_hi:[0,1,1]
	v_cvt_scalef32_pk_f16_fp4 v78, v59, 1.0 op_sel:[1,0,0]
	v_pk_fma_f16 v78, v24, v78, v86 op_sel_hi:[0,1,1]
	v_cvt_scalef32_pk_f16_fp4 v86, v59, 1.0 op_sel:[0,1,0]
	v_cvt_scalef32_pk_f16_fp4 v59, v59, 1.0 op_sel:[1,1,0]
	v_pk_fma_f16 v59, v24, v59, v71 op_sel_hi:[0,1,1]
	v_cvt_scalef32_pk_f16_fp4 v71, v60, 1.0
	v_pk_fma_f16 v71, v24, v71, v79 op_sel_hi:[0,1,1]
	v_cvt_scalef32_pk_f16_fp4 v79, v60, 1.0 op_sel:[1,0,0]
	v_pk_fma_f16 v79, v24, v79, v87 op_sel_hi:[0,1,1]
	v_cvt_scalef32_pk_f16_fp4 v87, v60, 1.0 op_sel:[0,1,0]
	v_cvt_scalef32_pk_f16_fp4 v60, v60, 1.0 op_sel:[1,1,0]
	v_pk_fma_f16 v60, v24, v60, v72 op_sel_hi:[0,1,1]
	v_cvt_scalef32_pk_f16_fp4 v72, v61, 1.0
	v_pk_fma_f16 v72, v24, v72, v80 op_sel_hi:[0,1,1]
	v_cvt_scalef32_pk_f16_fp4 v80, v61, 1.0 op_sel:[1,0,0]
	v_pk_fma_f16 v80, v24, v80, v88 op_sel_hi:[0,1,1]
	v_cvt_scalef32_pk_f16_fp4 v88, v61, 1.0 op_sel:[0,1,0]
	v_cvt_scalef32_pk_f16_fp4 v61, v61, 1.0 op_sel:[1,1,0]
	v_pk_fma_f16 v22, v24, v61, v22 op_sel_hi:[0,1,1]
	s_waitcnt vmcnt(27)
	v_cvt_scalef32_pk_f16_fp4 v61, v50, 1.0
	v_pk_fma_f16 v73, v24, v73, v89 op_sel_hi:[0,1,1]
	v_pk_fma_f16 v23, v24, v61, v23 op_sel:[1,0,0]
	v_cvt_scalef32_pk_f16_fp4 v61, v50, 1.0 op_sel:[1,0,0]
	v_pk_fma_f16 v61, v24, v61, v73 op_sel:[1,0,0]
	v_cvt_scalef32_pk_f16_fp4 v73, v50, 1.0 op_sel:[0,1,0]
	v_cvt_scalef32_pk_f16_fp4 v50, v50, 1.0 op_sel:[1,1,0]
	v_pk_fma_f16 v50, v24, v50, v58 op_sel:[1,0,0]
	v_cvt_scalef32_pk_f16_fp4 v58, v51, 1.0
	v_pk_fma_f16 v58, v24, v58, v70 op_sel:[1,0,0]
	v_cvt_scalef32_pk_f16_fp4 v70, v51, 1.0 op_sel:[1,0,0]
	v_pk_fma_f16 v70, v24, v70, v78 op_sel:[1,0,0]
	v_cvt_scalef32_pk_f16_fp4 v78, v51, 1.0 op_sel:[0,1,0]
	v_cvt_scalef32_pk_f16_fp4 v51, v51, 1.0 op_sel:[1,1,0]
	v_pk_fma_f16 v51, v24, v51, v59 op_sel:[1,0,0]
	v_cvt_scalef32_pk_f16_fp4 v59, v52, 1.0
	v_pk_fma_f16 v59, v24, v59, v71 op_sel:[1,0,0]
	v_cvt_scalef32_pk_f16_fp4 v71, v52, 1.0 op_sel:[1,0,0]
	v_pk_fma_f16 v71, v24, v71, v79 op_sel:[1,0,0]
	v_cvt_scalef32_pk_f16_fp4 v79, v52, 1.0 op_sel:[0,1,0]
	v_cvt_scalef32_pk_f16_fp4 v52, v52, 1.0 op_sel:[1,1,0]
	v_pk_fma_f16 v52, v24, v52, v60 op_sel:[1,0,0]
	v_cvt_scalef32_pk_f16_fp4 v60, v53, 1.0
	v_pk_fma_f16 v60, v24, v60, v72 op_sel:[1,0,0]
	v_cvt_scalef32_pk_f16_fp4 v72, v53, 1.0 op_sel:[1,0,0]
	v_pk_fma_f16 v81, v24, v81, v94 op_sel_hi:[0,1,1]
	v_pk_fma_f16 v86, v24, v86, v95 op_sel_hi:[0,1,1]
	v_pk_fma_f16 v87, v24, v87, v96 op_sel_hi:[0,1,1]
	v_pk_fma_f16 v88, v24, v88, v97 op_sel_hi:[0,1,1]
	v_pk_fma_f16 v72, v24, v72, v80 op_sel:[1,0,0]
	v_cvt_scalef32_pk_f16_fp4 v80, v53, 1.0 op_sel:[0,1,0]
	v_cvt_scalef32_pk_f16_fp4 v53, v53, 1.0 op_sel:[1,1,0]
	v_pk_fma_f16 v73, v24, v73, v81 op_sel:[1,0,0]
	v_pk_fma_f16 v78, v24, v78, v86 op_sel:[1,0,0]
	v_pk_fma_f16 v79, v24, v79, v87 op_sel:[1,0,0]
	v_pk_fma_f16 v80, v24, v80, v88 op_sel:[1,0,0]
	v_pk_fma_f16 v22, v24, v53, v22 op_sel:[1,0,0]
	s_waitcnt vmcnt(26)
	v_cvt_scalef32_pk_f16_fp4 v24, v42, 1.0
	v_pk_fma_f16 v23, v25, v24, v23 op_sel_hi:[0,1,1]
	v_cvt_scalef32_pk_f16_fp4 v24, v42, 1.0 op_sel:[1,0,0]
	v_cvt_scalef32_pk_f16_fp4 v53, v42, 1.0 op_sel:[0,1,0]
	v_cvt_scalef32_pk_f16_fp4 v42, v42, 1.0 op_sel:[1,1,0]
	v_pk_fma_f16 v42, v25, v42, v50 op_sel_hi:[0,1,1]
	v_cvt_scalef32_pk_f16_fp4 v50, v43, 1.0
	v_pk_fma_f16 v24, v25, v24, v61 op_sel_hi:[0,1,1]
	v_pk_fma_f16 v50, v25, v50, v58 op_sel_hi:[0,1,1]
	v_cvt_scalef32_pk_f16_fp4 v58, v43, 1.0 op_sel:[1,0,0]
	v_cvt_scalef32_pk_f16_fp4 v61, v43, 1.0 op_sel:[0,1,0]
	v_cvt_scalef32_pk_f16_fp4 v43, v43, 1.0 op_sel:[1,1,0]
	v_pk_fma_f16 v43, v25, v43, v51 op_sel_hi:[0,1,1]
	v_cvt_scalef32_pk_f16_fp4 v51, v44, 1.0
	v_pk_fma_f16 v58, v25, v58, v70 op_sel_hi:[0,1,1]
	v_pk_fma_f16 v51, v25, v51, v59 op_sel_hi:[0,1,1]
	v_cvt_scalef32_pk_f16_fp4 v59, v44, 1.0 op_sel:[1,0,0]
	v_cvt_scalef32_pk_f16_fp4 v70, v44, 1.0 op_sel:[0,1,0]
	v_cvt_scalef32_pk_f16_fp4 v44, v44, 1.0 op_sel:[1,1,0]
	v_pk_fma_f16 v44, v25, v44, v52 op_sel_hi:[0,1,1]
	v_cvt_scalef32_pk_f16_fp4 v52, v45, 1.0
	v_pk_fma_f16 v59, v25, v59, v71 op_sel_hi:[0,1,1]
	v_pk_fma_f16 v52, v25, v52, v60 op_sel_hi:[0,1,1]
	v_cvt_scalef32_pk_f16_fp4 v60, v45, 1.0 op_sel:[1,0,0]
	v_cvt_scalef32_pk_f16_fp4 v71, v45, 1.0 op_sel:[0,1,0]
	v_cvt_scalef32_pk_f16_fp4 v45, v45, 1.0 op_sel:[1,1,0]
	v_pk_fma_f16 v22, v25, v45, v22 op_sel_hi:[0,1,1]
	s_waitcnt vmcnt(25)
	v_cvt_scalef32_pk_f16_fp4 v45, v30, 1.0
	v_pk_fma_f16 v23, v25, v45, v23 op_sel:[1,0,0]
	v_cvt_scalef32_pk_f16_fp4 v45, v30, 1.0 op_sel:[1,0,0]
	v_pk_fma_f16 v24, v25, v45, v24 op_sel:[1,0,0]
	v_cvt_scalef32_pk_f16_fp4 v45, v30, 1.0 op_sel:[0,1,0]
	v_cvt_scalef32_pk_f16_fp4 v30, v30, 1.0 op_sel:[1,1,0]
	v_pk_fma_f16 v53, v25, v53, v73 op_sel_hi:[0,1,1]
	v_pk_fma_f16 v30, v25, v30, v42 op_sel:[1,0,0]
	v_cvt_scalef32_pk_f16_fp4 v42, v31, 1.0
	v_pk_fma_f16 v45, v25, v45, v53 op_sel:[1,0,0]
	v_pk_fma_f16 v42, v25, v42, v50 op_sel:[1,0,0]
	v_cvt_scalef32_pk_f16_fp4 v50, v31, 1.0 op_sel:[1,0,0]
	v_cvt_scalef32_pk_f16_fp4 v53, v31, 1.0 op_sel:[0,1,0]
	v_cvt_scalef32_pk_f16_fp4 v31, v31, 1.0 op_sel:[1,1,0]
	v_pk_fma_f16 v31, v25, v31, v43 op_sel:[1,0,0]
	v_cvt_scalef32_pk_f16_fp4 v43, v32, 1.0
	v_pk_fma_f16 v50, v25, v50, v58 op_sel:[1,0,0]
	v_pk_fma_f16 v43, v25, v43, v51 op_sel:[1,0,0]
	v_cvt_scalef32_pk_f16_fp4 v51, v32, 1.0 op_sel:[1,0,0]
	v_cvt_scalef32_pk_f16_fp4 v58, v32, 1.0 op_sel:[0,1,0]
	v_cvt_scalef32_pk_f16_fp4 v32, v32, 1.0 op_sel:[1,1,0]
	v_pk_fma_f16 v61, v25, v61, v78 op_sel_hi:[0,1,1]
	v_pk_fma_f16 v70, v25, v70, v79 op_sel_hi:[0,1,1]
	v_pk_fma_f16 v71, v25, v71, v80 op_sel_hi:[0,1,1]
	v_pk_fma_f16 v51, v25, v51, v59 op_sel:[1,0,0]
	v_pk_fma_f16 v32, v25, v32, v44 op_sel:[1,0,0]
	v_cvt_scalef32_pk_f16_fp4 v44, v33, 1.0
	v_cvt_scalef32_pk_f16_fp4 v59, v33, 1.0 op_sel:[0,1,0]
	v_pk_fma_f16 v53, v25, v53, v61 op_sel:[1,0,0]
	v_pk_fma_f16 v58, v25, v58, v70 op_sel:[1,0,0]
	v_pk_fma_f16 v44, v25, v44, v52 op_sel:[1,0,0]
	v_cvt_scalef32_pk_f16_fp4 v52, v33, 1.0 op_sel:[1,0,0]
	v_pk_fma_f16 v59, v25, v59, v71 op_sel:[1,0,0]
	v_cvt_scalef32_pk_f16_fp4 v33, v33, 1.0 op_sel:[1,1,0]
	v_pk_fma_f16 v60, v25, v60, v72 op_sel_hi:[0,1,1]
	v_pk_fma_f16 v22, v25, v33, v22 op_sel:[1,0,0]
	v_permlane32_swap_b32_e32 v23, v43
	v_permlane32_swap_b32_e32 v45, v58
	v_permlane32_swap_b32_e32 v30, v32
	v_permlane32_swap_b32_e32 v42, v44
	v_permlane32_swap_b32_e32 v53, v59
	v_pk_fma_f16 v52, v25, v52, v60 op_sel:[1,0,0]
	v_pk_add_f16 v23, v23, v43
	v_pk_add_f16 v25, v45, v58
	v_pk_add_f16 v30, v30, v32
	v_pk_add_f16 v32, v42, v44
	v_pk_add_f16 v42, v53, v59
	v_permlane32_swap_b32_e32 v31, v22
	v_permlane32_swap_b32_e32 v24, v51
	v_permlane32_swap_b32_e32 v50, v52
	v_pk_add_f16 v22, v31, v22
	v_permlane16_swap_b32_e32 v23, v32
	v_permlane16_swap_b32_e32 v25, v42
	v_pk_add_f16 v24, v24, v51
	v_pk_add_f16 v33, v50, v52
	v_pk_add_f16 v23, v23, v32
	v_pk_add_f16 v25, v25, v42
	v_permlane16_swap_b32_e32 v30, v22
	v_permlane16_swap_b32_e32 v24, v33
	v_pk_add_f16 v22, v30, v22
	v_cndmask_b32_e64 v30, v25, v23, s[4:5]
	v_cndmask_b32_e64 v23, v23, v25, s[4:5]
	v_pk_add_f16 v24, v24, v33
	v_cvt_f32_f16_e32 v32, v201
	v_mov_b32_dpp v23, v23 row_ror:8 row_mask:0xf bank_mask:0xf bound_ctrl:1
	v_pk_add_f16 v25, v30, v23
	v_cndmask_b32_e64 v30, v22, v24, s[4:5]
	v_cndmask_b32_e64 v22, v24, v22, s[4:5]
	v_cvt_f32_f16_sdwa v23, v200 dst_sel:DWORD dst_unused:UNUSED_PAD src0_sel:WORD_1
	v_cvt_f32_f16_e32 v24, v25
	v_mov_b32_dpp v31, v22 row_ror:8 row_mask:0xf bank_mask:0xf bound_ctrl:1
	v_cvt_f32_f16_e32 v22, v200
	v_cvt_f32_f16_sdwa v25, v25 dst_sel:DWORD dst_unused:UNUSED_PAD src0_sel:WORD_1
	v_pk_add_f16 v43, v30, v31
	v_cvt_f32_f16_e32 v30, v198
	v_cvt_f32_f16_sdwa v31, v198 dst_sel:DWORD dst_unused:UNUSED_PAD src0_sel:WORD_1
	v_cvt_f32_f16_sdwa v33, v201 dst_sel:DWORD dst_unused:UNUSED_PAD src0_sel:WORD_1
	v_cvt_f32_f16_e32 v42, v43
	v_cvt_f32_f16_sdwa v43, v43 dst_sel:DWORD dst_unused:UNUSED_PAD src0_sel:WORD_1
	v_pk_fma_f32 v[22:23], v[2:3], v[24:25], v[22:23]
	v_cvt_f32_f16_e32 v24, v199
	v_cvt_f32_f16_sdwa v25, v199 dst_sel:DWORD dst_unused:UNUSED_PAD src0_sel:WORD_1
	v_pk_add_f32 v[22:23], v[22:23], v[30:31]
	v_pk_fma_f32 v[30:31], v[4:5], v[42:43], v[32:33]
	v_cvt_pk_f16_f32 v22, v22, v23
	v_pk_add_f32 v[24:25], v[30:31], v[24:25]
	s_nop 0
	v_cvt_pk_f16_f32 v23, v24, v25
	global_store_dwordx2 v[196:197], v[22:23], off
	s_mov_b32 s25, s13
	s_cbranch_scc0 .LBB0_4094
	s_mov_b64 s[14:15], 0
